# dn solve: LDS-broadcast A quads + the 63 x-init ds_read_u16 issued together at the top (into the registers that used to hold A rows), compiler LDS waits recounted
# baseline (speedup 1.0000x reference)
.LBB0_654:
	s_andn2_saveexec_b64 s[0:1], s[2:3]
	s_cbranch_execz .LBB0_660
	v_cmp_lt_i32_e64 s[40:41], 63, v74
	ds_read_b128 v[202:205], v137 offset:27904
	ds_read_b128 v[206:209], v137 offset:28160
	ds_read_b128 v[210:213], v137 offset:28416
	ds_read_b128 v[214:217], v137 offset:28672
	ds_read_b128 v[218:221], v137 offset:28928
	ds_read_b128 v[222:225], v137 offset:28944
	ds_read_b128 v[226:229], v137 offset:29184
	ds_read_b128 v[230:233], v137 offset:29200
	v_cndmask_b32_e64 v0, v194, v192, s[40:41]
	v_lshlrev_b32_e32 v77, 1, v75
	v_or_b32_e32 v82, v0, v77
	ds_read_u16 v0, v82
	ds_read_u16 v12, v82 offset:144
	ds_read_u16 v13, v82 offset:288
	ds_read_u16 v14, v82 offset:432
	ds_read_u16 v15, v82 offset:576
	ds_read_u16 v16, v82 offset:720
	ds_read_u16 v17, v82 offset:864
	ds_read_u16 v18, v82 offset:1008
	ds_read_u16 v19, v82 offset:1152
	ds_read_u16 v20, v82 offset:1296
	ds_read_u16 v21, v82 offset:1440
	ds_read_u16 v22, v82 offset:1584
	ds_read_u16 v23, v82 offset:1728
	ds_read_u16 v24, v82 offset:1872
	ds_read_u16 v25, v82 offset:2016
	ds_read_u16 v26, v82 offset:2160
	ds_read_u16 v27, v82 offset:2304
	ds_read_u16 v28, v82 offset:2448
	ds_read_u16 v29, v82 offset:2592
	ds_read_u16 v30, v82 offset:2736
	ds_read_u16 v31, v82 offset:2880
	ds_read_u16 v32, v82 offset:3024
	ds_read_u16 v33, v82 offset:3168
	ds_read_u16 v34, v82 offset:3312
	ds_read_u16 v35, v82 offset:3456
	ds_read_u16 v36, v82 offset:3600
	ds_read_u16 v37, v82 offset:3744
	ds_read_u16 v38, v82 offset:3888
	ds_read_u16 v39, v82 offset:4032
	ds_read_u16 v40, v82 offset:4176
	ds_read_u16 v41, v82 offset:4320
	ds_read_u16 v42, v82 offset:4464
	ds_read_u16 v43, v82 offset:4608
	ds_read_u16 v44, v82 offset:4752
	ds_read_u16 v45, v82 offset:4896
	ds_read_u16 v46, v82 offset:5040
	ds_read_u16 v47, v82 offset:5184
	ds_read_u16 v48, v82 offset:5328
	ds_read_u16 v49, v82 offset:5472
	ds_read_u16 v50, v82 offset:5616
	ds_read_u16 v51, v82 offset:5760
	ds_read_u16 v52, v82 offset:5904
	ds_read_u16 v53, v82 offset:6048
	ds_read_u16 v54, v82 offset:6192
	ds_read_u16 v55, v82 offset:6336
	ds_read_u16 v56, v82 offset:6480
	ds_read_u16 v57, v82 offset:6624
	ds_read_u16 v58, v82 offset:6768
	ds_read_u16 v59, v82 offset:6912
	ds_read_u16 v60, v82 offset:7056
	ds_read_u16 v61, v82 offset:7200
	ds_read_u16 v62, v82 offset:7344
	ds_read_u16 v63, v82 offset:7488
	ds_read_u16 v64, v82 offset:7632
	ds_read_u16 v65, v82 offset:7776
	ds_read_u16 v66, v82 offset:7920
	ds_read_u16 v67, v82 offset:8064
	ds_read_u16 v68, v82 offset:8208
	ds_read_u16 v69, v82 offset:8352
	ds_read_u16 v70, v82 offset:8496
	ds_read_u16 v71, v82 offset:8640
	ds_read_u16 v72, v82 offset:8784
	ds_read_u16 v73, v82 offset:8928
	ds_read_u16 v80, v82 offset:9072
	ds_read_b128 v[84:87], v137 offset:60672
	s_waitcnt lgkmcnt(15)
	v_cmp_gt_i32_e64 s[38:39], 64, v74
	s_waitcnt lgkmcnt(15)
	v_lshlrev_b32_e32 v0, 16, v0
	s_waitcnt lgkmcnt(0)
	v_mul_f32_e32 v79, v84, v0
	ds_read_b128 v[88:91], v137 offset:60416
	ds_read_b128 v[8:11], v137 offset:60432
	ds_read_b128 v[4:7], v137 offset:60448
	ds_read_b128 v[0:3], v137 offset:60464
	v_mov_b32_e32 v83, v12
	s_waitcnt lgkmcnt(3)
	v_mul_f32_e32 v84, 0x3fb8aa3b, v89
	v_exp_f32_e32 v84, v84
	s_waitcnt lgkmcnt(2)
	v_mul_f32_e32 v8, 0x3fb8aa3b, v8
	v_exp_f32_e32 v8, v8
	s_waitcnt lgkmcnt(0)
	v_lshlrev_b32_e32 v83, 16, v83
	v_mul_f32_e32 v83, v85, v83
	v_mul_f32_e32 v84, v83, v84
	v_cndmask_b32_e64 v105, v83, v84, s[40:41]
	v_mov_b32_e32 v83, v13
	v_mul_f32_e32 v84, 0x3fb8aa3b, v90
	v_exp_f32_e32 v84, v84
	v_mul_f32_e32 v9, 0x3fb8aa3b, v9
	v_exp_f32_e32 v9, v9
	s_waitcnt lgkmcnt(0)
	v_lshlrev_b32_e32 v83, 16, v83
	v_mul_f32_e32 v83, v86, v83
	v_mul_f32_e32 v84, v83, v84
	v_cndmask_b32_e64 v106, v83, v84, s[40:41]
	v_mov_b32_e32 v83, v14
	v_mul_f32_e32 v84, 0x3fb8aa3b, v91
	v_exp_f32_e32 v84, v84
	v_mul_f32_e32 v10, 0x3fb8aa3b, v10
	v_exp_f32_e32 v10, v10
	s_waitcnt lgkmcnt(0)
	v_lshlrev_b32_e32 v83, 16, v83
	v_mul_f32_e32 v83, v87, v83
	v_mul_f32_e32 v84, v83, v84
	v_cndmask_b32_e64 v109, v83, v84, s[40:41]
	v_mov_b32_e32 v83, v15
	ds_read_b128 v[84:87], v137 offset:60688
	v_mul_f32_e32 v11, 0x3fb8aa3b, v11
	v_exp_f32_e32 v11, v11
	v_mul_f32_e32 v4, 0x3fb8aa3b, v4
	s_waitcnt lgkmcnt(1)
	v_lshlrev_b32_e32 v83, 16, v83
	s_waitcnt lgkmcnt(0)
	v_mul_f32_e32 v83, v84, v83
	v_mul_f32_e32 v8, v83, v8
	v_cndmask_b32_e64 v8, v83, v8, s[40:41]
	v_mov_b32_e32 v83, v16
	v_exp_f32_e32 v4, v4
	v_mul_f32_e32 v5, 0x3fb8aa3b, v5
	v_exp_f32_e32 v5, v5
	v_mul_f32_e32 v0, 0x3fb8aa3b, v0
	s_waitcnt lgkmcnt(0)
	v_lshlrev_b32_e32 v83, 16, v83
	v_mul_f32_e32 v83, v85, v83
	v_mul_f32_e32 v9, v83, v9
	v_cndmask_b32_e64 v9, v83, v9, s[40:41]
	v_mov_b32_e32 v83, v17
	v_exp_f32_e32 v0, v0
	v_mul_f32_e32 v1, 0x3fb8aa3b, v1
	v_exp_f32_e32 v1, v1
	v_mul_f32_e32 v78, 0x3fb8aa3b, v88
	s_waitcnt lgkmcnt(0)
	v_lshlrev_b32_e32 v83, 16, v83
	v_mul_f32_e32 v83, v86, v83
	v_mul_f32_e32 v10, v83, v10
	v_cndmask_b32_e64 v10, v83, v10, s[40:41]
	v_mov_b32_e32 v83, v18
	v_exp_f32_e32 v78, v78
	s_waitcnt lgkmcnt(0)
	v_lshlrev_b32_e32 v83, 16, v83
	v_mul_f32_e32 v83, v87, v83
	v_mul_f32_e32 v11, v83, v11
	v_cndmask_b32_e64 v11, v83, v11, s[40:41]
	v_mov_b32_e32 v83, v19
	ds_read_b128 v[84:87], v137 offset:60704
	v_mul_f32_e32 v78, v79, v78
	v_cndmask_b32_e64 v81, v79, v78, s[40:41]
	s_waitcnt lgkmcnt(1)
	v_lshlrev_b32_e32 v83, 16, v83
	s_waitcnt lgkmcnt(0)
	v_mul_f32_e32 v83, v84, v83
	v_mul_f32_e32 v4, v83, v4
	v_cndmask_b32_e64 v116, v83, v4, s[40:41]
	v_mov_b32_e32 v4, v20
	s_waitcnt lgkmcnt(0)
	v_lshlrev_b32_e32 v4, 16, v4
	v_mul_f32_e32 v4, v85, v4
	v_mul_f32_e32 v5, v4, v5
	v_cndmask_b32_e64 v117, v4, v5, s[40:41]
	v_mov_b32_e32 v4, v21
	v_mul_f32_e32 v5, 0x3fb8aa3b, v6
	v_exp_f32_e32 v5, v5
	s_waitcnt lgkmcnt(0)
	v_lshlrev_b32_e32 v4, 16, v4
	v_mul_f32_e32 v4, v86, v4
	v_mul_f32_e32 v5, v4, v5
	v_cndmask_b32_e64 v120, v4, v5, s[40:41]
	v_mov_b32_e32 v4, v22
	v_mul_f32_e32 v5, 0x3fb8aa3b, v7
	v_exp_f32_e32 v5, v5
	s_waitcnt lgkmcnt(0)
	v_lshlrev_b32_e32 v4, 16, v4
	v_mul_f32_e32 v4, v87, v4
	v_mul_f32_e32 v5, v4, v5
	v_cndmask_b32_e64 v121, v4, v5, s[40:41]
	v_mov_b32_e32 v4, v23
	s_waitcnt lgkmcnt(0)
	v_lshlrev_b32_e32 v83, 16, v4
	ds_read_b128 v[4:7], v137 offset:60720
	s_waitcnt lgkmcnt(0)
	v_mul_f32_e32 v4, v4, v83
	v_mul_f32_e32 v0, v4, v0
	v_cndmask_b32_e64 v122, v4, v0, s[40:41]
	v_mov_b32_e32 v0, v24
	s_waitcnt lgkmcnt(0)
	v_lshlrev_b32_e32 v0, 16, v0
	v_mul_f32_e32 v0, v5, v0
	v_mul_f32_e32 v1, v0, v1
	v_cndmask_b32_e64 v123, v0, v1, s[40:41]
	v_mov_b32_e32 v0, v25
	v_mul_f32_e32 v1, 0x3fb8aa3b, v2
	v_exp_f32_e32 v1, v1
	s_waitcnt lgkmcnt(0)
	v_lshlrev_b32_e32 v0, 16, v0
	v_mul_f32_e32 v0, v6, v0
	v_mul_f32_e32 v1, v0, v1
	v_cndmask_b32_e64 v124, v0, v1, s[40:41]
	v_mov_b32_e32 v0, v26
	v_mul_f32_e32 v1, 0x3fb8aa3b, v3
	v_exp_f32_e32 v1, v1
	s_waitcnt lgkmcnt(0)
	v_lshlrev_b32_e32 v0, 16, v0
	v_mul_f32_e32 v0, v7, v0
	v_mul_f32_e32 v1, v0, v1
	v_cndmask_b32_e64 v143, v0, v1, s[40:41]
	v_mov_b32_e32 v0, v27
	s_waitcnt lgkmcnt(0)
	v_lshlrev_b32_e32 v4, 16, v0
	ds_read_b128 v[0:3], v137 offset:60736
	s_waitcnt lgkmcnt(0)
	v_mul_f32_e32 v0, v0, v4
	ds_read_b128 v[4:7], v137 offset:60480
	s_waitcnt lgkmcnt(0)
	v_mul_f32_e32 v4, 0x3fb8aa3b, v4
	v_exp_f32_e32 v4, v4
	s_nop 0
	v_mul_f32_e32 v4, v0, v4
	v_cndmask_b32_e64 v145, v0, v4, s[40:41]
	v_mov_b32_e32 v0, v28
	s_waitcnt lgkmcnt(0)
	v_lshlrev_b32_e32 v0, 16, v0
	v_mul_f32_e32 v0, v1, v0
	v_mul_f32_e32 v1, 0x3fb8aa3b, v5
	v_exp_f32_e32 v1, v1
	s_nop 0
	v_mul_f32_e32 v1, v0, v1
	v_cndmask_b32_e64 v133, v0, v1, s[40:41]
	v_mov_b32_e32 v0, v29
	v_mul_f32_e32 v1, 0x3fb8aa3b, v6
	v_exp_f32_e32 v1, v1
	s_waitcnt lgkmcnt(0)
	v_lshlrev_b32_e32 v0, 16, v0
	v_mul_f32_e32 v0, v2, v0
	v_mul_f32_e32 v1, v0, v1
	v_cndmask_b32_e64 v129, v0, v1, s[40:41]
	v_mov_b32_e32 v0, v30
	v_mul_f32_e32 v1, 0x3fb8aa3b, v7
	v_exp_f32_e32 v1, v1
	s_waitcnt lgkmcnt(0)
	v_lshlrev_b32_e32 v0, 16, v0
	v_mul_f32_e32 v0, v3, v0
	v_mul_f32_e32 v1, v0, v1
	v_cndmask_b32_e64 v125, v0, v1, s[40:41]
	v_mov_b32_e32 v0, v31
	s_waitcnt lgkmcnt(0)
	v_lshlrev_b32_e32 v4, 16, v0
	ds_read_b128 v[0:3], v137 offset:60752
	s_waitcnt lgkmcnt(0)
	v_mul_f32_e32 v0, v0, v4
	ds_read_b128 v[4:7], v137 offset:60496
	s_waitcnt lgkmcnt(0)
	v_mul_f32_e32 v4, 0x3fb8aa3b, v4
	v_exp_f32_e32 v4, v4
	s_nop 0
	v_mul_f32_e32 v4, v0, v4
	v_cndmask_b32_e64 v136, v0, v4, s[40:41]
	v_mov_b32_e32 v0, v32
	s_waitcnt lgkmcnt(0)
	v_lshlrev_b32_e32 v0, 16, v0
	v_mul_f32_e32 v0, v1, v0
	v_mul_f32_e32 v1, 0x3fb8aa3b, v5
	v_exp_f32_e32 v1, v1
	s_nop 0
	v_mul_f32_e32 v1, v0, v1
	v_cndmask_b32_e64 v134, v0, v1, s[40:41]
	v_mov_b32_e32 v0, v33
	v_mul_f32_e32 v1, 0x3fb8aa3b, v6
	v_exp_f32_e32 v1, v1
	s_waitcnt lgkmcnt(0)
	v_lshlrev_b32_e32 v0, 16, v0
	v_mul_f32_e32 v0, v2, v0
	v_mul_f32_e32 v1, v0, v1
	v_cndmask_b32_e64 v132, v0, v1, s[40:41]
	v_mov_b32_e32 v0, v34
	v_mul_f32_e32 v1, 0x3fb8aa3b, v7
	v_exp_f32_e32 v1, v1
	s_waitcnt lgkmcnt(0)
	v_lshlrev_b32_e32 v0, 16, v0
	v_mul_f32_e32 v0, v3, v0
	v_mul_f32_e32 v1, v0, v1
	v_cndmask_b32_e64 v147, v0, v1, s[40:41]
	v_mov_b32_e32 v0, v35
	s_waitcnt lgkmcnt(0)
	v_lshlrev_b32_e32 v4, 16, v0
	ds_read_b128 v[0:3], v137 offset:60768
	s_waitcnt lgkmcnt(0)
	v_mul_f32_e32 v0, v0, v4
	ds_read_b128 v[4:7], v137 offset:60512
	s_waitcnt lgkmcnt(0)
	v_mul_f32_e32 v4, 0x3fb8aa3b, v4
	v_exp_f32_e32 v4, v4
	s_nop 0
	v_mul_f32_e32 v4, v0, v4
	v_cndmask_b32_e64 v146, v0, v4, s[40:41]
	v_mov_b32_e32 v0, v36
	s_waitcnt lgkmcnt(0)
	v_lshlrev_b32_e32 v0, 16, v0
	v_mul_f32_e32 v0, v1, v0
	v_mul_f32_e32 v1, 0x3fb8aa3b, v5
	v_exp_f32_e32 v1, v1
	s_nop 0
	v_mul_f32_e32 v1, v0, v1
	v_cndmask_b32_e64 v135, v0, v1, s[40:41]
	v_mov_b32_e32 v0, v37
	v_mul_f32_e32 v1, 0x3fb8aa3b, v6
	v_exp_f32_e32 v1, v1
	s_waitcnt lgkmcnt(0)
	v_lshlrev_b32_e32 v0, 16, v0
	v_mul_f32_e32 v0, v2, v0
	v_mul_f32_e32 v1, v0, v1
	v_cndmask_b32_e64 v128, v0, v1, s[40:41]
	v_mov_b32_e32 v0, v38
	v_mul_f32_e32 v1, 0x3fb8aa3b, v7
	v_exp_f32_e32 v1, v1
	s_waitcnt lgkmcnt(0)
	v_lshlrev_b32_e32 v0, 16, v0
	v_mul_f32_e32 v0, v3, v0
	v_mul_f32_e32 v1, v0, v1
	v_cndmask_b32_e64 v118, v0, v1, s[40:41]
	v_mov_b32_e32 v0, v39
	s_waitcnt lgkmcnt(0)
	v_lshlrev_b32_e32 v4, 16, v0
	ds_read_b128 v[0:3], v137 offset:60784
	s_waitcnt lgkmcnt(0)
	v_mul_f32_e32 v0, v0, v4
	ds_read_b128 v[4:7], v137 offset:60528
	s_waitcnt lgkmcnt(0)
	v_mul_f32_e32 v4, 0x3fb8aa3b, v4
	v_exp_f32_e32 v4, v4
	s_nop 0
	v_mul_f32_e32 v4, v0, v4
	v_cndmask_b32_e64 v130, v0, v4, s[40:41]
	v_mov_b32_e32 v0, v40
	s_waitcnt lgkmcnt(0)
	v_lshlrev_b32_e32 v0, 16, v0
	v_mul_f32_e32 v0, v1, v0
	v_mul_f32_e32 v1, 0x3fb8aa3b, v5
	v_exp_f32_e32 v1, v1
	s_nop 0
	v_mul_f32_e32 v1, v0, v1
	v_cndmask_b32_e64 v127, v0, v1, s[40:41]
	v_mov_b32_e32 v0, v41
	v_mul_f32_e32 v1, 0x3fb8aa3b, v6
	v_exp_f32_e32 v1, v1
	s_waitcnt lgkmcnt(0)
	v_lshlrev_b32_e32 v0, 16, v0
	v_mul_f32_e32 v0, v2, v0
	v_mul_f32_e32 v1, v0, v1
	v_cndmask_b32_e64 v119, v0, v1, s[40:41]
	v_mov_b32_e32 v0, v42
	v_mul_f32_e32 v1, 0x3fb8aa3b, v7
	v_exp_f32_e32 v1, v1
	s_waitcnt lgkmcnt(0)
	v_lshlrev_b32_e32 v0, 16, v0
	v_mul_f32_e32 v0, v3, v0
	v_mul_f32_e32 v1, v0, v1
	v_cndmask_b32_e64 v131, v0, v1, s[40:41]
	v_mov_b32_e32 v0, v43
	s_waitcnt lgkmcnt(0)
	v_lshlrev_b32_e32 v4, 16, v0
	ds_read_b128 v[0:3], v137 offset:60800
	s_waitcnt lgkmcnt(0)
	v_mul_f32_e32 v0, v0, v4
	ds_read_b128 v[4:7], v137 offset:60544
	s_waitcnt lgkmcnt(0)
	v_mul_f32_e32 v4, 0x3fb8aa3b, v4
	v_exp_f32_e32 v4, v4
	s_nop 0
	v_mul_f32_e32 v4, v0, v4
	v_cndmask_b32_e64 v126, v0, v4, s[40:41]
	v_mov_b32_e32 v0, v44
	s_waitcnt lgkmcnt(0)
	v_lshlrev_b32_e32 v0, 16, v0
	v_mul_f32_e32 v0, v1, v0
	v_mul_f32_e32 v1, 0x3fb8aa3b, v5
	v_exp_f32_e32 v1, v1
	s_nop 0
	v_mul_f32_e32 v1, v0, v1
	v_cndmask_b32_e64 v115, v0, v1, s[40:41]
	v_mov_b32_e32 v0, v45
	v_mul_f32_e32 v1, 0x3fb8aa3b, v6
	v_exp_f32_e32 v1, v1
	s_waitcnt lgkmcnt(0)
	v_lshlrev_b32_e32 v0, 16, v0
	v_mul_f32_e32 v0, v2, v0
	v_mul_f32_e32 v1, v0, v1
	v_cndmask_b32_e64 v114, v0, v1, s[40:41]
	v_mov_b32_e32 v0, v46
	v_mul_f32_e32 v1, 0x3fb8aa3b, v7
	v_exp_f32_e32 v1, v1
	s_waitcnt lgkmcnt(0)
	v_lshlrev_b32_e32 v0, 16, v0
	v_mul_f32_e32 v0, v3, v0
	v_mul_f32_e32 v1, v0, v1
	v_cndmask_b32_e64 v111, v0, v1, s[40:41]
	v_mov_b32_e32 v0, v47
	s_waitcnt lgkmcnt(0)
	v_lshlrev_b32_e32 v4, 16, v0
	ds_read_b128 v[0:3], v137 offset:60816
	s_waitcnt lgkmcnt(0)
	v_mul_f32_e32 v0, v0, v4
	ds_read_b128 v[4:7], v137 offset:60560
	s_waitcnt lgkmcnt(0)
	v_mul_f32_e32 v4, 0x3fb8aa3b, v4
	v_exp_f32_e32 v4, v4
	s_nop 0
	v_mul_f32_e32 v4, v0, v4
	v_cndmask_b32_e64 v113, v0, v4, s[40:41]
	v_mov_b32_e32 v0, v48
	s_waitcnt lgkmcnt(0)
	v_lshlrev_b32_e32 v0, 16, v0
	v_mul_f32_e32 v0, v1, v0
	v_mul_f32_e32 v1, 0x3fb8aa3b, v5
	v_exp_f32_e32 v1, v1
	s_nop 0
	v_mul_f32_e32 v1, v0, v1
	v_cndmask_b32_e64 v112, v0, v1, s[40:41]
	v_mov_b32_e32 v0, v49
	v_mul_f32_e32 v1, 0x3fb8aa3b, v6
	v_exp_f32_e32 v1, v1
	s_waitcnt lgkmcnt(0)
	v_lshlrev_b32_e32 v0, 16, v0
	v_mul_f32_e32 v0, v2, v0
	v_mul_f32_e32 v1, v0, v1
	v_cndmask_b32_e64 v108, v0, v1, s[40:41]
	v_mov_b32_e32 v0, v50
	v_mul_f32_e32 v1, 0x3fb8aa3b, v7
	v_exp_f32_e32 v1, v1
	s_waitcnt lgkmcnt(0)
	v_lshlrev_b32_e32 v0, 16, v0
	v_mul_f32_e32 v0, v3, v0
	v_mul_f32_e32 v1, v0, v1
	v_cndmask_b32_e64 v110, v0, v1, s[40:41]
	v_mov_b32_e32 v0, v51
	s_waitcnt lgkmcnt(0)
	v_lshlrev_b32_e32 v4, 16, v0
	ds_read_b128 v[0:3], v137 offset:60832
	s_waitcnt lgkmcnt(0)
	v_mul_f32_e32 v0, v0, v4
	ds_read_b128 v[4:7], v137 offset:60576
	s_waitcnt lgkmcnt(0)
	v_mul_f32_e32 v4, 0x3fb8aa3b, v4
	v_exp_f32_e32 v4, v4
	s_nop 0
	v_mul_f32_e32 v4, v0, v4
	v_cndmask_b32_e64 v107, v0, v4, s[40:41]
	v_mov_b32_e32 v0, v52
	s_waitcnt lgkmcnt(0)
	v_lshlrev_b32_e32 v0, 16, v0
	v_mul_f32_e32 v0, v1, v0
	v_mul_f32_e32 v1, 0x3fb8aa3b, v5
	v_exp_f32_e32 v1, v1
	s_nop 0
	v_mul_f32_e32 v1, v0, v1
	v_cndmask_b32_e64 v104, v0, v1, s[40:41]
	v_mov_b32_e32 v0, v53
	v_mul_f32_e32 v1, 0x3fb8aa3b, v6
	v_exp_f32_e32 v1, v1
	s_waitcnt lgkmcnt(0)
	v_lshlrev_b32_e32 v0, 16, v0
	v_mul_f32_e32 v0, v2, v0
	v_mul_f32_e32 v1, v0, v1
	v_cndmask_b32_e64 v103, v0, v1, s[40:41]
	v_mov_b32_e32 v0, v54
	v_mul_f32_e32 v1, 0x3fb8aa3b, v7
	v_exp_f32_e32 v1, v1
	s_waitcnt lgkmcnt(0)
	v_lshlrev_b32_e32 v0, 16, v0
	v_mul_f32_e32 v0, v3, v0
	v_mul_f32_e32 v1, v0, v1
	v_cndmask_b32_e64 v101, v0, v1, s[40:41]
	v_mov_b32_e32 v0, v55
	s_waitcnt lgkmcnt(0)
	v_lshlrev_b32_e32 v4, 16, v0
	ds_read_b128 v[0:3], v137 offset:60848
	s_waitcnt lgkmcnt(0)
	v_mul_f32_e32 v0, v0, v4
	ds_read_b128 v[4:7], v137 offset:60592
	s_waitcnt lgkmcnt(0)
	v_mul_f32_e32 v4, 0x3fb8aa3b, v4
	v_exp_f32_e32 v4, v4
	s_nop 0
	v_mul_f32_e32 v4, v0, v4
	v_cndmask_b32_e64 v102, v0, v4, s[40:41]
	v_mov_b32_e32 v0, v56
	s_waitcnt lgkmcnt(0)
	v_lshlrev_b32_e32 v0, 16, v0
	v_mul_f32_e32 v0, v1, v0
	v_mul_f32_e32 v1, 0x3fb8aa3b, v5
	v_exp_f32_e32 v1, v1
	s_nop 0
	v_mul_f32_e32 v1, v0, v1
	v_cndmask_b32_e64 v100, v0, v1, s[40:41]
	v_mov_b32_e32 v0, v57
	v_mul_f32_e32 v1, 0x3fb8aa3b, v6
	v_exp_f32_e32 v1, v1
	s_waitcnt lgkmcnt(0)
	v_lshlrev_b32_e32 v0, 16, v0
	v_mul_f32_e32 v0, v2, v0
	v_mul_f32_e32 v1, v0, v1
	v_cndmask_b32_e64 v98, v0, v1, s[40:41]
	v_mov_b32_e32 v0, v58
	v_mul_f32_e32 v1, 0x3fb8aa3b, v7
	v_exp_f32_e32 v1, v1
	s_waitcnt lgkmcnt(0)
	v_lshlrev_b32_e32 v0, 16, v0
	v_mul_f32_e32 v0, v3, v0
	v_mul_f32_e32 v1, v0, v1
	v_cndmask_b32_e64 v99, v0, v1, s[40:41]
	v_mov_b32_e32 v0, v59
	s_waitcnt lgkmcnt(0)
	v_lshlrev_b32_e32 v4, 16, v0
	ds_read_b128 v[0:3], v137 offset:60864
	s_waitcnt lgkmcnt(0)
	v_mul_f32_e32 v0, v0, v4
	ds_read_b128 v[4:7], v137 offset:60608
	s_waitcnt lgkmcnt(0)
	v_mul_f32_e32 v4, 0x3fb8aa3b, v4
	v_exp_f32_e32 v4, v4
	s_nop 0
	v_mul_f32_e32 v4, v0, v4
	v_cndmask_b32_e64 v97, v0, v4, s[40:41]
	v_mov_b32_e32 v0, v60
	s_waitcnt lgkmcnt(0)
	v_lshlrev_b32_e32 v0, 16, v0
	v_mul_f32_e32 v0, v1, v0
	v_mul_f32_e32 v1, 0x3fb8aa3b, v5
	v_exp_f32_e32 v1, v1
	s_nop 0
	v_mul_f32_e32 v1, v0, v1
	v_cndmask_b32_e64 v96, v0, v1, s[40:41]
	v_mov_b32_e32 v0, v61
	v_mul_f32_e32 v1, 0x3fb8aa3b, v6
	v_exp_f32_e32 v1, v1
	s_waitcnt lgkmcnt(0)
	v_lshlrev_b32_e32 v0, 16, v0
	v_mul_f32_e32 v0, v2, v0
	v_mul_f32_e32 v1, v0, v1
	v_cndmask_b32_e64 v95, v0, v1, s[40:41]
	v_mov_b32_e32 v0, v62
	v_mul_f32_e32 v1, 0x3fb8aa3b, v7
	v_exp_f32_e32 v1, v1
	s_waitcnt lgkmcnt(0)
	v_lshlrev_b32_e32 v0, 16, v0
	v_mul_f32_e32 v0, v3, v0
	v_mul_f32_e32 v1, v0, v1
	v_cndmask_b32_e64 v93, v0, v1, s[40:41]
	v_mov_b32_e32 v0, v63
	s_waitcnt lgkmcnt(0)
	v_lshlrev_b32_e32 v4, 16, v0
	ds_read_b128 v[0:3], v137 offset:60880
	s_waitcnt lgkmcnt(0)
	v_mul_f32_e32 v0, v0, v4
	ds_read_b128 v[4:7], v137 offset:60624
	s_waitcnt lgkmcnt(0)
	v_mul_f32_e32 v4, 0x3fb8aa3b, v4
	v_exp_f32_e32 v4, v4
	s_nop 0
	v_mul_f32_e32 v4, v0, v4
	v_cndmask_b32_e64 v94, v0, v4, s[40:41]
	v_mov_b32_e32 v0, v64
	s_waitcnt lgkmcnt(0)
	v_lshlrev_b32_e32 v0, 16, v0
	v_mul_f32_e32 v0, v1, v0
	v_mul_f32_e32 v1, 0x3fb8aa3b, v5
	v_exp_f32_e32 v1, v1
	s_nop 0
	v_mul_f32_e32 v1, v0, v1
	v_cndmask_b32_e64 v92, v0, v1, s[40:41]
	v_mov_b32_e32 v0, v65
	v_mul_f32_e32 v1, 0x3fb8aa3b, v6
	v_exp_f32_e32 v1, v1
	s_waitcnt lgkmcnt(0)
	v_lshlrev_b32_e32 v0, 16, v0
	v_mul_f32_e32 v0, v2, v0
	v_mul_f32_e32 v1, v0, v1
	v_cndmask_b32_e64 v90, v0, v1, s[40:41]
	v_mov_b32_e32 v0, v66
	v_mul_f32_e32 v1, 0x3fb8aa3b, v7
	v_exp_f32_e32 v1, v1
	s_waitcnt lgkmcnt(0)
	v_lshlrev_b32_e32 v0, 16, v0
	v_mul_f32_e32 v0, v3, v0
	v_mul_f32_e32 v1, v0, v1
	v_cndmask_b32_e64 v91, v0, v1, s[40:41]
	v_mov_b32_e32 v0, v67
	s_waitcnt lgkmcnt(0)
	v_lshlrev_b32_e32 v4, 16, v0
	ds_read_b128 v[0:3], v137 offset:60896
	s_waitcnt lgkmcnt(0)
	v_mul_f32_e32 v0, v0, v4
	ds_read_b128 v[4:7], v137 offset:60640
	s_waitcnt lgkmcnt(0)
	v_mul_f32_e32 v4, 0x3fb8aa3b, v4
	v_exp_f32_e32 v4, v4
	s_nop 0
	v_mul_f32_e32 v4, v0, v4
	v_cndmask_b32_e64 v89, v0, v4, s[40:41]
	v_mov_b32_e32 v0, v68
	s_waitcnt lgkmcnt(0)
	v_lshlrev_b32_e32 v0, 16, v0
	v_mul_f32_e32 v0, v1, v0
	v_mul_f32_e32 v1, 0x3fb8aa3b, v5
	v_exp_f32_e32 v1, v1
	s_nop 0
	v_mul_f32_e32 v1, v0, v1
	v_cndmask_b32_e64 v88, v0, v1, s[40:41]
	v_mov_b32_e32 v0, v69
	v_mul_f32_e32 v1, 0x3fb8aa3b, v6
	v_exp_f32_e32 v1, v1
	s_waitcnt lgkmcnt(0)
	v_lshlrev_b32_e32 v0, 16, v0
	v_mul_f32_e32 v0, v2, v0
	v_mul_f32_e32 v1, v0, v1
	v_cndmask_b32_e64 v87, v0, v1, s[40:41]
	v_mov_b32_e32 v0, v70
	v_mul_f32_e32 v1, 0x3fb8aa3b, v7
	v_exp_f32_e32 v1, v1
	s_waitcnt lgkmcnt(0)
	v_lshlrev_b32_e32 v0, 16, v0
	v_mul_f32_e32 v0, v3, v0
	v_mul_f32_e32 v1, v0, v1
	v_cndmask_b32_e64 v86, v0, v1, s[40:41]
	v_mov_b32_e32 v0, v71
	s_waitcnt lgkmcnt(0)
	v_lshlrev_b32_e32 v4, 16, v0
	ds_read_b128 v[0:3], v137 offset:60912
	s_waitcnt lgkmcnt(0)
	v_mul_f32_e32 v0, v0, v4
	ds_read_b128 v[4:7], v137 offset:60656
	s_waitcnt lgkmcnt(0)
	v_mul_f32_e32 v4, 0x3fb8aa3b, v4
	v_exp_f32_e32 v4, v4
	s_nop 0
	v_mul_f32_e32 v4, v0, v4
	v_cndmask_b32_e64 v85, v0, v4, s[40:41]
	v_mov_b32_e32 v0, v72
	s_waitcnt lgkmcnt(0)
	v_lshlrev_b32_e32 v0, 16, v0
	v_mul_f32_e32 v0, v1, v0
	v_mul_f32_e32 v1, 0x3fb8aa3b, v5
	v_exp_f32_e32 v1, v1
	s_nop 0
	v_mul_f32_e32 v1, v0, v1
	v_cndmask_b32_e64 v84, v0, v1, s[40:41]
	v_mov_b32_e32 v0, v73
	v_mul_f32_e32 v1, 0x3fb8aa3b, v6
	v_exp_f32_e32 v1, v1
	s_waitcnt lgkmcnt(0)
	v_lshlrev_b32_e32 v0, 16, v0
	v_mul_f32_e32 v0, v2, v0
	v_mul_f32_e32 v1, v0, v1
	v_cndmask_b32_e64 v83, v0, v1, s[40:41]
	v_mov_b32_e32 v0, v80
	v_mul_f32_e32 v1, 0x3fb8aa3b, v7
	v_exp_f32_e32 v1, v1
	s_waitcnt lgkmcnt(0)
	v_lshlrev_b32_e32 v0, 16, v0
	v_mul_f32_e32 v0, v3, v0
	v_mul_f32_e32 v1, v0, v1
	v_cndmask_b32_e64 v82, v0, v1, s[40:41]
	ds_read_b128 v[234:237], v137 offset:29440
	s_waitcnt lgkmcnt(15)
	v_fma_f32 v0, -v81, v202, v105
	v_add_f32_e32 v0, 0, v0
	s_nop 0
	ds_read_b128 v[238:241], v137 offset:29456
	s_waitcnt lgkmcnt(15)
	v_fma_f32 v1, -v81, v206, v106
	v_fma_f32 v2, -v0, v207, 0
	v_add_f32_e32 v1, v1, v2
	s_nop 0
	ds_read_b128 v[248:251], v137 offset:29696
	s_waitcnt lgkmcnt(15)
	v_fma_f32 v2, -v81, v210, v109
	v_fma_f32 v3, -v0, v211, 0
	v_fma_f32 v2, -v1, v212, v2
	v_add_f32_e32 v2, v3, v2
	s_nop 0
	ds_read_b128 v[252:255], v137 offset:29712
	s_waitcnt lgkmcnt(15)
	v_fma_f32 v3, -v81, v214, v8
	v_fma_f32 v4, -v0, v215, 0
	v_fma_f32 v3, -v1, v216, v3
	v_fma_f32 v4, -v2, v217, v4
	v_add_f32_e32 v3, v3, v4
	s_nop 0
	ds_read_b128 v[202:205], v137 offset:29952
	s_waitcnt lgkmcnt(15)
	v_fma_f32 v4, -v81, v218, v9
	v_fma_f32 v5, -v0, v219, 0
	v_fma_f32 v4, -v1, v220, v4
	v_fma_f32 v5, -v2, v221, v5
	ds_read_b128 v[206:209], v137 offset:29968
	s_waitcnt lgkmcnt(15)
	v_fma_f32 v4, -v3, v222, v4
	v_add_f32_e32 v4, v5, v4
	s_nop 0
	ds_read_b128 v[210:213], v137 offset:29984
	s_waitcnt lgkmcnt(15)
	v_fma_f32 v5, -v81, v226, v10
	v_fma_f32 v6, -v0, v227, 0
	v_fma_f32 v5, -v1, v228, v5
	v_fma_f32 v6, -v2, v229, v6
	ds_read_b128 v[214:217], v137 offset:30208
	s_waitcnt lgkmcnt(15)
	v_fma_f32 v5, -v3, v230, v5
	v_fma_f32 v6, -v4, v231, v6
	v_add_f32_e32 v5, v5, v6
	s_nop 0
	ds_read_b128 v[218:221], v137 offset:30224
	s_waitcnt lgkmcnt(8)
	v_fma_f32 v6, -v81, v234, v11
	v_fma_f32 v7, -v0, v235, 0
	v_fma_f32 v6, -v1, v236, v6
	v_fma_f32 v7, -v2, v237, v7
	ds_read_b128 v[222:225], v137 offset:30240
	s_waitcnt lgkmcnt(8)
	v_fma_f32 v6, -v3, v238, v6
	v_fma_f32 v7, -v4, v239, v7
	v_fma_f32 v6, -v5, v240, v6
	v_add_f32_e32 v7, v7, v6
	s_nop 0
	ds_read_b128 v[226:229], v137 offset:30464
	s_waitcnt lgkmcnt(8)
	v_fma_f32 v6, -v81, v248, v116
	v_fma_f32 v8, -v0, v249, 0
	v_fma_f32 v6, -v1, v250, v6
	v_fma_f32 v8, -v2, v251, v8
	ds_read_b128 v[230:233], v137 offset:30480
	s_waitcnt lgkmcnt(8)
	v_fma_f32 v6, -v3, v252, v6
	v_fma_f32 v8, -v4, v253, v8
	v_fma_f32 v6, -v5, v254, v6
	v_fma_f32 v8, -v7, v255, v8
	v_add_f32_e32 v6, v6, v8
	s_nop 0
	ds_read_b128 v[234:237], v137 offset:30496
	s_waitcnt lgkmcnt(8)
	v_fma_f32 v8, -v81, v202, v117
	v_fma_f32 v9, -v0, v203, 0
	v_fma_f32 v8, -v1, v204, v8
	v_fma_f32 v9, -v2, v205, v9
	ds_read_b128 v[238:241], v137 offset:30720
	s_waitcnt lgkmcnt(8)
	v_fma_f32 v8, -v3, v206, v8
	v_fma_f32 v9, -v4, v207, v9
	v_fma_f32 v8, -v5, v208, v8
	v_fma_f32 v9, -v7, v209, v9
	ds_read_b128 v[248:251], v137 offset:30736
	s_waitcnt lgkmcnt(8)
	v_fma_f32 v8, -v6, v210, v8
	v_add_f32_e32 v8, v9, v8
	s_nop 0
	ds_read_b128 v[252:255], v137 offset:30752
	s_waitcnt lgkmcnt(8)
	v_fma_f32 v9, -v81, v214, v120
	v_fma_f32 v10, -v0, v215, 0
	v_fma_f32 v9, -v1, v216, v9
	v_fma_f32 v10, -v2, v217, v10
	ds_read_b128 v[202:205], v137 offset:30976
	s_waitcnt lgkmcnt(8)
	v_fma_f32 v9, -v3, v218, v9
	v_fma_f32 v10, -v4, v219, v10
	v_fma_f32 v9, -v5, v220, v9
	v_fma_f32 v10, -v7, v221, v10
	ds_read_b128 v[206:209], v137 offset:30992
	s_waitcnt lgkmcnt(8)
	v_fma_f32 v9, -v6, v222, v9
	v_fma_f32 v10, -v8, v223, v10
	v_add_f32_e32 v9, v9, v10
	s_nop 0
	ds_read_b128 v[210:213], v137 offset:31008
	s_waitcnt lgkmcnt(8)
	v_fma_f32 v10, -v81, v226, v121
	v_fma_f32 v11, -v0, v227, 0
	v_fma_f32 v10, -v1, v228, v10
	v_fma_f32 v11, -v2, v229, v11
	ds_read_b128 v[214:217], v137 offset:31024
	s_waitcnt lgkmcnt(8)
	v_fma_f32 v10, -v3, v230, v10
	v_fma_f32 v11, -v4, v231, v11
	v_fma_f32 v10, -v5, v232, v10
	v_fma_f32 v11, -v7, v233, v11
	ds_read_b128 v[218:221], v137 offset:31232
	s_waitcnt lgkmcnt(8)
	v_fma_f32 v10, -v6, v234, v10
	v_fma_f32 v11, -v8, v235, v11
	v_fma_f32 v10, -v9, v236, v10
	v_add_f32_e32 v10, v11, v10
	s_nop 0
	ds_read_b128 v[222:225], v137 offset:31248
	s_waitcnt lgkmcnt(8)
	v_fma_f32 v11, -v81, v238, v122
	v_fma_f32 v62, -v0, v239, 0
	v_fma_f32 v11, -v1, v240, v11
	v_fma_f32 v62, -v2, v241, v62
	ds_read_b128 v[226:229], v137 offset:31264
	s_waitcnt lgkmcnt(8)
	v_fma_f32 v11, -v3, v248, v11
	v_fma_f32 v62, -v4, v249, v62
	v_fma_f32 v11, -v5, v250, v11
	v_fma_f32 v62, -v7, v251, v62
	ds_read_b128 v[230:233], v137 offset:31280
	s_waitcnt lgkmcnt(8)
	v_fma_f32 v11, -v6, v252, v11
	v_fma_f32 v62, -v8, v253, v62
	v_fma_f32 v11, -v9, v254, v11
	v_fma_f32 v62, -v10, v255, v62
	v_add_f32_e32 v11, v11, v62
	s_nop 0
	ds_read_b128 v[234:237], v137 offset:31488
	s_waitcnt lgkmcnt(8)
	v_fma_f32 v62, -v81, v202, v123
	v_fma_f32 v63, -v0, v203, 0
	v_fma_f32 v62, -v1, v204, v62
	v_fma_f32 v63, -v2, v205, v63
	ds_read_b128 v[238:241], v137 offset:31504
	s_waitcnt lgkmcnt(8)
	v_fma_f32 v62, -v3, v206, v62
	v_fma_f32 v63, -v4, v207, v63
	v_fma_f32 v62, -v5, v208, v62
	v_fma_f32 v63, -v7, v209, v63
	ds_read_b128 v[248:251], v137 offset:31520
	s_waitcnt lgkmcnt(8)
	v_fma_f32 v62, -v6, v210, v62
	v_fma_f32 v63, -v8, v211, v63
	v_fma_f32 v62, -v9, v212, v62
	v_fma_f32 v63, -v10, v213, v63
	ds_read_b128 v[252:255], v137 offset:31536
	s_waitcnt lgkmcnt(8)
	v_fma_f32 v60, -v11, v214, v62
	v_add_f32_e32 v60, v63, v60
	s_nop 0
	ds_read_b128 v[202:205], v137 offset:31744
	s_waitcnt lgkmcnt(8)
	v_fma_f32 v62, -v81, v218, v124
	v_fma_f32 v63, -v0, v219, 0
	v_fma_f32 v62, -v1, v220, v62
	v_fma_f32 v63, -v2, v221, v63
	ds_read_b128 v[206:209], v137 offset:31760
	s_waitcnt lgkmcnt(8)
	v_fma_f32 v62, -v3, v222, v62
	v_fma_f32 v63, -v4, v223, v63
	v_fma_f32 v62, -v5, v224, v62
	v_fma_f32 v63, -v7, v225, v63
	ds_read_b128 v[210:213], v137 offset:31776
	s_waitcnt lgkmcnt(8)
	v_fma_f32 v62, -v6, v226, v62
	v_fma_f32 v63, -v8, v227, v63
	v_fma_f32 v62, -v9, v228, v62
	v_fma_f32 v63, -v10, v229, v63
	ds_read_b128 v[214:217], v137 offset:31792
	s_waitcnt lgkmcnt(8)
	v_fma_f32 v62, -v11, v230, v62
	v_fma_f32 v61, -v60, v231, v63
	v_add_f32_e32 v61, v62, v61
	s_nop 0
	ds_read_b128 v[218:221], v137 offset:32000
	s_waitcnt lgkmcnt(8)
	v_fma_f32 v62, -v81, v234, v143
	v_fma_f32 v63, -v0, v235, 0
	v_fma_f32 v62, -v1, v236, v62
	v_fma_f32 v63, -v2, v237, v63
	ds_read_b128 v[222:225], v137 offset:32016
	s_waitcnt lgkmcnt(8)
	v_fma_f32 v62, -v3, v238, v62
	v_fma_f32 v63, -v4, v239, v63
	v_fma_f32 v62, -v5, v240, v62
	v_fma_f32 v63, -v7, v241, v63
	ds_read_b128 v[226:229], v137 offset:32032
	s_waitcnt lgkmcnt(8)
	v_fma_f32 v62, -v6, v248, v62
	v_fma_f32 v63, -v8, v249, v63
	v_fma_f32 v62, -v9, v250, v62
	v_fma_f32 v63, -v10, v251, v63
	ds_read_b128 v[230:233], v137 offset:32048
	s_waitcnt lgkmcnt(8)
	v_fma_f32 v62, -v11, v252, v62
	v_fma_f32 v63, -v60, v253, v63
	v_fma_f32 v58, -v61, v254, v62
	v_add_f32_e32 v58, v63, v58
	s_nop 0
	ds_read_b128 v[234:237], v137 offset:32064
	s_waitcnt lgkmcnt(8)
	v_fma_f32 v62, -v81, v202, v145
	v_fma_f32 v63, -v0, v203, 0
	v_fma_f32 v62, -v1, v204, v62
	v_fma_f32 v63, -v2, v205, v63
	ds_read_b128 v[238:241], v137 offset:32256
	s_waitcnt lgkmcnt(8)
	v_fma_f32 v62, -v3, v206, v62
	v_fma_f32 v63, -v4, v207, v63
	v_fma_f32 v62, -v5, v208, v62
	v_fma_f32 v63, -v7, v209, v63
	ds_read_b128 v[248:251], v137 offset:32272
	s_waitcnt lgkmcnt(8)
	v_fma_f32 v62, -v6, v210, v62
	v_fma_f32 v63, -v8, v211, v63
	v_fma_f32 v62, -v9, v212, v62
	v_fma_f32 v63, -v10, v213, v63
	ds_read_b128 v[252:255], v137 offset:32288
	s_waitcnt lgkmcnt(8)
	v_fma_f32 v62, -v11, v214, v62
	v_fma_f32 v63, -v60, v215, v63
	v_fma_f32 v62, -v61, v216, v62
	v_fma_f32 v59, -v58, v217, v63
	v_add_f32_e32 v59, v62, v59
	s_nop 0
	ds_read_b128 v[202:205], v137 offset:32304
	s_waitcnt lgkmcnt(8)
	v_fma_f32 v62, -v81, v218, v133
	v_fma_f32 v63, -v0, v219, 0
	v_fma_f32 v62, -v1, v220, v62
	v_fma_f32 v63, -v2, v221, v63
	ds_read_b128 v[206:209], v137 offset:32320
	s_waitcnt lgkmcnt(8)
	v_fma_f32 v62, -v3, v222, v62
	v_fma_f32 v63, -v4, v223, v63
	v_fma_f32 v62, -v5, v224, v62
	v_fma_f32 v63, -v7, v225, v63
	ds_read_b128 v[210:213], v137 offset:32512
	s_waitcnt lgkmcnt(8)
	v_fma_f32 v62, -v6, v226, v62
	v_fma_f32 v63, -v8, v227, v63
	v_fma_f32 v62, -v9, v228, v62
	v_fma_f32 v63, -v10, v229, v63
	ds_read_b128 v[214:217], v137 offset:32528
	s_waitcnt lgkmcnt(8)
	v_fma_f32 v62, -v11, v230, v62
	v_fma_f32 v63, -v60, v231, v63
	v_fma_f32 v62, -v61, v232, v62
	v_fma_f32 v63, -v58, v233, v63
	ds_read_b128 v[218:221], v137 offset:32544
	s_waitcnt lgkmcnt(8)
	v_fma_f32 v56, -v59, v234, v62
	v_add_f32_e32 v56, v63, v56
	s_nop 0
	ds_read_b128 v[222:225], v137 offset:32560
	s_waitcnt lgkmcnt(8)
	v_fma_f32 v62, -v81, v238, v129
	v_fma_f32 v63, -v0, v239, 0
	v_fma_f32 v62, -v1, v240, v62
	v_fma_f32 v63, -v2, v241, v63
	ds_read_b128 v[226:229], v137 offset:32576
	s_waitcnt lgkmcnt(8)
	v_fma_f32 v62, -v3, v248, v62
	v_fma_f32 v63, -v4, v249, v63
	v_fma_f32 v62, -v5, v250, v62
	v_fma_f32 v63, -v7, v251, v63
	ds_read_b128 v[230:233], v137 offset:32768
	s_waitcnt lgkmcnt(8)
	v_fma_f32 v62, -v6, v252, v62
	v_fma_f32 v63, -v8, v253, v63
	v_fma_f32 v62, -v9, v254, v62
	v_fma_f32 v63, -v10, v255, v63
	ds_read_b128 v[234:237], v137 offset:32784
	s_waitcnt lgkmcnt(8)
	v_fma_f32 v62, -v11, v202, v62
	v_fma_f32 v63, -v60, v203, v63
	v_fma_f32 v62, -v61, v204, v62
	v_fma_f32 v63, -v58, v205, v63
	ds_read_b128 v[238:241], v137 offset:32800
	s_waitcnt lgkmcnt(8)
	v_fma_f32 v62, -v59, v206, v62
	v_fma_f32 v57, -v56, v207, v63
	v_add_f32_e32 v57, v62, v57
	s_nop 0
	ds_read_b128 v[248:251], v137 offset:32816
	s_waitcnt lgkmcnt(8)
	v_fma_f32 v62, -v81, v210, v125
	v_fma_f32 v63, -v0, v211, 0
	v_fma_f32 v62, -v1, v212, v62
	v_fma_f32 v63, -v2, v213, v63
	ds_read_b128 v[252:255], v137 offset:32832
	s_waitcnt lgkmcnt(8)
	v_fma_f32 v62, -v3, v214, v62
	v_fma_f32 v63, -v4, v215, v63
	v_fma_f32 v62, -v5, v216, v62
	v_fma_f32 v63, -v7, v217, v63
	ds_read_b128 v[202:205], v137 offset:33024
	s_waitcnt lgkmcnt(8)
	v_fma_f32 v62, -v6, v218, v62
	v_fma_f32 v63, -v8, v219, v63
	v_fma_f32 v62, -v9, v220, v62
	v_fma_f32 v63, -v10, v221, v63
	ds_read_b128 v[206:209], v137 offset:33040
	s_waitcnt lgkmcnt(8)
	v_fma_f32 v62, -v11, v222, v62
	v_fma_f32 v63, -v60, v223, v63
	v_fma_f32 v62, -v61, v224, v62
	v_fma_f32 v63, -v58, v225, v63
	ds_read_b128 v[210:213], v137 offset:33056
	s_waitcnt lgkmcnt(8)
	v_fma_f32 v62, -v59, v226, v62
	v_fma_f32 v63, -v56, v227, v63
	v_fma_f32 v54, -v57, v228, v62
	v_add_f32_e32 v54, v63, v54
	s_nop 0
	ds_read_b128 v[214:217], v137 offset:33072
	s_waitcnt lgkmcnt(8)
	v_fma_f32 v62, -v81, v230, v136
	v_fma_f32 v63, -v0, v231, 0
	v_fma_f32 v62, -v1, v232, v62
	v_fma_f32 v63, -v2, v233, v63
	ds_read_b128 v[218:221], v137 offset:33088
	s_waitcnt lgkmcnt(8)
	v_fma_f32 v62, -v3, v234, v62
	v_fma_f32 v63, -v4, v235, v63
	v_fma_f32 v62, -v5, v236, v62
	v_fma_f32 v63, -v7, v237, v63
	ds_read_b128 v[222:225], v137 offset:33104
	s_waitcnt lgkmcnt(8)
	v_fma_f32 v62, -v6, v238, v62
	v_fma_f32 v63, -v8, v239, v63
	v_fma_f32 v62, -v9, v240, v62
	v_fma_f32 v63, -v10, v241, v63
	ds_read_b128 v[226:229], v137 offset:33280
	s_waitcnt lgkmcnt(8)
	v_fma_f32 v62, -v11, v248, v62
	v_fma_f32 v63, -v60, v249, v63
	v_fma_f32 v62, -v61, v250, v62
	v_fma_f32 v63, -v58, v251, v63
	ds_read_b128 v[230:233], v137 offset:33296
	s_waitcnt lgkmcnt(8)
	v_fma_f32 v62, -v59, v252, v62
	v_fma_f32 v63, -v56, v253, v63
	v_fma_f32 v62, -v57, v254, v62
	v_fma_f32 v55, -v54, v255, v63
	v_add_f32_e32 v55, v62, v55
	s_nop 0
	ds_read_b128 v[234:237], v137 offset:33312
	s_waitcnt lgkmcnt(8)
	v_fma_f32 v62, -v81, v202, v134
	v_fma_f32 v63, -v0, v203, 0
	v_fma_f32 v62, -v1, v204, v62
	v_fma_f32 v63, -v2, v205, v63
	ds_read_b128 v[238:241], v137 offset:33328
	s_waitcnt lgkmcnt(8)
	v_fma_f32 v62, -v3, v206, v62
	v_fma_f32 v63, -v4, v207, v63
	v_fma_f32 v62, -v5, v208, v62
	v_fma_f32 v63, -v7, v209, v63
	ds_read_b128 v[248:251], v137 offset:33344
	s_waitcnt lgkmcnt(8)
	v_fma_f32 v62, -v6, v210, v62
	v_fma_f32 v63, -v8, v211, v63
	v_fma_f32 v62, -v9, v212, v62
	v_fma_f32 v63, -v10, v213, v63
	ds_read_b128 v[252:255], v137 offset:33360
	s_waitcnt lgkmcnt(8)
	v_fma_f32 v62, -v11, v214, v62
	v_fma_f32 v63, -v60, v215, v63
	v_fma_f32 v62, -v61, v216, v62
	v_fma_f32 v63, -v58, v217, v63
	ds_read_b128 v[202:205], v137 offset:33536
	s_waitcnt lgkmcnt(8)
	v_fma_f32 v62, -v59, v218, v62
	v_fma_f32 v63, -v56, v219, v63
	v_fma_f32 v62, -v57, v220, v62
	v_fma_f32 v63, -v54, v221, v63
	ds_read_b128 v[206:209], v137 offset:33552
	s_waitcnt lgkmcnt(8)
	v_fma_f32 v52, -v55, v222, v62
	v_add_f32_e32 v52, v63, v52
	s_nop 0
	ds_read_b128 v[210:213], v137 offset:33568
	s_waitcnt lgkmcnt(8)
	v_fma_f32 v62, -v81, v226, v132
	v_fma_f32 v63, -v0, v227, 0
	v_fma_f32 v62, -v1, v228, v62
	v_fma_f32 v63, -v2, v229, v63
	ds_read_b128 v[214:217], v137 offset:33584
	s_waitcnt lgkmcnt(8)
	v_fma_f32 v62, -v3, v230, v62
	v_fma_f32 v63, -v4, v231, v63
	v_fma_f32 v62, -v5, v232, v62
	v_fma_f32 v63, -v7, v233, v63
	ds_read_b128 v[218:221], v137 offset:33600
	s_waitcnt lgkmcnt(8)
	v_fma_f32 v62, -v6, v234, v62
	v_fma_f32 v63, -v8, v235, v63
	v_fma_f32 v62, -v9, v236, v62
	v_fma_f32 v63, -v10, v237, v63
	ds_read_b128 v[222:225], v137 offset:33616
	s_waitcnt lgkmcnt(8)
	v_fma_f32 v62, -v11, v238, v62
	v_fma_f32 v63, -v60, v239, v63
	v_fma_f32 v62, -v61, v240, v62
	v_fma_f32 v63, -v58, v241, v63
	ds_read_b128 v[226:229], v137 offset:33792
	s_waitcnt lgkmcnt(8)
	v_fma_f32 v62, -v59, v248, v62
	v_fma_f32 v63, -v56, v249, v63
	v_fma_f32 v62, -v57, v250, v62
	v_fma_f32 v63, -v54, v251, v63
	ds_read_b128 v[230:233], v137 offset:33808
	s_waitcnt lgkmcnt(8)
	v_fma_f32 v62, -v55, v252, v62
	v_fma_f32 v53, -v52, v253, v63
	v_add_f32_e32 v53, v62, v53
	s_nop 0
	ds_read_b128 v[234:237], v137 offset:33824
	s_waitcnt lgkmcnt(8)
	v_fma_f32 v62, -v81, v202, v147
	v_fma_f32 v63, -v0, v203, 0
	v_fma_f32 v62, -v1, v204, v62
	v_fma_f32 v63, -v2, v205, v63
	ds_read_b128 v[238:241], v137 offset:33840
	s_waitcnt lgkmcnt(8)
	v_fma_f32 v62, -v3, v206, v62
	v_fma_f32 v63, -v4, v207, v63
	v_fma_f32 v62, -v5, v208, v62
	v_fma_f32 v63, -v7, v209, v63
	ds_read_b128 v[248:251], v137 offset:33856
	s_waitcnt lgkmcnt(8)
	v_fma_f32 v62, -v6, v210, v62
	v_fma_f32 v63, -v8, v211, v63
	v_fma_f32 v62, -v9, v212, v62
	v_fma_f32 v63, -v10, v213, v63
	ds_read_b128 v[252:255], v137 offset:33872
	s_waitcnt lgkmcnt(8)
	v_fma_f32 v62, -v11, v214, v62
	v_fma_f32 v63, -v60, v215, v63
	v_fma_f32 v62, -v61, v216, v62
	v_fma_f32 v63, -v58, v217, v63
	ds_read_b128 v[202:205], v137 offset:34048
	s_waitcnt lgkmcnt(8)
	v_fma_f32 v62, -v59, v218, v62
	v_fma_f32 v63, -v56, v219, v63
	v_fma_f32 v62, -v57, v220, v62
	v_fma_f32 v63, -v54, v221, v63
	ds_read_b128 v[206:209], v137 offset:34064
	s_waitcnt lgkmcnt(8)
	v_fma_f32 v62, -v55, v222, v62
	v_fma_f32 v63, -v52, v223, v63
	v_fma_f32 v50, -v53, v224, v62
	v_add_f32_e32 v50, v63, v50
	s_nop 0
	ds_read_b128 v[210:213], v137 offset:34080
	s_waitcnt lgkmcnt(8)
	v_fma_f32 v62, -v81, v226, v146
	v_fma_f32 v63, -v0, v227, 0
	v_fma_f32 v62, -v1, v228, v62
	v_fma_f32 v63, -v2, v229, v63
	ds_read_b128 v[214:217], v137 offset:34096
	s_waitcnt lgkmcnt(8)
	v_fma_f32 v62, -v3, v230, v62
	v_fma_f32 v63, -v4, v231, v63
	v_fma_f32 v62, -v5, v232, v62
	v_fma_f32 v63, -v7, v233, v63
	ds_read_b128 v[218:221], v137 offset:34112
	s_waitcnt lgkmcnt(8)
	v_fma_f32 v62, -v6, v234, v62
	v_fma_f32 v63, -v8, v235, v63
	v_fma_f32 v62, -v9, v236, v62
	v_fma_f32 v63, -v10, v237, v63
	ds_read_b128 v[222:225], v137 offset:34128
	s_waitcnt lgkmcnt(8)
	v_fma_f32 v62, -v11, v238, v62
	v_fma_f32 v63, -v60, v239, v63
	v_fma_f32 v62, -v61, v240, v62
	v_fma_f32 v63, -v58, v241, v63
	ds_read_b128 v[226:229], v137 offset:34144
	s_waitcnt lgkmcnt(8)
	v_fma_f32 v62, -v59, v248, v62
	v_fma_f32 v63, -v56, v249, v63
	v_fma_f32 v62, -v57, v250, v62
	v_fma_f32 v63, -v54, v251, v63
	ds_read_b128 v[230:233], v137 offset:34304
	s_waitcnt lgkmcnt(8)
	v_fma_f32 v62, -v55, v252, v62
	v_fma_f32 v63, -v52, v253, v63
	v_fma_f32 v62, -v53, v254, v62
	v_fma_f32 v51, -v50, v255, v63
	v_add_f32_e32 v51, v62, v51
	s_nop 0
	ds_read_b128 v[234:237], v137 offset:34320
	s_waitcnt lgkmcnt(8)
	v_fma_f32 v62, -v81, v202, v135
	v_fma_f32 v63, -v0, v203, 0
	v_fma_f32 v62, -v1, v204, v62
	v_fma_f32 v63, -v2, v205, v63
	ds_read_b128 v[238:241], v137 offset:34336
	s_waitcnt lgkmcnt(8)
	v_fma_f32 v62, -v3, v206, v62
	v_fma_f32 v63, -v4, v207, v63
	v_fma_f32 v62, -v5, v208, v62
	v_fma_f32 v63, -v7, v209, v63
	ds_read_b128 v[248:251], v137 offset:34352
	s_waitcnt lgkmcnt(8)
	v_fma_f32 v62, -v6, v210, v62
	v_fma_f32 v63, -v8, v211, v63
	v_fma_f32 v62, -v9, v212, v62
	v_fma_f32 v63, -v10, v213, v63
	ds_read_b128 v[252:255], v137 offset:34368
	s_waitcnt lgkmcnt(8)
	v_fma_f32 v62, -v11, v214, v62
	v_fma_f32 v63, -v60, v215, v63
	v_fma_f32 v62, -v61, v216, v62
	v_fma_f32 v63, -v58, v217, v63
	ds_read_b128 v[202:205], v137 offset:34384
	s_waitcnt lgkmcnt(8)
	v_fma_f32 v62, -v59, v218, v62
	v_fma_f32 v63, -v56, v219, v63
	v_fma_f32 v62, -v57, v220, v62
	v_fma_f32 v63, -v54, v221, v63
	ds_read_b128 v[206:209], v137 offset:34400
	s_waitcnt lgkmcnt(8)
	v_fma_f32 v62, -v55, v222, v62
	v_fma_f32 v63, -v52, v223, v63
	v_fma_f32 v62, -v53, v224, v62
	v_fma_f32 v63, -v50, v225, v63
	ds_read_b128 v[210:213], v137 offset:34560
	s_waitcnt lgkmcnt(8)
	v_fma_f32 v48, -v51, v226, v62
	v_add_f32_e32 v48, v63, v48
	s_nop 0
	ds_read_b128 v[214:217], v137 offset:34576
	s_waitcnt lgkmcnt(8)
	v_fma_f32 v62, -v81, v230, v128
	v_fma_f32 v63, -v0, v231, 0
	v_fma_f32 v62, -v1, v232, v62
	v_fma_f32 v63, -v2, v233, v63
	ds_read_b128 v[218:221], v137 offset:34592
	s_waitcnt lgkmcnt(8)
	v_fma_f32 v62, -v3, v234, v62
	v_fma_f32 v63, -v4, v235, v63
	v_fma_f32 v62, -v5, v236, v62
	v_fma_f32 v63, -v7, v237, v63
	ds_read_b128 v[222:225], v137 offset:34608
	s_waitcnt lgkmcnt(8)
	v_fma_f32 v62, -v6, v238, v62
	v_fma_f32 v63, -v8, v239, v63
	v_fma_f32 v62, -v9, v240, v62
	v_fma_f32 v63, -v10, v241, v63
	ds_read_b128 v[226:229], v137 offset:34624
	s_waitcnt lgkmcnt(8)
	v_fma_f32 v62, -v11, v248, v62
	v_fma_f32 v63, -v60, v249, v63
	v_fma_f32 v62, -v61, v250, v62
	v_fma_f32 v63, -v58, v251, v63
	ds_read_b128 v[230:233], v137 offset:34640
	s_waitcnt lgkmcnt(8)
	v_fma_f32 v62, -v59, v252, v62
	v_fma_f32 v63, -v56, v253, v63
	v_fma_f32 v62, -v57, v254, v62
	v_fma_f32 v63, -v54, v255, v63
	ds_read_b128 v[234:237], v137 offset:34656
	s_waitcnt lgkmcnt(8)
	v_fma_f32 v62, -v55, v202, v62
	v_fma_f32 v63, -v52, v203, v63
	v_fma_f32 v62, -v53, v204, v62
	v_fma_f32 v63, -v50, v205, v63
	ds_read_b128 v[238:241], v137 offset:34816
	s_waitcnt lgkmcnt(8)
	v_fma_f32 v62, -v51, v206, v62
	v_fma_f32 v49, -v48, v207, v63
	v_add_f32_e32 v49, v62, v49
	s_nop 0
	ds_read_b128 v[248:251], v137 offset:34832
	s_waitcnt lgkmcnt(8)
	v_fma_f32 v62, -v81, v210, v118
	v_fma_f32 v63, -v0, v211, 0
	v_fma_f32 v62, -v1, v212, v62
	v_fma_f32 v63, -v2, v213, v63
	ds_read_b128 v[252:255], v137 offset:34848
	s_waitcnt lgkmcnt(8)
	v_fma_f32 v62, -v3, v214, v62
	v_fma_f32 v63, -v4, v215, v63
	v_fma_f32 v62, -v5, v216, v62
	v_fma_f32 v63, -v7, v217, v63
	ds_read_b128 v[202:205], v137 offset:34864
	s_waitcnt lgkmcnt(8)
	v_fma_f32 v62, -v6, v218, v62
	v_fma_f32 v63, -v8, v219, v63
	v_fma_f32 v62, -v9, v220, v62
	v_fma_f32 v63, -v10, v221, v63
	ds_read_b128 v[206:209], v137 offset:34880
	s_waitcnt lgkmcnt(8)
	v_fma_f32 v62, -v11, v222, v62
	v_fma_f32 v63, -v60, v223, v63
	v_fma_f32 v62, -v61, v224, v62
	v_fma_f32 v63, -v58, v225, v63
	ds_read_b128 v[210:213], v137 offset:34896
	s_waitcnt lgkmcnt(8)
	v_fma_f32 v62, -v59, v226, v62
	v_fma_f32 v63, -v56, v227, v63
	v_fma_f32 v62, -v57, v228, v62
	v_fma_f32 v63, -v54, v229, v63
	ds_read_b128 v[214:217], v137 offset:34912
	s_waitcnt lgkmcnt(8)
	v_fma_f32 v62, -v55, v230, v62
	v_fma_f32 v63, -v52, v231, v63
	v_fma_f32 v62, -v53, v232, v62
	v_fma_f32 v63, -v50, v233, v63
	ds_read_b128 v[218:221], v137 offset:35072
	s_waitcnt lgkmcnt(8)
	v_fma_f32 v62, -v51, v234, v62
	v_fma_f32 v63, -v48, v235, v63
	v_fma_f32 v46, -v49, v236, v62
	v_add_f32_e32 v46, v63, v46
	s_nop 0
	ds_read_b128 v[222:225], v137 offset:35088
	s_waitcnt lgkmcnt(8)
	v_fma_f32 v62, -v81, v238, v130
	v_fma_f32 v63, -v0, v239, 0
	v_fma_f32 v62, -v1, v240, v62
	v_fma_f32 v63, -v2, v241, v63
	ds_read_b128 v[226:229], v137 offset:35104
	s_waitcnt lgkmcnt(8)
	v_fma_f32 v62, -v3, v248, v62
	v_fma_f32 v63, -v4, v249, v63
	v_fma_f32 v62, -v5, v250, v62
	v_fma_f32 v63, -v7, v251, v63
	ds_read_b128 v[230:233], v137 offset:35120
	s_waitcnt lgkmcnt(8)
	v_fma_f32 v62, -v6, v252, v62
	v_fma_f32 v63, -v8, v253, v63
	v_fma_f32 v62, -v9, v254, v62
	v_fma_f32 v63, -v10, v255, v63
	ds_read_b128 v[234:237], v137 offset:35136
	s_waitcnt lgkmcnt(8)
	v_fma_f32 v62, -v11, v202, v62
	v_fma_f32 v63, -v60, v203, v63
	v_fma_f32 v62, -v61, v204, v62
	v_fma_f32 v63, -v58, v205, v63
	ds_read_b128 v[238:241], v137 offset:35152
	s_waitcnt lgkmcnt(8)
	v_fma_f32 v62, -v59, v206, v62
	v_fma_f32 v63, -v56, v207, v63
	v_fma_f32 v62, -v57, v208, v62
	v_fma_f32 v63, -v54, v209, v63
	ds_read_b128 v[248:251], v137 offset:35168
	s_waitcnt lgkmcnt(8)
	v_fma_f32 v62, -v55, v210, v62
	v_fma_f32 v63, -v52, v211, v63
	v_fma_f32 v62, -v53, v212, v62
	v_fma_f32 v63, -v50, v213, v63
	ds_read_b128 v[252:255], v137 offset:35184
	s_waitcnt lgkmcnt(8)
	v_fma_f32 v62, -v51, v214, v62
	v_fma_f32 v63, -v48, v215, v63
	v_fma_f32 v62, -v49, v216, v62
	v_fma_f32 v47, -v46, v217, v63
	v_add_f32_e32 v47, v62, v47
	s_nop 0
	ds_read_b128 v[202:205], v137 offset:35328
	s_waitcnt lgkmcnt(8)
	v_fma_f32 v62, -v81, v218, v127
	v_fma_f32 v63, -v0, v219, 0
	v_fma_f32 v62, -v1, v220, v62
	v_fma_f32 v63, -v2, v221, v63
	ds_read_b128 v[206:209], v137 offset:35344
	s_waitcnt lgkmcnt(8)
	v_fma_f32 v62, -v3, v222, v62
	v_fma_f32 v63, -v4, v223, v63
	v_fma_f32 v62, -v5, v224, v62
	v_fma_f32 v63, -v7, v225, v63
	ds_read_b128 v[210:213], v137 offset:35360
	s_waitcnt lgkmcnt(8)
	v_fma_f32 v62, -v6, v226, v62
	v_fma_f32 v63, -v8, v227, v63
	v_fma_f32 v62, -v9, v228, v62
	v_fma_f32 v63, -v10, v229, v63
	ds_read_b128 v[214:217], v137 offset:35376
	s_waitcnt lgkmcnt(8)
	v_fma_f32 v62, -v11, v230, v62
	v_fma_f32 v63, -v60, v231, v63
	v_fma_f32 v62, -v61, v232, v62
	v_fma_f32 v63, -v58, v233, v63
	ds_read_b128 v[218:221], v137 offset:35392
	s_waitcnt lgkmcnt(8)
	v_fma_f32 v62, -v59, v234, v62
	v_fma_f32 v63, -v56, v235, v63
	v_fma_f32 v62, -v57, v236, v62
	v_fma_f32 v63, -v54, v237, v63
	ds_read_b128 v[222:225], v137 offset:35408
	s_waitcnt lgkmcnt(8)
	v_fma_f32 v62, -v55, v238, v62
	v_fma_f32 v63, -v52, v239, v63
	v_fma_f32 v62, -v53, v240, v62
	v_fma_f32 v63, -v50, v241, v63
	ds_read_b128 v[226:229], v137 offset:35424
	s_waitcnt lgkmcnt(8)
	v_fma_f32 v62, -v51, v248, v62
	v_fma_f32 v63, -v48, v249, v63
	v_fma_f32 v62, -v49, v250, v62
	v_fma_f32 v63, -v46, v251, v63
	ds_read_b128 v[230:233], v137 offset:35440
	s_waitcnt lgkmcnt(8)
	v_fma_f32 v44, -v47, v252, v62
	v_add_f32_e32 v44, v63, v44
	s_nop 0
	ds_read_b128 v[234:237], v137 offset:35584
	s_waitcnt lgkmcnt(8)
	v_fma_f32 v62, -v81, v202, v119
	v_fma_f32 v63, -v0, v203, 0
	v_fma_f32 v62, -v1, v204, v62
	v_fma_f32 v63, -v2, v205, v63
	ds_read_b128 v[238:241], v137 offset:35600
	s_waitcnt lgkmcnt(8)
	v_fma_f32 v62, -v3, v206, v62
	v_fma_f32 v63, -v4, v207, v63
	v_fma_f32 v62, -v5, v208, v62
	v_fma_f32 v63, -v7, v209, v63
	ds_read_b128 v[248:251], v137 offset:35616
	s_waitcnt lgkmcnt(8)
	v_fma_f32 v62, -v6, v210, v62
	v_fma_f32 v63, -v8, v211, v63
	v_fma_f32 v62, -v9, v212, v62
	v_fma_f32 v63, -v10, v213, v63
	ds_read_b128 v[252:255], v137 offset:35632
	s_waitcnt lgkmcnt(8)
	v_fma_f32 v62, -v11, v214, v62
	v_fma_f32 v63, -v60, v215, v63
	v_fma_f32 v62, -v61, v216, v62
	v_fma_f32 v63, -v58, v217, v63
	ds_read_b128 v[202:205], v137 offset:35648
	s_waitcnt lgkmcnt(8)
	v_fma_f32 v62, -v59, v218, v62
	v_fma_f32 v63, -v56, v219, v63
	v_fma_f32 v62, -v57, v220, v62
	v_fma_f32 v63, -v54, v221, v63
	ds_read_b128 v[206:209], v137 offset:35664
	s_waitcnt lgkmcnt(8)
	v_fma_f32 v62, -v55, v222, v62
	v_fma_f32 v63, -v52, v223, v63
	v_fma_f32 v62, -v53, v224, v62
	v_fma_f32 v63, -v50, v225, v63
	ds_read_b128 v[210:213], v137 offset:35680
	s_waitcnt lgkmcnt(8)
	v_fma_f32 v62, -v51, v226, v62
	v_fma_f32 v63, -v48, v227, v63
	v_fma_f32 v62, -v49, v228, v62
	v_fma_f32 v63, -v46, v229, v63
	ds_read_b128 v[214:217], v137 offset:35696
	s_waitcnt lgkmcnt(8)
	v_fma_f32 v62, -v47, v230, v62
	v_fma_f32 v45, -v44, v231, v63
	v_add_f32_e32 v45, v62, v45
	s_nop 0
	ds_read_b128 v[218:221], v137 offset:35840
	s_waitcnt lgkmcnt(8)
	v_fma_f32 v62, -v81, v234, v131
	v_fma_f32 v63, -v0, v235, 0
	v_fma_f32 v62, -v1, v236, v62
	v_fma_f32 v63, -v2, v237, v63
	ds_read_b128 v[222:225], v137 offset:35856
	s_waitcnt lgkmcnt(8)
	v_fma_f32 v62, -v3, v238, v62
	v_fma_f32 v63, -v4, v239, v63
	v_fma_f32 v62, -v5, v240, v62
	v_fma_f32 v63, -v7, v241, v63
	ds_read_b128 v[226:229], v137 offset:35872
	s_waitcnt lgkmcnt(8)
	v_fma_f32 v62, -v6, v248, v62
	v_fma_f32 v63, -v8, v249, v63
	v_fma_f32 v62, -v9, v250, v62
	v_fma_f32 v63, -v10, v251, v63
	ds_read_b128 v[230:233], v137 offset:35888
	s_waitcnt lgkmcnt(8)
	v_fma_f32 v62, -v11, v252, v62
	v_fma_f32 v63, -v60, v253, v63
	v_fma_f32 v62, -v61, v254, v62
	v_fma_f32 v63, -v58, v255, v63
	ds_read_b128 v[234:237], v137 offset:35904
	s_waitcnt lgkmcnt(8)
	v_fma_f32 v62, -v59, v202, v62
	v_fma_f32 v63, -v56, v203, v63
	v_fma_f32 v62, -v57, v204, v62
	v_fma_f32 v63, -v54, v205, v63
	ds_read_b128 v[238:241], v137 offset:35920
	s_waitcnt lgkmcnt(8)
	v_fma_f32 v62, -v55, v206, v62
	v_fma_f32 v63, -v52, v207, v63
	v_fma_f32 v62, -v53, v208, v62
	v_fma_f32 v63, -v50, v209, v63
	ds_read_b128 v[248:251], v137 offset:35936
	s_waitcnt lgkmcnt(8)
	v_fma_f32 v62, -v51, v210, v62
	v_fma_f32 v63, -v48, v211, v63
	v_fma_f32 v62, -v49, v212, v62
	v_fma_f32 v63, -v46, v213, v63
	ds_read_b128 v[252:255], v137 offset:35952
	s_waitcnt lgkmcnt(8)
	v_fma_f32 v62, -v47, v214, v62
	v_fma_f32 v63, -v44, v215, v63
	v_fma_f32 v42, -v45, v216, v62
	v_add_f32_e32 v42, v63, v42
	s_nop 0
	ds_read_b128 v[202:205], v137 offset:36096
	s_waitcnt lgkmcnt(8)
	v_fma_f32 v62, -v81, v218, v126
	v_fma_f32 v63, -v0, v219, 0
	v_fma_f32 v62, -v1, v220, v62
	v_fma_f32 v63, -v2, v221, v63
	ds_read_b128 v[206:209], v137 offset:36112
	s_waitcnt lgkmcnt(8)
	v_fma_f32 v62, -v3, v222, v62
	v_fma_f32 v63, -v4, v223, v63
	v_fma_f32 v62, -v5, v224, v62
	v_fma_f32 v63, -v7, v225, v63
	ds_read_b128 v[210:213], v137 offset:36128
	s_waitcnt lgkmcnt(8)
	v_fma_f32 v62, -v6, v226, v62
	v_fma_f32 v63, -v8, v227, v63
	v_fma_f32 v62, -v9, v228, v62
	v_fma_f32 v63, -v10, v229, v63
	ds_read_b128 v[214:217], v137 offset:36144
	s_waitcnt lgkmcnt(8)
	v_fma_f32 v62, -v11, v230, v62
	v_fma_f32 v63, -v60, v231, v63
	v_fma_f32 v62, -v61, v232, v62
	v_fma_f32 v63, -v58, v233, v63
	ds_read_b128 v[218:221], v137 offset:36160
	s_waitcnt lgkmcnt(8)
	v_fma_f32 v62, -v59, v234, v62
	v_fma_f32 v63, -v56, v235, v63
	v_fma_f32 v62, -v57, v236, v62
	v_fma_f32 v63, -v54, v237, v63
	ds_read_b128 v[222:225], v137 offset:36176
	s_waitcnt lgkmcnt(8)
	v_fma_f32 v62, -v55, v238, v62
	v_fma_f32 v63, -v52, v239, v63
	v_fma_f32 v62, -v53, v240, v62
	v_fma_f32 v63, -v50, v241, v63
	ds_read_b128 v[226:229], v137 offset:36192
	s_waitcnt lgkmcnt(8)
	v_fma_f32 v62, -v51, v248, v62
	v_fma_f32 v63, -v48, v249, v63
	v_fma_f32 v62, -v49, v250, v62
	v_fma_f32 v63, -v46, v251, v63
	ds_read_b128 v[230:233], v137 offset:36208
	s_waitcnt lgkmcnt(8)
	v_fma_f32 v62, -v47, v252, v62
	v_fma_f32 v63, -v44, v253, v63
	v_fma_f32 v62, -v45, v254, v62
	v_fma_f32 v43, -v42, v255, v63
	v_add_f32_e32 v43, v62, v43
	s_nop 0
	ds_read_b128 v[234:237], v137 offset:36224
	s_waitcnt lgkmcnt(8)
	v_fma_f32 v62, -v81, v202, v115
	v_fma_f32 v63, -v0, v203, 0
	v_fma_f32 v62, -v1, v204, v62
	v_fma_f32 v63, -v2, v205, v63
	ds_read_b128 v[238:241], v137 offset:36352
	s_waitcnt lgkmcnt(8)
	v_fma_f32 v62, -v3, v206, v62
	v_fma_f32 v63, -v4, v207, v63
	v_fma_f32 v62, -v5, v208, v62
	v_fma_f32 v63, -v7, v209, v63
	ds_read_b128 v[248:251], v137 offset:36368
	s_waitcnt lgkmcnt(8)
	v_fma_f32 v62, -v6, v210, v62
	v_fma_f32 v63, -v8, v211, v63
	v_fma_f32 v62, -v9, v212, v62
	v_fma_f32 v63, -v10, v213, v63
	ds_read_b128 v[252:255], v137 offset:36384
	s_waitcnt lgkmcnt(8)
	v_fma_f32 v62, -v11, v214, v62
	v_fma_f32 v63, -v60, v215, v63
	v_fma_f32 v62, -v61, v216, v62
	v_fma_f32 v63, -v58, v217, v63
	ds_read_b128 v[202:205], v137 offset:36400
	s_waitcnt lgkmcnt(8)
	v_fma_f32 v62, -v59, v218, v62
	v_fma_f32 v63, -v56, v219, v63
	v_fma_f32 v62, -v57, v220, v62
	v_fma_f32 v63, -v54, v221, v63
	ds_read_b128 v[206:209], v137 offset:36416
	s_waitcnt lgkmcnt(8)
	v_fma_f32 v62, -v55, v222, v62
	v_fma_f32 v63, -v52, v223, v63
	v_fma_f32 v62, -v53, v224, v62
	v_fma_f32 v63, -v50, v225, v63
	ds_read_b128 v[210:213], v137 offset:36432
	s_waitcnt lgkmcnt(8)
	v_fma_f32 v62, -v51, v226, v62
	v_fma_f32 v63, -v48, v227, v63
	v_fma_f32 v62, -v49, v228, v62
	v_fma_f32 v63, -v46, v229, v63
	ds_read_b128 v[214:217], v137 offset:36448
	s_waitcnt lgkmcnt(8)
	v_fma_f32 v62, -v47, v230, v62
	v_fma_f32 v63, -v44, v231, v63
	v_fma_f32 v62, -v45, v232, v62
	v_fma_f32 v63, -v42, v233, v63
	ds_read_b128 v[218:221], v137 offset:36464
	s_waitcnt lgkmcnt(8)
	v_fma_f32 v40, -v43, v234, v62
	v_add_f32_e32 v40, v63, v40
	s_nop 0
	ds_read_b128 v[222:225], v137 offset:36480
	s_waitcnt lgkmcnt(8)
	v_fma_f32 v62, -v81, v238, v114
	v_fma_f32 v63, -v0, v239, 0
	v_fma_f32 v62, -v1, v240, v62
	v_fma_f32 v63, -v2, v241, v63
	ds_read_b128 v[226:229], v137 offset:36608
	s_waitcnt lgkmcnt(8)
	v_fma_f32 v62, -v3, v248, v62
	v_fma_f32 v63, -v4, v249, v63
	v_fma_f32 v62, -v5, v250, v62
	v_fma_f32 v63, -v7, v251, v63
	ds_read_b128 v[230:233], v137 offset:36624
	s_waitcnt lgkmcnt(8)
	v_fma_f32 v62, -v6, v252, v62
	v_fma_f32 v63, -v8, v253, v63
	v_fma_f32 v62, -v9, v254, v62
	v_fma_f32 v63, -v10, v255, v63
	ds_read_b128 v[234:237], v137 offset:36640
	s_waitcnt lgkmcnt(8)
	v_fma_f32 v62, -v11, v202, v62
	v_fma_f32 v63, -v60, v203, v63
	v_fma_f32 v62, -v61, v204, v62
	v_fma_f32 v63, -v58, v205, v63
	ds_read_b128 v[238:241], v137 offset:36656
	s_waitcnt lgkmcnt(8)
	v_fma_f32 v62, -v59, v206, v62
	v_fma_f32 v63, -v56, v207, v63
	v_fma_f32 v62, -v57, v208, v62
	v_fma_f32 v63, -v54, v209, v63
	ds_read_b128 v[248:251], v137 offset:36672
	s_waitcnt lgkmcnt(8)
	v_fma_f32 v62, -v55, v210, v62
	v_fma_f32 v63, -v52, v211, v63
	v_fma_f32 v62, -v53, v212, v62
	v_fma_f32 v63, -v50, v213, v63
	ds_read_b128 v[252:255], v137 offset:36688
	s_waitcnt lgkmcnt(8)
	v_fma_f32 v62, -v51, v214, v62
	v_fma_f32 v63, -v48, v215, v63
	v_fma_f32 v62, -v49, v216, v62
	v_fma_f32 v63, -v46, v217, v63
	ds_read_b128 v[202:205], v137 offset:36704
	s_waitcnt lgkmcnt(8)
	v_fma_f32 v62, -v47, v218, v62
	v_fma_f32 v63, -v44, v219, v63
	v_fma_f32 v62, -v45, v220, v62
	v_fma_f32 v63, -v42, v221, v63
	ds_read_b128 v[206:209], v137 offset:36720
	s_waitcnt lgkmcnt(8)
	v_fma_f32 v62, -v43, v222, v62
	v_fma_f32 v41, -v40, v223, v63
	v_add_f32_e32 v41, v62, v41
	s_nop 0
	ds_read_b128 v[210:213], v137 offset:36736
	s_waitcnt lgkmcnt(8)
	v_fma_f32 v62, -v81, v226, v111
	v_fma_f32 v63, -v0, v227, 0
	v_fma_f32 v62, -v1, v228, v62
	v_fma_f32 v63, -v2, v229, v63
	ds_read_b128 v[214:217], v137 offset:36864
	s_waitcnt lgkmcnt(8)
	v_fma_f32 v62, -v3, v230, v62
	v_fma_f32 v63, -v4, v231, v63
	v_fma_f32 v62, -v5, v232, v62
	v_fma_f32 v63, -v7, v233, v63
	ds_read_b128 v[218:221], v137 offset:36880
	s_waitcnt lgkmcnt(8)
	v_fma_f32 v62, -v6, v234, v62
	v_fma_f32 v63, -v8, v235, v63
	v_fma_f32 v62, -v9, v236, v62
	v_fma_f32 v63, -v10, v237, v63
	ds_read_b128 v[222:225], v137 offset:36896
	s_waitcnt lgkmcnt(8)
	v_fma_f32 v62, -v11, v238, v62
	v_fma_f32 v63, -v60, v239, v63
	v_fma_f32 v62, -v61, v240, v62
	v_fma_f32 v63, -v58, v241, v63
	ds_read_b128 v[226:229], v137 offset:36912
	s_waitcnt lgkmcnt(8)
	v_fma_f32 v62, -v59, v248, v62
	v_fma_f32 v63, -v56, v249, v63
	v_fma_f32 v62, -v57, v250, v62
	v_fma_f32 v63, -v54, v251, v63
	ds_read_b128 v[230:233], v137 offset:36928
	s_waitcnt lgkmcnt(8)
	v_fma_f32 v62, -v55, v252, v62
	v_fma_f32 v63, -v52, v253, v63
	v_fma_f32 v62, -v53, v254, v62
	v_fma_f32 v63, -v50, v255, v63
	ds_read_b128 v[234:237], v137 offset:36944
	s_waitcnt lgkmcnt(8)
	v_fma_f32 v62, -v51, v202, v62
	v_fma_f32 v63, -v48, v203, v63
	v_fma_f32 v62, -v49, v204, v62
	v_fma_f32 v63, -v46, v205, v63
	ds_read_b128 v[238:241], v137 offset:36960
	s_waitcnt lgkmcnt(8)
	v_fma_f32 v62, -v47, v206, v62
	v_fma_f32 v63, -v44, v207, v63
	v_fma_f32 v62, -v45, v208, v62
	v_fma_f32 v63, -v42, v209, v63
	ds_read_b128 v[248:251], v137 offset:36976
	s_waitcnt lgkmcnt(8)
	v_fma_f32 v62, -v43, v210, v62
	v_fma_f32 v63, -v40, v211, v63
	v_fma_f32 v38, -v41, v212, v62
	v_add_f32_e32 v38, v63, v38
	s_nop 0
	ds_read_b128 v[252:255], v137 offset:36992
	s_waitcnt lgkmcnt(8)
	v_fma_f32 v62, -v81, v214, v113
	v_fma_f32 v63, -v0, v215, 0
	v_fma_f32 v62, -v1, v216, v62
	v_fma_f32 v63, -v2, v217, v63
	ds_read_b128 v[202:205], v137 offset:37120
	s_waitcnt lgkmcnt(8)
	v_fma_f32 v62, -v3, v218, v62
	v_fma_f32 v63, -v4, v219, v63
	v_fma_f32 v62, -v5, v220, v62
	v_fma_f32 v63, -v7, v221, v63
	ds_read_b128 v[206:209], v137 offset:37136
	s_waitcnt lgkmcnt(8)
	v_fma_f32 v62, -v6, v222, v62
	v_fma_f32 v63, -v8, v223, v63
	v_fma_f32 v62, -v9, v224, v62
	v_fma_f32 v63, -v10, v225, v63
	ds_read_b128 v[210:213], v137 offset:37152
	s_waitcnt lgkmcnt(8)
	v_fma_f32 v62, -v11, v226, v62
	v_fma_f32 v63, -v60, v227, v63
	v_fma_f32 v62, -v61, v228, v62
	v_fma_f32 v63, -v58, v229, v63
	ds_read_b128 v[214:217], v137 offset:37168
	s_waitcnt lgkmcnt(8)
	v_fma_f32 v62, -v59, v230, v62
	v_fma_f32 v63, -v56, v231, v63
	v_fma_f32 v62, -v57, v232, v62
	v_fma_f32 v63, -v54, v233, v63
	ds_read_b128 v[218:221], v137 offset:37184
	s_waitcnt lgkmcnt(8)
	v_fma_f32 v62, -v55, v234, v62
	v_fma_f32 v63, -v52, v235, v63
	v_fma_f32 v62, -v53, v236, v62
	v_fma_f32 v63, -v50, v237, v63
	ds_read_b128 v[222:225], v137 offset:37200
	s_waitcnt lgkmcnt(8)
	v_fma_f32 v62, -v51, v238, v62
	v_fma_f32 v63, -v48, v239, v63
	v_fma_f32 v62, -v49, v240, v62
	v_fma_f32 v63, -v46, v241, v63
	ds_read_b128 v[226:229], v137 offset:37216
	s_waitcnt lgkmcnt(8)
	v_fma_f32 v62, -v47, v248, v62
	v_fma_f32 v63, -v44, v249, v63
	v_fma_f32 v62, -v45, v250, v62
	v_fma_f32 v63, -v42, v251, v63
	ds_read_b128 v[230:233], v137 offset:37232
	s_waitcnt lgkmcnt(8)
	v_fma_f32 v62, -v43, v252, v62
	v_fma_f32 v63, -v40, v253, v63
	v_fma_f32 v62, -v41, v254, v62
	v_fma_f32 v39, -v38, v255, v63
	v_add_f32_e32 v39, v62, v39
	s_nop 0
	ds_read_b128 v[234:237], v137 offset:37248
	s_waitcnt lgkmcnt(8)
	v_fma_f32 v62, -v81, v202, v112
	v_fma_f32 v63, -v0, v203, 0
	v_fma_f32 v62, -v1, v204, v62
	v_fma_f32 v63, -v2, v205, v63
	ds_read_b128 v[238:241], v137 offset:37264
	s_waitcnt lgkmcnt(8)
	v_fma_f32 v62, -v3, v206, v62
	v_fma_f32 v63, -v4, v207, v63
	v_fma_f32 v62, -v5, v208, v62
	v_fma_f32 v63, -v7, v209, v63
	ds_read_b128 v[248:251], v137 offset:37376
	s_waitcnt lgkmcnt(8)
	v_fma_f32 v62, -v6, v210, v62
	v_fma_f32 v63, -v8, v211, v63
	v_fma_f32 v62, -v9, v212, v62
	v_fma_f32 v63, -v10, v213, v63
	ds_read_b128 v[252:255], v137 offset:37392
	s_waitcnt lgkmcnt(8)
	v_fma_f32 v62, -v11, v214, v62
	v_fma_f32 v63, -v60, v215, v63
	v_fma_f32 v62, -v61, v216, v62
	v_fma_f32 v63, -v58, v217, v63
	ds_read_b128 v[202:205], v137 offset:37408
	s_waitcnt lgkmcnt(8)
	v_fma_f32 v62, -v59, v218, v62
	v_fma_f32 v63, -v56, v219, v63
	v_fma_f32 v62, -v57, v220, v62
	v_fma_f32 v63, -v54, v221, v63
	ds_read_b128 v[206:209], v137 offset:37424
	s_waitcnt lgkmcnt(8)
	v_fma_f32 v62, -v55, v222, v62
	v_fma_f32 v63, -v52, v223, v63
	v_fma_f32 v62, -v53, v224, v62
	v_fma_f32 v63, -v50, v225, v63
	ds_read_b128 v[210:213], v137 offset:37440
	s_waitcnt lgkmcnt(8)
	v_fma_f32 v62, -v51, v226, v62
	v_fma_f32 v63, -v48, v227, v63
	v_fma_f32 v62, -v49, v228, v62
	v_fma_f32 v63, -v46, v229, v63
	ds_read_b128 v[214:217], v137 offset:37456
	s_waitcnt lgkmcnt(8)
	v_fma_f32 v62, -v47, v230, v62
	v_fma_f32 v63, -v44, v231, v63
	v_fma_f32 v62, -v45, v232, v62
	v_fma_f32 v63, -v42, v233, v63
	ds_read_b128 v[218:221], v137 offset:37472
	s_waitcnt lgkmcnt(8)
	v_fma_f32 v62, -v43, v234, v62
	v_fma_f32 v63, -v40, v235, v63
	v_fma_f32 v62, -v41, v236, v62
	v_fma_f32 v63, -v38, v237, v63
	ds_read_b128 v[222:225], v137 offset:37488
	s_waitcnt lgkmcnt(8)
	v_fma_f32 v36, -v39, v238, v62
	v_add_f32_e32 v36, v63, v36
	s_nop 0
	ds_read_b128 v[226:229], v137 offset:37504
	s_waitcnt lgkmcnt(8)
	v_fma_f32 v62, -v81, v248, v108
	v_fma_f32 v63, -v0, v249, 0
	v_fma_f32 v62, -v1, v250, v62
	v_fma_f32 v63, -v2, v251, v63
	ds_read_b128 v[230:233], v137 offset:37520
	s_waitcnt lgkmcnt(8)
	v_fma_f32 v62, -v3, v252, v62
	v_fma_f32 v63, -v4, v253, v63
	v_fma_f32 v62, -v5, v254, v62
	v_fma_f32 v63, -v7, v255, v63
	ds_read_b128 v[234:237], v137 offset:37632
	s_waitcnt lgkmcnt(8)
	v_fma_f32 v62, -v6, v202, v62
	v_fma_f32 v63, -v8, v203, v63
	v_fma_f32 v62, -v9, v204, v62
	v_fma_f32 v63, -v10, v205, v63
	ds_read_b128 v[238:241], v137 offset:37648
	s_waitcnt lgkmcnt(8)
	v_fma_f32 v62, -v11, v206, v62
	v_fma_f32 v63, -v60, v207, v63
	v_fma_f32 v62, -v61, v208, v62
	v_fma_f32 v63, -v58, v209, v63
	ds_read_b128 v[248:251], v137 offset:37664
	s_waitcnt lgkmcnt(8)
	v_fma_f32 v62, -v59, v210, v62
	v_fma_f32 v63, -v56, v211, v63
	v_fma_f32 v62, -v57, v212, v62
	v_fma_f32 v63, -v54, v213, v63
	ds_read_b128 v[252:255], v137 offset:37680
	s_waitcnt lgkmcnt(8)
	v_fma_f32 v62, -v55, v214, v62
	v_fma_f32 v63, -v52, v215, v63
	v_fma_f32 v62, -v53, v216, v62
	v_fma_f32 v63, -v50, v217, v63
	ds_read_b128 v[202:205], v137 offset:37696
	s_waitcnt lgkmcnt(8)
	v_fma_f32 v62, -v51, v218, v62
	v_fma_f32 v63, -v48, v219, v63
	v_fma_f32 v62, -v49, v220, v62
	v_fma_f32 v63, -v46, v221, v63
	ds_read_b128 v[206:209], v137 offset:37712
	s_waitcnt lgkmcnt(8)
	v_fma_f32 v62, -v47, v222, v62
	v_fma_f32 v63, -v44, v223, v63
	v_fma_f32 v62, -v45, v224, v62
	v_fma_f32 v63, -v42, v225, v63
	ds_read_b128 v[210:213], v137 offset:37728
	s_waitcnt lgkmcnt(8)
	v_fma_f32 v62, -v43, v226, v62
	v_fma_f32 v63, -v40, v227, v63
	v_fma_f32 v62, -v41, v228, v62
	v_fma_f32 v63, -v38, v229, v63
	ds_read_b128 v[214:217], v137 offset:37744
	s_waitcnt lgkmcnt(8)
	v_fma_f32 v62, -v39, v230, v62
	v_fma_f32 v37, -v36, v231, v63
	v_add_f32_e32 v37, v62, v37
	s_nop 0
	ds_read_b128 v[218:221], v137 offset:37760
	s_waitcnt lgkmcnt(8)
	v_fma_f32 v62, -v81, v234, v110
	v_fma_f32 v63, -v0, v235, 0
	v_fma_f32 v62, -v1, v236, v62
	v_fma_f32 v63, -v2, v237, v63
	ds_read_b128 v[222:225], v137 offset:37776
	s_waitcnt lgkmcnt(8)
	v_fma_f32 v62, -v3, v238, v62
	v_fma_f32 v63, -v4, v239, v63
	v_fma_f32 v62, -v5, v240, v62
	v_fma_f32 v63, -v7, v241, v63
	ds_read_b128 v[226:229], v137 offset:37888
	s_waitcnt lgkmcnt(8)
	v_fma_f32 v62, -v6, v248, v62
	v_fma_f32 v63, -v8, v249, v63
	v_fma_f32 v62, -v9, v250, v62
	v_fma_f32 v63, -v10, v251, v63
	ds_read_b128 v[230:233], v137 offset:37904
	s_waitcnt lgkmcnt(8)
	v_fma_f32 v62, -v11, v252, v62
	v_fma_f32 v63, -v60, v253, v63
	v_fma_f32 v62, -v61, v254, v62
	v_fma_f32 v63, -v58, v255, v63
	ds_read_b128 v[234:237], v137 offset:37920
	s_waitcnt lgkmcnt(8)
	v_fma_f32 v62, -v59, v202, v62
	v_fma_f32 v63, -v56, v203, v63
	v_fma_f32 v62, -v57, v204, v62
	v_fma_f32 v63, -v54, v205, v63
	ds_read_b128 v[238:241], v137 offset:37936
	s_waitcnt lgkmcnt(8)
	v_fma_f32 v62, -v55, v206, v62
	v_fma_f32 v63, -v52, v207, v63
	v_fma_f32 v62, -v53, v208, v62
	v_fma_f32 v63, -v50, v209, v63
	ds_read_b128 v[248:251], v137 offset:37952
	s_waitcnt lgkmcnt(8)
	v_fma_f32 v62, -v51, v210, v62
	v_fma_f32 v63, -v48, v211, v63
	v_fma_f32 v62, -v49, v212, v62
	v_fma_f32 v63, -v46, v213, v63
	ds_read_b128 v[252:255], v137 offset:37968
	s_waitcnt lgkmcnt(8)
	v_fma_f32 v62, -v47, v214, v62
	v_fma_f32 v63, -v44, v215, v63
	v_fma_f32 v62, -v45, v216, v62
	v_fma_f32 v63, -v42, v217, v63
	ds_read_b128 v[202:205], v137 offset:37984
	s_waitcnt lgkmcnt(8)
	v_fma_f32 v62, -v43, v218, v62
	v_fma_f32 v63, -v40, v219, v63
	v_fma_f32 v62, -v41, v220, v62
	v_fma_f32 v63, -v38, v221, v63
	ds_read_b128 v[206:209], v137 offset:38000
	s_waitcnt lgkmcnt(8)
	v_fma_f32 v62, -v39, v222, v62
	v_fma_f32 v63, -v36, v223, v63
	v_fma_f32 v34, -v37, v224, v62
	v_add_f32_e32 v34, v63, v34
	s_nop 0
	ds_read_b128 v[210:213], v137 offset:38016
	s_waitcnt lgkmcnt(8)
	v_fma_f32 v62, -v81, v226, v107
	v_fma_f32 v63, -v0, v227, 0
	v_fma_f32 v62, -v1, v228, v62
	v_fma_f32 v63, -v2, v229, v63
	ds_read_b128 v[214:217], v137 offset:38032
	s_waitcnt lgkmcnt(8)
	v_fma_f32 v62, -v3, v230, v62
	v_fma_f32 v63, -v4, v231, v63
	v_fma_f32 v62, -v5, v232, v62
	v_fma_f32 v63, -v7, v233, v63
	ds_read_b128 v[218:221], v137 offset:38144
	s_waitcnt lgkmcnt(8)
	v_fma_f32 v62, -v6, v234, v62
	v_fma_f32 v63, -v8, v235, v63
	v_fma_f32 v62, -v9, v236, v62
	v_fma_f32 v63, -v10, v237, v63
	ds_read_b128 v[222:225], v137 offset:38160
	s_waitcnt lgkmcnt(8)
	v_fma_f32 v62, -v11, v238, v62
	v_fma_f32 v63, -v60, v239, v63
	v_fma_f32 v62, -v61, v240, v62
	v_fma_f32 v63, -v58, v241, v63
	ds_read_b128 v[226:229], v137 offset:38176
	s_waitcnt lgkmcnt(8)
	v_fma_f32 v62, -v59, v248, v62
	v_fma_f32 v63, -v56, v249, v63
	v_fma_f32 v62, -v57, v250, v62
	v_fma_f32 v63, -v54, v251, v63
	ds_read_b128 v[230:233], v137 offset:38192
	s_waitcnt lgkmcnt(8)
	v_fma_f32 v62, -v55, v252, v62
	v_fma_f32 v63, -v52, v253, v63
	v_fma_f32 v62, -v53, v254, v62
	v_fma_f32 v63, -v50, v255, v63
	ds_read_b128 v[234:237], v137 offset:38208
	s_waitcnt lgkmcnt(8)
	v_fma_f32 v62, -v51, v202, v62
	v_fma_f32 v63, -v48, v203, v63
	v_fma_f32 v62, -v49, v204, v62
	v_fma_f32 v63, -v46, v205, v63
	ds_read_b128 v[238:241], v137 offset:38224
	s_waitcnt lgkmcnt(8)
	v_fma_f32 v62, -v47, v206, v62
	v_fma_f32 v63, -v44, v207, v63
	v_fma_f32 v62, -v45, v208, v62
	v_fma_f32 v63, -v42, v209, v63
	ds_read_b128 v[248:251], v137 offset:38240
	s_waitcnt lgkmcnt(8)
	v_fma_f32 v62, -v43, v210, v62
	v_fma_f32 v63, -v40, v211, v63
	v_fma_f32 v62, -v41, v212, v62
	v_fma_f32 v63, -v38, v213, v63
	ds_read_b128 v[252:255], v137 offset:38256
	s_waitcnt lgkmcnt(8)
	v_fma_f32 v62, -v39, v214, v62
	v_fma_f32 v63, -v36, v215, v63
	v_fma_f32 v62, -v37, v216, v62
	v_fma_f32 v35, -v34, v217, v63
	v_add_f32_e32 v35, v62, v35
	s_nop 0
	ds_read_b128 v[202:205], v137 offset:38272
	s_waitcnt lgkmcnt(8)
	v_fma_f32 v62, -v81, v218, v104
	v_fma_f32 v63, -v0, v219, 0
	v_fma_f32 v62, -v1, v220, v62
	v_fma_f32 v63, -v2, v221, v63
	ds_read_b128 v[206:209], v137 offset:38288
	s_waitcnt lgkmcnt(8)
	v_fma_f32 v62, -v3, v222, v62
	v_fma_f32 v63, -v4, v223, v63
	v_fma_f32 v62, -v5, v224, v62
	v_fma_f32 v63, -v7, v225, v63
	ds_read_b128 v[210:213], v137 offset:38304
	s_waitcnt lgkmcnt(8)
	v_fma_f32 v62, -v6, v226, v62
	v_fma_f32 v63, -v8, v227, v63
	v_fma_f32 v62, -v9, v228, v62
	v_fma_f32 v63, -v10, v229, v63
	ds_read_b128 v[214:217], v137 offset:38400
	s_waitcnt lgkmcnt(8)
	v_fma_f32 v62, -v11, v230, v62
	v_fma_f32 v63, -v60, v231, v63
	v_fma_f32 v62, -v61, v232, v62
	v_fma_f32 v63, -v58, v233, v63
	ds_read_b128 v[218:221], v137 offset:38416
	s_waitcnt lgkmcnt(8)
	v_fma_f32 v62, -v59, v234, v62
	v_fma_f32 v63, -v56, v235, v63
	v_fma_f32 v62, -v57, v236, v62
	v_fma_f32 v63, -v54, v237, v63
	ds_read_b128 v[222:225], v137 offset:38432
	s_waitcnt lgkmcnt(8)
	v_fma_f32 v62, -v55, v238, v62
	v_fma_f32 v63, -v52, v239, v63
	v_fma_f32 v62, -v53, v240, v62
	v_fma_f32 v63, -v50, v241, v63
	ds_read_b128 v[226:229], v137 offset:38448
	s_waitcnt lgkmcnt(8)
	v_fma_f32 v62, -v51, v248, v62
	v_fma_f32 v63, -v48, v249, v63
	v_fma_f32 v62, -v49, v250, v62
	v_fma_f32 v63, -v46, v251, v63
	ds_read_b128 v[230:233], v137 offset:38464
	s_waitcnt lgkmcnt(8)
	v_fma_f32 v62, -v47, v252, v62
	v_fma_f32 v63, -v44, v253, v63
	v_fma_f32 v62, -v45, v254, v62
	v_fma_f32 v63, -v42, v255, v63
	ds_read_b128 v[234:237], v137 offset:38480
	s_waitcnt lgkmcnt(8)
	v_fma_f32 v62, -v43, v202, v62
	v_fma_f32 v63, -v40, v203, v63
	v_fma_f32 v62, -v41, v204, v62
	v_fma_f32 v63, -v38, v205, v63
	ds_read_b128 v[238:241], v137 offset:38496
	s_waitcnt lgkmcnt(8)
	v_fma_f32 v62, -v39, v206, v62
	v_fma_f32 v63, -v36, v207, v63
	v_fma_f32 v62, -v37, v208, v62
	v_fma_f32 v63, -v34, v209, v63
	ds_read_b128 v[248:251], v137 offset:38512
	s_waitcnt lgkmcnt(8)
	v_fma_f32 v32, -v35, v210, v62
	v_add_f32_e32 v32, v63, v32
	s_nop 0
	ds_read_b128 v[252:255], v137 offset:38528
	s_waitcnt lgkmcnt(8)
	v_fma_f32 v62, -v81, v214, v103
	v_fma_f32 v63, -v0, v215, 0
	v_fma_f32 v62, -v1, v216, v62
	v_fma_f32 v63, -v2, v217, v63
	ds_read_b128 v[202:205], v137 offset:38544
	s_waitcnt lgkmcnt(8)
	v_fma_f32 v62, -v3, v218, v62
	v_fma_f32 v63, -v4, v219, v63
	v_fma_f32 v62, -v5, v220, v62
	v_fma_f32 v63, -v7, v221, v63
	ds_read_b128 v[206:209], v137 offset:38560
	s_waitcnt lgkmcnt(8)
	v_fma_f32 v62, -v6, v222, v62
	v_fma_f32 v63, -v8, v223, v63
	v_fma_f32 v62, -v9, v224, v62
	v_fma_f32 v63, -v10, v225, v63
	ds_read_b128 v[210:213], v137 offset:38656
	s_waitcnt lgkmcnt(8)
	v_fma_f32 v62, -v11, v226, v62
	v_fma_f32 v63, -v60, v227, v63
	v_fma_f32 v62, -v61, v228, v62
	v_fma_f32 v63, -v58, v229, v63
	ds_read_b128 v[214:217], v137 offset:38672
	s_waitcnt lgkmcnt(8)
	v_fma_f32 v62, -v59, v230, v62
	v_fma_f32 v63, -v56, v231, v63
	v_fma_f32 v62, -v57, v232, v62
	v_fma_f32 v63, -v54, v233, v63
	ds_read_b128 v[218:221], v137 offset:38688
	s_waitcnt lgkmcnt(8)
	v_fma_f32 v62, -v55, v234, v62
	v_fma_f32 v63, -v52, v235, v63
	v_fma_f32 v62, -v53, v236, v62
	v_fma_f32 v63, -v50, v237, v63
	ds_read_b128 v[222:225], v137 offset:38704
	s_waitcnt lgkmcnt(8)
	v_fma_f32 v62, -v51, v238, v62
	v_fma_f32 v63, -v48, v239, v63
	v_fma_f32 v62, -v49, v240, v62
	v_fma_f32 v63, -v46, v241, v63
	ds_read_b128 v[226:229], v137 offset:38720
	s_waitcnt lgkmcnt(8)
	v_fma_f32 v62, -v47, v248, v62
	v_fma_f32 v63, -v44, v249, v63
	v_fma_f32 v62, -v45, v250, v62
	v_fma_f32 v63, -v42, v251, v63
	ds_read_b128 v[230:233], v137 offset:38736
	s_waitcnt lgkmcnt(8)
	v_fma_f32 v62, -v43, v252, v62
	v_fma_f32 v63, -v40, v253, v63
	v_fma_f32 v62, -v41, v254, v62
	v_fma_f32 v63, -v38, v255, v63
	ds_read_b128 v[234:237], v137 offset:38752
	s_waitcnt lgkmcnt(8)
	v_fma_f32 v62, -v39, v202, v62
	v_fma_f32 v63, -v36, v203, v63
	v_fma_f32 v62, -v37, v204, v62
	v_fma_f32 v63, -v34, v205, v63
	ds_read_b128 v[238:241], v137 offset:38768
	s_waitcnt lgkmcnt(8)
	v_fma_f32 v62, -v35, v206, v62
	v_fma_f32 v33, -v32, v207, v63
	v_add_f32_e32 v33, v62, v33
	s_nop 0
	ds_read_b128 v[248:251], v137 offset:38784
	s_waitcnt lgkmcnt(8)
	v_fma_f32 v62, -v81, v210, v101
	v_fma_f32 v63, -v0, v211, 0
	v_fma_f32 v62, -v1, v212, v62
	v_fma_f32 v63, -v2, v213, v63
	ds_read_b128 v[252:255], v137 offset:38800
	s_waitcnt lgkmcnt(8)
	v_fma_f32 v62, -v3, v214, v62
	v_fma_f32 v63, -v4, v215, v63
	v_fma_f32 v62, -v5, v216, v62
	v_fma_f32 v63, -v7, v217, v63
	ds_read_b128 v[202:205], v137 offset:38816
	s_waitcnt lgkmcnt(8)
	v_fma_f32 v62, -v6, v218, v62
	v_fma_f32 v63, -v8, v219, v63
	v_fma_f32 v62, -v9, v220, v62
	v_fma_f32 v63, -v10, v221, v63
	ds_read_b128 v[206:209], v137 offset:38912
	s_waitcnt lgkmcnt(8)
	v_fma_f32 v62, -v11, v222, v62
	v_fma_f32 v63, -v60, v223, v63
	v_fma_f32 v62, -v61, v224, v62
	v_fma_f32 v63, -v58, v225, v63
	ds_read_b128 v[210:213], v137 offset:38928
	s_waitcnt lgkmcnt(8)
	v_fma_f32 v62, -v59, v226, v62
	v_fma_f32 v63, -v56, v227, v63
	v_fma_f32 v62, -v57, v228, v62
	v_fma_f32 v63, -v54, v229, v63
	ds_read_b128 v[214:217], v137 offset:38944
	s_waitcnt lgkmcnt(8)
	v_fma_f32 v62, -v55, v230, v62
	v_fma_f32 v63, -v52, v231, v63
	v_fma_f32 v62, -v53, v232, v62
	v_fma_f32 v63, -v50, v233, v63
	ds_read_b128 v[218:221], v137 offset:38960
	s_waitcnt lgkmcnt(8)
	v_fma_f32 v62, -v51, v234, v62
	v_fma_f32 v63, -v48, v235, v63
	v_fma_f32 v62, -v49, v236, v62
	v_fma_f32 v63, -v46, v237, v63
	ds_read_b128 v[222:225], v137 offset:38976
	s_waitcnt lgkmcnt(8)
	v_fma_f32 v62, -v47, v238, v62
	v_fma_f32 v63, -v44, v239, v63
	v_fma_f32 v62, -v45, v240, v62
	v_fma_f32 v63, -v42, v241, v63
	ds_read_b128 v[226:229], v137 offset:38992
	s_waitcnt lgkmcnt(8)
	v_fma_f32 v62, -v43, v248, v62
	v_fma_f32 v63, -v40, v249, v63
	v_fma_f32 v62, -v41, v250, v62
	v_fma_f32 v63, -v38, v251, v63
	ds_read_b128 v[230:233], v137 offset:39008
	s_waitcnt lgkmcnt(8)
	v_fma_f32 v62, -v39, v252, v62
	v_fma_f32 v63, -v36, v253, v63
	v_fma_f32 v62, -v37, v254, v62
	v_fma_f32 v63, -v34, v255, v63
	ds_read_b128 v[234:237], v137 offset:39024
	s_waitcnt lgkmcnt(8)
	v_fma_f32 v62, -v35, v202, v62
	v_fma_f32 v63, -v32, v203, v63
	v_fma_f32 v30, -v33, v204, v62
	v_add_f32_e32 v30, v63, v30
	s_nop 0
	ds_read_b128 v[238:241], v137 offset:39040
	s_waitcnt lgkmcnt(8)
	v_fma_f32 v62, -v81, v206, v102
	v_fma_f32 v63, -v0, v207, 0
	v_fma_f32 v62, -v1, v208, v62
	v_fma_f32 v63, -v2, v209, v63
	ds_read_b128 v[248:251], v137 offset:39056
	s_waitcnt lgkmcnt(8)
	v_fma_f32 v62, -v3, v210, v62
	v_fma_f32 v63, -v4, v211, v63
	v_fma_f32 v62, -v5, v212, v62
	v_fma_f32 v63, -v7, v213, v63
	ds_read_b128 v[252:255], v137 offset:39072
	s_waitcnt lgkmcnt(8)
	v_fma_f32 v62, -v6, v214, v62
	v_fma_f32 v63, -v8, v215, v63
	v_fma_f32 v62, -v9, v216, v62
	v_fma_f32 v63, -v10, v217, v63
	ds_read_b128 v[202:205], v137 offset:39168
	s_waitcnt lgkmcnt(8)
	v_fma_f32 v62, -v11, v218, v62
	v_fma_f32 v63, -v60, v219, v63
	v_fma_f32 v62, -v61, v220, v62
	v_fma_f32 v63, -v58, v221, v63
	ds_read_b128 v[206:209], v137 offset:39184
	s_waitcnt lgkmcnt(8)
	v_fma_f32 v62, -v59, v222, v62
	v_fma_f32 v63, -v56, v223, v63
	v_fma_f32 v62, -v57, v224, v62
	v_fma_f32 v63, -v54, v225, v63
	ds_read_b128 v[210:213], v137 offset:39200
	s_waitcnt lgkmcnt(8)
	v_fma_f32 v62, -v55, v226, v62
	v_fma_f32 v63, -v52, v227, v63
	v_fma_f32 v62, -v53, v228, v62
	v_fma_f32 v63, -v50, v229, v63
	ds_read_b128 v[214:217], v137 offset:39216
	s_waitcnt lgkmcnt(8)
	v_fma_f32 v62, -v51, v230, v62
	v_fma_f32 v63, -v48, v231, v63
	v_fma_f32 v62, -v49, v232, v62
	v_fma_f32 v63, -v46, v233, v63
	ds_read_b128 v[218:221], v137 offset:39232
	s_waitcnt lgkmcnt(8)
	v_fma_f32 v62, -v47, v234, v62
	v_fma_f32 v63, -v44, v235, v63
	v_fma_f32 v62, -v45, v236, v62
	v_fma_f32 v63, -v42, v237, v63
	ds_read_b128 v[222:225], v137 offset:39248
	s_waitcnt lgkmcnt(8)
	v_fma_f32 v62, -v43, v238, v62
	v_fma_f32 v63, -v40, v239, v63
	v_fma_f32 v62, -v41, v240, v62
	v_fma_f32 v63, -v38, v241, v63
	ds_read_b128 v[226:229], v137 offset:39264
	s_waitcnt lgkmcnt(8)
	v_fma_f32 v62, -v39, v248, v62
	v_fma_f32 v63, -v36, v249, v63
	v_fma_f32 v62, -v37, v250, v62
	v_fma_f32 v63, -v34, v251, v63
	ds_read_b128 v[230:233], v137 offset:39280
	s_waitcnt lgkmcnt(8)
	v_fma_f32 v62, -v35, v252, v62
	v_fma_f32 v63, -v32, v253, v63
	v_fma_f32 v62, -v33, v254, v62
	v_fma_f32 v31, -v30, v255, v63
	v_add_f32_e32 v31, v62, v31
	s_nop 0
	ds_read_b128 v[234:237], v137 offset:39296
	s_waitcnt lgkmcnt(8)
	v_fma_f32 v62, -v81, v202, v100
	v_fma_f32 v63, -v0, v203, 0
	v_fma_f32 v62, -v1, v204, v62
	v_fma_f32 v63, -v2, v205, v63
	ds_read_b128 v[238:241], v137 offset:39312
	s_waitcnt lgkmcnt(8)
	v_fma_f32 v62, -v3, v206, v62
	v_fma_f32 v63, -v4, v207, v63
	v_fma_f32 v62, -v5, v208, v62
	v_fma_f32 v63, -v7, v209, v63
	ds_read_b128 v[248:251], v137 offset:39328
	s_waitcnt lgkmcnt(8)
	v_fma_f32 v62, -v6, v210, v62
	v_fma_f32 v63, -v8, v211, v63
	v_fma_f32 v62, -v9, v212, v62
	v_fma_f32 v63, -v10, v213, v63
	ds_read_b128 v[252:255], v137 offset:39344
	s_waitcnt lgkmcnt(8)
	v_fma_f32 v62, -v11, v214, v62
	v_fma_f32 v63, -v60, v215, v63
	v_fma_f32 v62, -v61, v216, v62
	v_fma_f32 v63, -v58, v217, v63
	ds_read_b128 v[202:205], v137 offset:39424
	s_waitcnt lgkmcnt(8)
	v_fma_f32 v62, -v59, v218, v62
	v_fma_f32 v63, -v56, v219, v63
	v_fma_f32 v62, -v57, v220, v62
	v_fma_f32 v63, -v54, v221, v63
	ds_read_b128 v[206:209], v137 offset:39440
	s_waitcnt lgkmcnt(8)
	v_fma_f32 v62, -v55, v222, v62
	v_fma_f32 v63, -v52, v223, v63
	v_fma_f32 v62, -v53, v224, v62
	v_fma_f32 v63, -v50, v225, v63
	ds_read_b128 v[210:213], v137 offset:39456
	s_waitcnt lgkmcnt(8)
	v_fma_f32 v62, -v51, v226, v62
	v_fma_f32 v63, -v48, v227, v63
	v_fma_f32 v62, -v49, v228, v62
	v_fma_f32 v63, -v46, v229, v63
	ds_read_b128 v[214:217], v137 offset:39472
	s_waitcnt lgkmcnt(8)
	v_fma_f32 v62, -v47, v230, v62
	v_fma_f32 v63, -v44, v231, v63
	v_fma_f32 v62, -v45, v232, v62
	v_fma_f32 v63, -v42, v233, v63
	ds_read_b128 v[218:221], v137 offset:39488
	s_waitcnt lgkmcnt(8)
	v_fma_f32 v62, -v43, v234, v62
	v_fma_f32 v63, -v40, v235, v63
	v_fma_f32 v62, -v41, v236, v62
	v_fma_f32 v63, -v38, v237, v63
	ds_read_b128 v[222:225], v137 offset:39504
	s_waitcnt lgkmcnt(8)
	v_fma_f32 v62, -v39, v238, v62
	v_fma_f32 v63, -v36, v239, v63
	v_fma_f32 v62, -v37, v240, v62
	v_fma_f32 v63, -v34, v241, v63
	ds_read_b128 v[226:229], v137 offset:39520
	s_waitcnt lgkmcnt(8)
	v_fma_f32 v62, -v35, v248, v62
	v_fma_f32 v63, -v32, v249, v63
	v_fma_f32 v62, -v33, v250, v62
	v_fma_f32 v63, -v30, v251, v63
	ds_read_b128 v[230:233], v137 offset:39536
	s_waitcnt lgkmcnt(8)
	v_fma_f32 v28, -v31, v252, v62
	v_add_f32_e32 v28, v63, v28
	s_nop 0
	ds_read_b128 v[234:237], v137 offset:39552
	s_waitcnt lgkmcnt(8)
	v_fma_f32 v62, -v81, v202, v98
	v_fma_f32 v63, -v0, v203, 0
	v_fma_f32 v62, -v1, v204, v62
	v_fma_f32 v63, -v2, v205, v63
	ds_read_b128 v[238:241], v137 offset:39568
	s_waitcnt lgkmcnt(8)
	v_fma_f32 v62, -v3, v206, v62
	v_fma_f32 v63, -v4, v207, v63
	v_fma_f32 v62, -v5, v208, v62
	v_fma_f32 v63, -v7, v209, v63
	ds_read_b128 v[248:251], v137 offset:39584
	s_waitcnt lgkmcnt(8)
	v_fma_f32 v62, -v6, v210, v62
	v_fma_f32 v63, -v8, v211, v63
	v_fma_f32 v62, -v9, v212, v62
	v_fma_f32 v63, -v10, v213, v63
	ds_read_b128 v[252:255], v137 offset:39600
	s_waitcnt lgkmcnt(8)
	v_fma_f32 v62, -v11, v214, v62
	v_fma_f32 v63, -v60, v215, v63
	v_fma_f32 v62, -v61, v216, v62
	v_fma_f32 v63, -v58, v217, v63
	ds_read_b128 v[202:205], v137 offset:39680
	s_waitcnt lgkmcnt(8)
	v_fma_f32 v62, -v59, v218, v62
	v_fma_f32 v63, -v56, v219, v63
	v_fma_f32 v62, -v57, v220, v62
	v_fma_f32 v63, -v54, v221, v63
	ds_read_b128 v[206:209], v137 offset:39696
	s_waitcnt lgkmcnt(8)
	v_fma_f32 v62, -v55, v222, v62
	v_fma_f32 v63, -v52, v223, v63
	v_fma_f32 v62, -v53, v224, v62
	v_fma_f32 v63, -v50, v225, v63
	ds_read_b128 v[210:213], v137 offset:39712
	s_waitcnt lgkmcnt(8)
	v_fma_f32 v62, -v51, v226, v62
	v_fma_f32 v63, -v48, v227, v63
	v_fma_f32 v62, -v49, v228, v62
	v_fma_f32 v63, -v46, v229, v63
	ds_read_b128 v[214:217], v137 offset:39728
	s_waitcnt lgkmcnt(8)
	v_fma_f32 v62, -v47, v230, v62
	v_fma_f32 v63, -v44, v231, v63
	v_fma_f32 v62, -v45, v232, v62
	v_fma_f32 v63, -v42, v233, v63
	ds_read_b128 v[218:221], v137 offset:39744
	s_waitcnt lgkmcnt(8)
	v_fma_f32 v62, -v43, v234, v62
	v_fma_f32 v63, -v40, v235, v63
	v_fma_f32 v62, -v41, v236, v62
	v_fma_f32 v63, -v38, v237, v63
	ds_read_b128 v[222:225], v137 offset:39760
	s_waitcnt lgkmcnt(8)
	v_fma_f32 v62, -v39, v238, v62
	v_fma_f32 v63, -v36, v239, v63
	v_fma_f32 v62, -v37, v240, v62
	v_fma_f32 v63, -v34, v241, v63
	ds_read_b128 v[226:229], v137 offset:39776
	s_waitcnt lgkmcnt(8)
	v_fma_f32 v62, -v35, v248, v62
	v_fma_f32 v63, -v32, v249, v63
	v_fma_f32 v62, -v33, v250, v62
	v_fma_f32 v63, -v30, v251, v63
	ds_read_b128 v[230:233], v137 offset:39792
	s_waitcnt lgkmcnt(8)
	v_fma_f32 v62, -v31, v252, v62
	v_fma_f32 v29, -v28, v253, v63
	v_add_f32_e32 v29, v62, v29
	s_nop 0
	ds_read_b128 v[234:237], v137 offset:39808
	s_waitcnt lgkmcnt(8)
	v_fma_f32 v62, -v81, v202, v99
	v_fma_f32 v63, -v0, v203, 0
	v_fma_f32 v62, -v1, v204, v62
	v_fma_f32 v63, -v2, v205, v63
	ds_read_b128 v[238:241], v137 offset:39824
	s_waitcnt lgkmcnt(8)
	v_fma_f32 v62, -v3, v206, v62
	v_fma_f32 v63, -v4, v207, v63
	v_fma_f32 v62, -v5, v208, v62
	v_fma_f32 v63, -v7, v209, v63
	ds_read_b128 v[248:251], v137 offset:39840
	s_waitcnt lgkmcnt(8)
	v_fma_f32 v62, -v6, v210, v62
	v_fma_f32 v63, -v8, v211, v63
	v_fma_f32 v62, -v9, v212, v62
	v_fma_f32 v63, -v10, v213, v63
	ds_read_b128 v[252:255], v137 offset:39856
	s_waitcnt lgkmcnt(8)
	v_fma_f32 v62, -v11, v214, v62
	v_fma_f32 v63, -v60, v215, v63
	v_fma_f32 v62, -v61, v216, v62
	v_fma_f32 v63, -v58, v217, v63
	ds_read_b128 v[202:205], v137 offset:39936
	s_waitcnt lgkmcnt(8)
	v_fma_f32 v62, -v59, v218, v62
	v_fma_f32 v63, -v56, v219, v63
	v_fma_f32 v62, -v57, v220, v62
	v_fma_f32 v63, -v54, v221, v63
	ds_read_b128 v[206:209], v137 offset:39952
	s_waitcnt lgkmcnt(8)
	v_fma_f32 v62, -v55, v222, v62
	v_fma_f32 v63, -v52, v223, v63
	v_fma_f32 v62, -v53, v224, v62
	v_fma_f32 v63, -v50, v225, v63
	ds_read_b128 v[210:213], v137 offset:39968
	s_waitcnt lgkmcnt(8)
	v_fma_f32 v62, -v51, v226, v62
	v_fma_f32 v63, -v48, v227, v63
	v_fma_f32 v62, -v49, v228, v62
	v_fma_f32 v63, -v46, v229, v63
	ds_read_b128 v[214:217], v137 offset:39984
	s_waitcnt lgkmcnt(8)
	v_fma_f32 v62, -v47, v230, v62
	v_fma_f32 v63, -v44, v231, v63
	v_fma_f32 v62, -v45, v232, v62
	v_fma_f32 v63, -v42, v233, v63
	ds_read_b128 v[218:221], v137 offset:40000
	s_waitcnt lgkmcnt(8)
	v_fma_f32 v62, -v43, v234, v62
	v_fma_f32 v63, -v40, v235, v63
	v_fma_f32 v62, -v41, v236, v62
	v_fma_f32 v63, -v38, v237, v63
	ds_read_b128 v[222:225], v137 offset:40016
	s_waitcnt lgkmcnt(8)
	v_fma_f32 v62, -v39, v238, v62
	v_fma_f32 v63, -v36, v239, v63
	v_fma_f32 v62, -v37, v240, v62
	v_fma_f32 v63, -v34, v241, v63
	ds_read_b128 v[226:229], v137 offset:40032
	s_waitcnt lgkmcnt(8)
	v_fma_f32 v62, -v35, v248, v62
	v_fma_f32 v63, -v32, v249, v63
	v_fma_f32 v62, -v33, v250, v62
	v_fma_f32 v63, -v30, v251, v63
	ds_read_b128 v[230:233], v137 offset:40048
	s_waitcnt lgkmcnt(8)
	v_fma_f32 v62, -v31, v252, v62
	v_fma_f32 v63, -v28, v253, v63
	v_fma_f32 v26, -v29, v254, v62
	v_add_f32_e32 v26, v63, v26
	s_nop 0
	ds_read_b128 v[234:237], v137 offset:40064
	s_waitcnt lgkmcnt(8)
	v_fma_f32 v62, -v81, v202, v97
	v_fma_f32 v63, -v0, v203, 0
	v_fma_f32 v62, -v1, v204, v62
	v_fma_f32 v63, -v2, v205, v63
	ds_read_b128 v[238:241], v137 offset:40080
	s_waitcnt lgkmcnt(8)
	v_fma_f32 v62, -v3, v206, v62
	v_fma_f32 v63, -v4, v207, v63
	v_fma_f32 v62, -v5, v208, v62
	v_fma_f32 v63, -v7, v209, v63
	ds_read_b128 v[248:251], v137 offset:40096
	s_waitcnt lgkmcnt(8)
	v_fma_f32 v62, -v6, v210, v62
	v_fma_f32 v63, -v8, v211, v63
	v_fma_f32 v62, -v9, v212, v62
	v_fma_f32 v63, -v10, v213, v63
	ds_read_b128 v[252:255], v137 offset:40112
	s_waitcnt lgkmcnt(8)
	v_fma_f32 v62, -v11, v214, v62
	v_fma_f32 v63, -v60, v215, v63
	v_fma_f32 v62, -v61, v216, v62
	v_fma_f32 v63, -v58, v217, v63
	ds_read_b128 v[202:205], v137 offset:40192
	s_waitcnt lgkmcnt(8)
	v_fma_f32 v62, -v59, v218, v62
	v_fma_f32 v63, -v56, v219, v63
	v_fma_f32 v62, -v57, v220, v62
	v_fma_f32 v63, -v54, v221, v63
	ds_read_b128 v[206:209], v137 offset:40208
	s_waitcnt lgkmcnt(8)
	v_fma_f32 v62, -v55, v222, v62
	v_fma_f32 v63, -v52, v223, v63
	v_fma_f32 v62, -v53, v224, v62
	v_fma_f32 v63, -v50, v225, v63
	ds_read_b128 v[210:213], v137 offset:40224
	s_waitcnt lgkmcnt(8)
	v_fma_f32 v62, -v51, v226, v62
	v_fma_f32 v63, -v48, v227, v63
	v_fma_f32 v62, -v49, v228, v62
	v_fma_f32 v63, -v46, v229, v63
	ds_read_b128 v[214:217], v137 offset:40240
	s_waitcnt lgkmcnt(8)
	v_fma_f32 v62, -v47, v230, v62
	v_fma_f32 v63, -v44, v231, v63
	v_fma_f32 v62, -v45, v232, v62
	v_fma_f32 v63, -v42, v233, v63
	ds_read_b128 v[218:221], v137 offset:40256
	s_waitcnt lgkmcnt(8)
	v_fma_f32 v62, -v43, v234, v62
	v_fma_f32 v63, -v40, v235, v63
	v_fma_f32 v62, -v41, v236, v62
	v_fma_f32 v63, -v38, v237, v63
	ds_read_b128 v[222:225], v137 offset:40272
	s_waitcnt lgkmcnt(8)
	v_fma_f32 v62, -v39, v238, v62
	v_fma_f32 v63, -v36, v239, v63
	v_fma_f32 v62, -v37, v240, v62
	v_fma_f32 v63, -v34, v241, v63
	ds_read_b128 v[226:229], v137 offset:40288
	s_waitcnt lgkmcnt(8)
	v_fma_f32 v62, -v35, v248, v62
	v_fma_f32 v63, -v32, v249, v63
	v_fma_f32 v62, -v33, v250, v62
	v_fma_f32 v63, -v30, v251, v63
	ds_read_b128 v[230:233], v137 offset:40304
	s_waitcnt lgkmcnt(8)
	v_fma_f32 v62, -v31, v252, v62
	v_fma_f32 v63, -v28, v253, v63
	v_fma_f32 v62, -v29, v254, v62
	v_fma_f32 v27, -v26, v255, v63
	v_add_f32_e32 v27, v62, v27
	s_nop 0
	ds_read_b128 v[234:237], v137 offset:40320
	s_waitcnt lgkmcnt(8)
	v_fma_f32 v62, -v81, v202, v96
	v_fma_f32 v63, -v0, v203, 0
	v_fma_f32 v62, -v1, v204, v62
	v_fma_f32 v63, -v2, v205, v63
	ds_read_b128 v[238:241], v137 offset:40336
	s_waitcnt lgkmcnt(8)
	v_fma_f32 v62, -v3, v206, v62
	v_fma_f32 v63, -v4, v207, v63
	v_fma_f32 v62, -v5, v208, v62
	v_fma_f32 v63, -v7, v209, v63
	ds_read_b128 v[248:251], v137 offset:40352
	s_waitcnt lgkmcnt(8)
	v_fma_f32 v62, -v6, v210, v62
	v_fma_f32 v63, -v8, v211, v63
	v_fma_f32 v62, -v9, v212, v62
	v_fma_f32 v63, -v10, v213, v63
	ds_read_b128 v[252:255], v137 offset:40368
	s_waitcnt lgkmcnt(8)
	v_fma_f32 v62, -v11, v214, v62
	v_fma_f32 v63, -v60, v215, v63
	v_fma_f32 v62, -v61, v216, v62
	v_fma_f32 v63, -v58, v217, v63
	ds_read_b128 v[202:205], v137 offset:40384
	s_waitcnt lgkmcnt(8)
	v_fma_f32 v62, -v59, v218, v62
	v_fma_f32 v63, -v56, v219, v63
	v_fma_f32 v62, -v57, v220, v62
	v_fma_f32 v63, -v54, v221, v63
	ds_read_b128 v[206:209], v137 offset:40448
	s_waitcnt lgkmcnt(8)
	v_fma_f32 v62, -v55, v222, v62
	v_fma_f32 v63, -v52, v223, v63
	v_fma_f32 v62, -v53, v224, v62
	v_fma_f32 v63, -v50, v225, v63
	ds_read_b128 v[210:213], v137 offset:40464
	s_waitcnt lgkmcnt(8)
	v_fma_f32 v62, -v51, v226, v62
	v_fma_f32 v63, -v48, v227, v63
	v_fma_f32 v62, -v49, v228, v62
	v_fma_f32 v63, -v46, v229, v63
	ds_read_b128 v[214:217], v137 offset:40480
	s_waitcnt lgkmcnt(8)
	v_fma_f32 v62, -v47, v230, v62
	v_fma_f32 v63, -v44, v231, v63
	v_fma_f32 v62, -v45, v232, v62
	v_fma_f32 v63, -v42, v233, v63
	ds_read_b128 v[218:221], v137 offset:40496
	s_waitcnt lgkmcnt(8)
	v_fma_f32 v62, -v43, v234, v62
	v_fma_f32 v63, -v40, v235, v63
	v_fma_f32 v62, -v41, v236, v62
	v_fma_f32 v63, -v38, v237, v63
	ds_read_b128 v[222:225], v137 offset:40512
	s_waitcnt lgkmcnt(8)
	v_fma_f32 v62, -v39, v238, v62
	v_fma_f32 v63, -v36, v239, v63
	v_fma_f32 v62, -v37, v240, v62
	v_fma_f32 v63, -v34, v241, v63
	ds_read_b128 v[226:229], v137 offset:40528
	s_waitcnt lgkmcnt(8)
	v_fma_f32 v62, -v35, v248, v62
	v_fma_f32 v63, -v32, v249, v63
	v_fma_f32 v62, -v33, v250, v62
	v_fma_f32 v63, -v30, v251, v63
	ds_read_b128 v[230:233], v137 offset:40544
	s_waitcnt lgkmcnt(8)
	v_fma_f32 v62, -v31, v252, v62
	v_fma_f32 v63, -v28, v253, v63
	v_fma_f32 v62, -v29, v254, v62
	v_fma_f32 v63, -v26, v255, v63
	ds_read_b128 v[234:237], v137 offset:40560
	s_waitcnt lgkmcnt(8)
	v_fma_f32 v24, -v27, v202, v62
	v_add_f32_e32 v24, v63, v24
	s_nop 0
	ds_read_b128 v[238:241], v137 offset:40576
	s_waitcnt lgkmcnt(8)
	v_fma_f32 v62, -v81, v206, v95
	v_fma_f32 v63, -v0, v207, 0
	v_fma_f32 v62, -v1, v208, v62
	v_fma_f32 v63, -v2, v209, v63
	ds_read_b128 v[248:251], v137 offset:40592
	s_waitcnt lgkmcnt(8)
	v_fma_f32 v62, -v3, v210, v62
	v_fma_f32 v63, -v4, v211, v63
	v_fma_f32 v62, -v5, v212, v62
	v_fma_f32 v63, -v7, v213, v63
	ds_read_b128 v[252:255], v137 offset:40608
	s_waitcnt lgkmcnt(8)
	v_fma_f32 v62, -v6, v214, v62
	v_fma_f32 v63, -v8, v215, v63
	v_fma_f32 v62, -v9, v216, v62
	v_fma_f32 v63, -v10, v217, v63
	ds_read_b128 v[202:205], v137 offset:40624
	s_waitcnt lgkmcnt(8)
	v_fma_f32 v62, -v11, v218, v62
	v_fma_f32 v63, -v60, v219, v63
	v_fma_f32 v62, -v61, v220, v62
	v_fma_f32 v63, -v58, v221, v63
	ds_read_b128 v[206:209], v137 offset:40640
	s_waitcnt lgkmcnt(8)
	v_fma_f32 v62, -v59, v222, v62
	v_fma_f32 v63, -v56, v223, v63
	v_fma_f32 v62, -v57, v224, v62
	v_fma_f32 v63, -v54, v225, v63
	ds_read_b128 v[210:213], v137 offset:40704
	s_waitcnt lgkmcnt(8)
	v_fma_f32 v62, -v55, v226, v62
	v_fma_f32 v63, -v52, v227, v63
	v_fma_f32 v62, -v53, v228, v62
	v_fma_f32 v63, -v50, v229, v63
	ds_read_b128 v[214:217], v137 offset:40720
	s_waitcnt lgkmcnt(8)
	v_fma_f32 v62, -v51, v230, v62
	v_fma_f32 v63, -v48, v231, v63
	v_fma_f32 v62, -v49, v232, v62
	v_fma_f32 v63, -v46, v233, v63
	ds_read_b128 v[218:221], v137 offset:40736
	s_waitcnt lgkmcnt(8)
	v_fma_f32 v62, -v47, v234, v62
	v_fma_f32 v63, -v44, v235, v63
	v_fma_f32 v62, -v45, v236, v62
	v_fma_f32 v63, -v42, v237, v63
	ds_read_b128 v[222:225], v137 offset:40752
	s_waitcnt lgkmcnt(8)
	v_fma_f32 v62, -v43, v238, v62
	v_fma_f32 v63, -v40, v239, v63
	v_fma_f32 v62, -v41, v240, v62
	v_fma_f32 v63, -v38, v241, v63
	ds_read_b128 v[226:229], v137 offset:40768
	s_waitcnt lgkmcnt(8)
	v_fma_f32 v62, -v39, v248, v62
	v_fma_f32 v63, -v36, v249, v63
	v_fma_f32 v62, -v37, v250, v62
	v_fma_f32 v63, -v34, v251, v63
	ds_read_b128 v[230:233], v137 offset:40784
	s_waitcnt lgkmcnt(8)
	v_fma_f32 v62, -v35, v252, v62
	v_fma_f32 v63, -v32, v253, v63
	v_fma_f32 v62, -v33, v254, v62
	v_fma_f32 v63, -v30, v255, v63
	ds_read_b128 v[234:237], v137 offset:40800
	s_waitcnt lgkmcnt(8)
	v_fma_f32 v62, -v31, v202, v62
	v_fma_f32 v63, -v28, v203, v63
	v_fma_f32 v62, -v29, v204, v62
	v_fma_f32 v63, -v26, v205, v63
	ds_read_b128 v[238:241], v137 offset:40816
	s_waitcnt lgkmcnt(8)
	v_fma_f32 v62, -v27, v206, v62
	v_fma_f32 v25, -v24, v207, v63
	v_add_f32_e32 v25, v62, v25
	s_nop 0
	ds_read_b128 v[248:251], v137 offset:40832
	s_waitcnt lgkmcnt(8)
	v_fma_f32 v62, -v81, v210, v93
	v_fma_f32 v63, -v0, v211, 0
	v_fma_f32 v62, -v1, v212, v62
	v_fma_f32 v63, -v2, v213, v63
	ds_read_b128 v[252:255], v137 offset:40848
	s_waitcnt lgkmcnt(8)
	v_fma_f32 v62, -v3, v214, v62
	v_fma_f32 v63, -v4, v215, v63
	v_fma_f32 v62, -v5, v216, v62
	v_fma_f32 v63, -v7, v217, v63
	ds_read_b128 v[202:205], v137 offset:40864
	s_waitcnt lgkmcnt(8)
	v_fma_f32 v62, -v6, v218, v62
	v_fma_f32 v63, -v8, v219, v63
	v_fma_f32 v62, -v9, v220, v62
	v_fma_f32 v63, -v10, v221, v63
	ds_read_b128 v[206:209], v137 offset:40880
	s_waitcnt lgkmcnt(8)
	v_fma_f32 v62, -v11, v222, v62
	v_fma_f32 v63, -v60, v223, v63
	v_fma_f32 v62, -v61, v224, v62
	v_fma_f32 v63, -v58, v225, v63
	ds_read_b128 v[210:213], v137 offset:40896
	s_waitcnt lgkmcnt(8)
	v_fma_f32 v62, -v59, v226, v62
	v_fma_f32 v63, -v56, v227, v63
	v_fma_f32 v62, -v57, v228, v62
	v_fma_f32 v63, -v54, v229, v63
	ds_read_b128 v[214:217], v137 offset:40960
	s_waitcnt lgkmcnt(8)
	v_fma_f32 v62, -v55, v230, v62
	v_fma_f32 v63, -v52, v231, v63
	v_fma_f32 v62, -v53, v232, v62
	v_fma_f32 v63, -v50, v233, v63
	ds_read_b128 v[218:221], v137 offset:40976
	s_waitcnt lgkmcnt(8)
	v_fma_f32 v62, -v51, v234, v62
	v_fma_f32 v63, -v48, v235, v63
	v_fma_f32 v62, -v49, v236, v62
	v_fma_f32 v63, -v46, v237, v63
	ds_read_b128 v[222:225], v137 offset:40992
	s_waitcnt lgkmcnt(8)
	v_fma_f32 v62, -v47, v238, v62
	v_fma_f32 v63, -v44, v239, v63
	v_fma_f32 v62, -v45, v240, v62
	v_fma_f32 v63, -v42, v241, v63
	ds_read_b128 v[226:229], v137 offset:41008
	s_waitcnt lgkmcnt(8)
	v_fma_f32 v62, -v43, v248, v62
	v_fma_f32 v63, -v40, v249, v63
	v_fma_f32 v62, -v41, v250, v62
	v_fma_f32 v63, -v38, v251, v63
	ds_read_b128 v[230:233], v137 offset:41024
	s_waitcnt lgkmcnt(8)
	v_fma_f32 v62, -v39, v252, v62
	v_fma_f32 v63, -v36, v253, v63
	v_fma_f32 v62, -v37, v254, v62
	v_fma_f32 v63, -v34, v255, v63
	ds_read_b128 v[234:237], v137 offset:41040
	s_waitcnt lgkmcnt(8)
	v_fma_f32 v62, -v35, v202, v62
	v_fma_f32 v63, -v32, v203, v63
	v_fma_f32 v62, -v33, v204, v62
	v_fma_f32 v63, -v30, v205, v63
	ds_read_b128 v[238:241], v137 offset:41056
	s_waitcnt lgkmcnt(8)
	v_fma_f32 v62, -v31, v206, v62
	v_fma_f32 v63, -v28, v207, v63
	v_fma_f32 v62, -v29, v208, v62
	v_fma_f32 v63, -v26, v209, v63
	ds_read_b128 v[248:251], v137 offset:41072
	s_waitcnt lgkmcnt(8)
	v_fma_f32 v62, -v27, v210, v62
	v_fma_f32 v63, -v24, v211, v63
	v_fma_f32 v22, -v25, v212, v62
	v_add_f32_e32 v22, v63, v22
	s_nop 0
	ds_read_b128 v[252:255], v137 offset:41088
	s_waitcnt lgkmcnt(8)
	v_fma_f32 v62, -v81, v214, v94
	v_fma_f32 v63, -v0, v215, 0
	v_fma_f32 v62, -v1, v216, v62
	v_fma_f32 v63, -v2, v217, v63
	ds_read_b128 v[202:205], v137 offset:41104
	s_waitcnt lgkmcnt(8)
	v_fma_f32 v62, -v3, v218, v62
	v_fma_f32 v63, -v4, v219, v63
	v_fma_f32 v62, -v5, v220, v62
	v_fma_f32 v63, -v7, v221, v63
	ds_read_b128 v[206:209], v137 offset:41120
	s_waitcnt lgkmcnt(8)
	v_fma_f32 v62, -v6, v222, v62
	v_fma_f32 v63, -v8, v223, v63
	v_fma_f32 v62, -v9, v224, v62
	v_fma_f32 v63, -v10, v225, v63
	ds_read_b128 v[210:213], v137 offset:41136
	s_waitcnt lgkmcnt(8)
	v_fma_f32 v62, -v11, v226, v62
	v_fma_f32 v63, -v60, v227, v63
	v_fma_f32 v62, -v61, v228, v62
	v_fma_f32 v63, -v58, v229, v63
	ds_read_b128 v[214:217], v137 offset:41152
	s_waitcnt lgkmcnt(8)
	v_fma_f32 v62, -v59, v230, v62
	v_fma_f32 v63, -v56, v231, v63
	v_fma_f32 v62, -v57, v232, v62
	v_fma_f32 v63, -v54, v233, v63
	ds_read_b128 v[218:221], v137 offset:41216
	s_waitcnt lgkmcnt(8)
	v_fma_f32 v62, -v55, v234, v62
	v_fma_f32 v63, -v52, v235, v63
	v_fma_f32 v62, -v53, v236, v62
	v_fma_f32 v63, -v50, v237, v63
	ds_read_b128 v[222:225], v137 offset:41232
	s_waitcnt lgkmcnt(8)
	v_fma_f32 v62, -v51, v238, v62
	v_fma_f32 v63, -v48, v239, v63
	v_fma_f32 v62, -v49, v240, v62
	v_fma_f32 v63, -v46, v241, v63
	ds_read_b128 v[226:229], v137 offset:41248
	s_waitcnt lgkmcnt(8)
	v_fma_f32 v62, -v47, v248, v62
	v_fma_f32 v63, -v44, v249, v63
	v_fma_f32 v62, -v45, v250, v62
	v_fma_f32 v63, -v42, v251, v63
	ds_read_b128 v[230:233], v137 offset:41264
	s_waitcnt lgkmcnt(8)
	v_fma_f32 v62, -v43, v252, v62
	v_fma_f32 v63, -v40, v253, v63
	v_fma_f32 v62, -v41, v254, v62
	v_fma_f32 v63, -v38, v255, v63
	ds_read_b128 v[234:237], v137 offset:41280
	s_waitcnt lgkmcnt(8)
	v_fma_f32 v62, -v39, v202, v62
	v_fma_f32 v63, -v36, v203, v63
	v_fma_f32 v62, -v37, v204, v62
	v_fma_f32 v63, -v34, v205, v63
	ds_read_b128 v[238:241], v137 offset:41296
	s_waitcnt lgkmcnt(8)
	v_fma_f32 v62, -v35, v206, v62
	v_fma_f32 v63, -v32, v207, v63
	v_fma_f32 v62, -v33, v208, v62
	v_fma_f32 v63, -v30, v209, v63
	ds_read_b128 v[248:251], v137 offset:41312
	s_waitcnt lgkmcnt(8)
	v_fma_f32 v62, -v31, v210, v62
	v_fma_f32 v63, -v28, v211, v63
	v_fma_f32 v62, -v29, v212, v62
	v_fma_f32 v63, -v26, v213, v63
	ds_read_b128 v[252:255], v137 offset:41328
	s_waitcnt lgkmcnt(8)
	v_fma_f32 v62, -v27, v214, v62
	v_fma_f32 v63, -v24, v215, v63
	v_fma_f32 v62, -v25, v216, v62
	v_fma_f32 v23, -v22, v217, v63
	v_add_f32_e32 v23, v62, v23
	s_nop 0
	ds_read_b128 v[202:205], v137 offset:41344
	s_waitcnt lgkmcnt(8)
	v_fma_f32 v62, -v81, v218, v92
	v_fma_f32 v63, -v0, v219, 0
	v_fma_f32 v62, -v1, v220, v62
	v_fma_f32 v63, -v2, v221, v63
	ds_read_b128 v[206:209], v137 offset:41360
	s_waitcnt lgkmcnt(8)
	v_fma_f32 v62, -v3, v222, v62
	v_fma_f32 v63, -v4, v223, v63
	v_fma_f32 v62, -v5, v224, v62
	v_fma_f32 v63, -v7, v225, v63
	ds_read_b128 v[210:213], v137 offset:41376
	s_waitcnt lgkmcnt(8)
	v_fma_f32 v62, -v6, v226, v62
	v_fma_f32 v63, -v8, v227, v63
	v_fma_f32 v62, -v9, v228, v62
	v_fma_f32 v63, -v10, v229, v63
	ds_read_b128 v[214:217], v137 offset:41392
	s_waitcnt lgkmcnt(8)
	v_fma_f32 v62, -v11, v230, v62
	v_fma_f32 v63, -v60, v231, v63
	v_fma_f32 v62, -v61, v232, v62
	v_fma_f32 v63, -v58, v233, v63
	ds_read_b128 v[218:221], v137 offset:41408
	s_waitcnt lgkmcnt(8)
	v_fma_f32 v62, -v59, v234, v62
	v_fma_f32 v63, -v56, v235, v63
	v_fma_f32 v62, -v57, v236, v62
	v_fma_f32 v63, -v54, v237, v63
	ds_read_b128 v[222:225], v137 offset:41424
	s_waitcnt lgkmcnt(8)
	v_fma_f32 v62, -v55, v238, v62
	v_fma_f32 v63, -v52, v239, v63
	v_fma_f32 v62, -v53, v240, v62
	v_fma_f32 v63, -v50, v241, v63
	ds_read_b128 v[226:229], v137 offset:41472
	s_waitcnt lgkmcnt(8)
	v_fma_f32 v62, -v51, v248, v62
	v_fma_f32 v63, -v48, v249, v63
	v_fma_f32 v62, -v49, v250, v62
	v_fma_f32 v63, -v46, v251, v63
	ds_read_b128 v[230:233], v137 offset:41488
	s_waitcnt lgkmcnt(8)
	v_fma_f32 v62, -v47, v252, v62
	v_fma_f32 v63, -v44, v253, v63
	v_fma_f32 v62, -v45, v254, v62
	v_fma_f32 v63, -v42, v255, v63
	ds_read_b128 v[234:237], v137 offset:41504
	s_waitcnt lgkmcnt(8)
	v_fma_f32 v62, -v43, v202, v62
	v_fma_f32 v63, -v40, v203, v63
	v_fma_f32 v62, -v41, v204, v62
	v_fma_f32 v63, -v38, v205, v63
	ds_read_b128 v[238:241], v137 offset:41520
	s_waitcnt lgkmcnt(8)
	v_fma_f32 v62, -v39, v206, v62
	v_fma_f32 v63, -v36, v207, v63
	v_fma_f32 v62, -v37, v208, v62
	v_fma_f32 v63, -v34, v209, v63
	ds_read_b128 v[248:251], v137 offset:41536
	s_waitcnt lgkmcnt(8)
	v_fma_f32 v62, -v35, v210, v62
	v_fma_f32 v63, -v32, v211, v63
	v_fma_f32 v62, -v33, v212, v62
	v_fma_f32 v63, -v30, v213, v63
	ds_read_b128 v[252:255], v137 offset:41552
	s_waitcnt lgkmcnt(8)
	v_fma_f32 v62, -v31, v214, v62
	v_fma_f32 v63, -v28, v215, v63
	v_fma_f32 v62, -v29, v216, v62
	v_fma_f32 v63, -v26, v217, v63
	ds_read_b128 v[202:205], v137 offset:41568
	s_waitcnt lgkmcnt(8)
	v_fma_f32 v62, -v27, v218, v62
	v_fma_f32 v63, -v24, v219, v63
	v_fma_f32 v62, -v25, v220, v62
	v_fma_f32 v63, -v22, v221, v63
	ds_read_b128 v[206:209], v137 offset:41584
	s_waitcnt lgkmcnt(8)
	v_fma_f32 v20, -v23, v222, v62
	v_add_f32_e32 v20, v63, v20
	s_nop 0
	ds_read_b128 v[210:213], v137 offset:41600
	s_waitcnt lgkmcnt(8)
	v_fma_f32 v62, -v81, v226, v90
	v_fma_f32 v63, -v0, v227, 0
	v_fma_f32 v62, -v1, v228, v62
	v_fma_f32 v63, -v2, v229, v63
	ds_read_b128 v[214:217], v137 offset:41616
	s_waitcnt lgkmcnt(8)
	v_fma_f32 v62, -v3, v230, v62
	v_fma_f32 v63, -v4, v231, v63
	v_fma_f32 v62, -v5, v232, v62
	v_fma_f32 v63, -v7, v233, v63
	ds_read_b128 v[218:221], v137 offset:41632
	s_waitcnt lgkmcnt(8)
	v_fma_f32 v62, -v6, v234, v62
	v_fma_f32 v63, -v8, v235, v63
	v_fma_f32 v62, -v9, v236, v62
	v_fma_f32 v63, -v10, v237, v63
	ds_read_b128 v[222:225], v137 offset:41648
	s_waitcnt lgkmcnt(8)
	v_fma_f32 v62, -v11, v238, v62
	v_fma_f32 v63, -v60, v239, v63
	v_fma_f32 v62, -v61, v240, v62
	v_fma_f32 v63, -v58, v241, v63
	ds_read_b128 v[226:229], v137 offset:41664
	s_waitcnt lgkmcnt(8)
	v_fma_f32 v62, -v59, v248, v62
	v_fma_f32 v63, -v56, v249, v63
	v_fma_f32 v62, -v57, v250, v62
	v_fma_f32 v63, -v54, v251, v63
	ds_read_b128 v[230:233], v137 offset:41680
	s_waitcnt lgkmcnt(8)
	v_fma_f32 v62, -v55, v252, v62
	v_fma_f32 v63, -v52, v253, v63
	v_fma_f32 v62, -v53, v254, v62
	v_fma_f32 v63, -v50, v255, v63
	ds_read_b128 v[234:237], v137 offset:41728
	s_waitcnt lgkmcnt(8)
	v_fma_f32 v62, -v51, v202, v62
	v_fma_f32 v63, -v48, v203, v63
	v_fma_f32 v62, -v49, v204, v62
	v_fma_f32 v63, -v46, v205, v63
	ds_read_b128 v[238:241], v137 offset:41744
	s_waitcnt lgkmcnt(8)
	v_fma_f32 v62, -v47, v206, v62
	v_fma_f32 v63, -v44, v207, v63
	v_fma_f32 v62, -v45, v208, v62
	v_fma_f32 v63, -v42, v209, v63
	ds_read_b128 v[248:251], v137 offset:41760
	s_waitcnt lgkmcnt(8)
	v_fma_f32 v62, -v43, v210, v62
	v_fma_f32 v63, -v40, v211, v63
	v_fma_f32 v62, -v41, v212, v62
	v_fma_f32 v63, -v38, v213, v63
	ds_read_b128 v[252:255], v137 offset:41776
	s_waitcnt lgkmcnt(8)
	v_fma_f32 v62, -v39, v214, v62
	v_fma_f32 v63, -v36, v215, v63
	v_fma_f32 v62, -v37, v216, v62
	v_fma_f32 v63, -v34, v217, v63
	ds_read_b128 v[202:205], v137 offset:41792
	s_waitcnt lgkmcnt(8)
	v_fma_f32 v62, -v35, v218, v62
	v_fma_f32 v63, -v32, v219, v63
	v_fma_f32 v62, -v33, v220, v62
	v_fma_f32 v63, -v30, v221, v63
	ds_read_b128 v[206:209], v137 offset:41808
	s_waitcnt lgkmcnt(8)
	v_fma_f32 v62, -v31, v222, v62
	v_fma_f32 v63, -v28, v223, v63
	v_fma_f32 v62, -v29, v224, v62
	v_fma_f32 v63, -v26, v225, v63
	ds_read_b128 v[210:213], v137 offset:41824
	s_waitcnt lgkmcnt(8)
	v_fma_f32 v62, -v27, v226, v62
	v_fma_f32 v63, -v24, v227, v63
	v_fma_f32 v62, -v25, v228, v62
	v_fma_f32 v63, -v22, v229, v63
	ds_read_b128 v[214:217], v137 offset:41840
	s_waitcnt lgkmcnt(8)
	v_fma_f32 v62, -v23, v230, v62
	v_fma_f32 v21, -v20, v231, v63
	v_add_f32_e32 v21, v62, v21
	s_nop 0
	ds_read_b128 v[218:221], v137 offset:41856
	s_waitcnt lgkmcnt(8)
	v_fma_f32 v62, -v81, v234, v91
	v_fma_f32 v63, -v0, v235, 0
	v_fma_f32 v62, -v1, v236, v62
	v_fma_f32 v63, -v2, v237, v63
	ds_read_b128 v[222:225], v137 offset:41872
	s_waitcnt lgkmcnt(8)
	v_fma_f32 v62, -v3, v238, v62
	v_fma_f32 v63, -v4, v239, v63
	v_fma_f32 v62, -v5, v240, v62
	v_fma_f32 v63, -v7, v241, v63
	ds_read_b128 v[226:229], v137 offset:41888
	s_waitcnt lgkmcnt(8)
	v_fma_f32 v62, -v6, v248, v62
	v_fma_f32 v63, -v8, v249, v63
	v_fma_f32 v62, -v9, v250, v62
	v_fma_f32 v63, -v10, v251, v63
	ds_read_b128 v[230:233], v137 offset:41904
	s_waitcnt lgkmcnt(8)
	v_fma_f32 v62, -v11, v252, v62
	v_fma_f32 v63, -v60, v253, v63
	v_fma_f32 v62, -v61, v254, v62
	v_fma_f32 v63, -v58, v255, v63
	ds_read_b128 v[234:237], v137 offset:41920
	s_waitcnt lgkmcnt(8)
	v_fma_f32 v62, -v59, v202, v62
	v_fma_f32 v63, -v56, v203, v63
	v_fma_f32 v62, -v57, v204, v62
	v_fma_f32 v63, -v54, v205, v63
	ds_read_b128 v[238:241], v137 offset:41936
	s_waitcnt lgkmcnt(8)
	v_fma_f32 v62, -v55, v206, v62
	v_fma_f32 v63, -v52, v207, v63
	v_fma_f32 v62, -v53, v208, v62
	v_fma_f32 v63, -v50, v209, v63
	ds_read_b128 v[248:251], v137 offset:41984
	s_waitcnt lgkmcnt(8)
	v_fma_f32 v62, -v51, v210, v62
	v_fma_f32 v63, -v48, v211, v63
	v_fma_f32 v62, -v49, v212, v62
	v_fma_f32 v63, -v46, v213, v63
	ds_read_b128 v[252:255], v137 offset:42000
	s_waitcnt lgkmcnt(8)
	v_fma_f32 v62, -v47, v214, v62
	v_fma_f32 v63, -v44, v215, v63
	v_fma_f32 v62, -v45, v216, v62
	v_fma_f32 v63, -v42, v217, v63
	ds_read_b128 v[202:205], v137 offset:42016
	s_waitcnt lgkmcnt(8)
	v_fma_f32 v62, -v43, v218, v62
	v_fma_f32 v63, -v40, v219, v63
	v_fma_f32 v62, -v41, v220, v62
	v_fma_f32 v63, -v38, v221, v63
	ds_read_b128 v[206:209], v137 offset:42032
	s_waitcnt lgkmcnt(8)
	v_fma_f32 v62, -v39, v222, v62
	v_fma_f32 v63, -v36, v223, v63
	v_fma_f32 v62, -v37, v224, v62
	v_fma_f32 v63, -v34, v225, v63
	ds_read_b128 v[210:213], v137 offset:42048
	s_waitcnt lgkmcnt(8)
	v_fma_f32 v62, -v35, v226, v62
	v_fma_f32 v63, -v32, v227, v63
	v_fma_f32 v62, -v33, v228, v62
	v_fma_f32 v63, -v30, v229, v63
	ds_read_b128 v[214:217], v137 offset:42064
	s_waitcnt lgkmcnt(8)
	v_fma_f32 v62, -v31, v230, v62
	v_fma_f32 v63, -v28, v231, v63
	v_fma_f32 v62, -v29, v232, v62
	v_fma_f32 v63, -v26, v233, v63
	ds_read_b128 v[218:221], v137 offset:42080
	s_waitcnt lgkmcnt(8)
	v_fma_f32 v62, -v27, v234, v62
	v_fma_f32 v63, -v24, v235, v63
	v_fma_f32 v62, -v25, v236, v62
	v_fma_f32 v63, -v22, v237, v63
	ds_read_b128 v[222:225], v137 offset:42096
	s_waitcnt lgkmcnt(8)
	v_fma_f32 v62, -v23, v238, v62
	v_fma_f32 v63, -v20, v239, v63
	v_fma_f32 v18, -v21, v240, v62
	v_add_f32_e32 v18, v63, v18
	s_nop 0
	ds_read_b128 v[226:229], v137 offset:42112
	s_waitcnt lgkmcnt(8)
	v_fma_f32 v62, -v81, v248, v89
	v_fma_f32 v63, -v0, v249, 0
	v_fma_f32 v62, -v1, v250, v62
	v_fma_f32 v63, -v2, v251, v63
	ds_read_b128 v[230:233], v137 offset:42128
	s_waitcnt lgkmcnt(8)
	v_fma_f32 v62, -v3, v252, v62
	v_fma_f32 v63, -v4, v253, v63
	v_fma_f32 v62, -v5, v254, v62
	v_fma_f32 v63, -v7, v255, v63
	ds_read_b128 v[234:237], v137 offset:42144
	s_waitcnt lgkmcnt(8)
	v_fma_f32 v62, -v6, v202, v62
	v_fma_f32 v63, -v8, v203, v63
	v_fma_f32 v62, -v9, v204, v62
	v_fma_f32 v63, -v10, v205, v63
	ds_read_b128 v[238:241], v137 offset:42160
	s_waitcnt lgkmcnt(8)
	v_fma_f32 v62, -v11, v206, v62
	v_fma_f32 v63, -v60, v207, v63
	v_fma_f32 v62, -v61, v208, v62
	v_fma_f32 v63, -v58, v209, v63
	ds_read_b128 v[248:251], v137 offset:42176
	s_waitcnt lgkmcnt(8)
	v_fma_f32 v62, -v59, v210, v62
	v_fma_f32 v63, -v56, v211, v63
	v_fma_f32 v62, -v57, v212, v62
	v_fma_f32 v63, -v54, v213, v63
	ds_read_b128 v[252:255], v137 offset:42192
	s_waitcnt lgkmcnt(8)
	v_fma_f32 v62, -v55, v214, v62
	v_fma_f32 v63, -v52, v215, v63
	v_fma_f32 v62, -v53, v216, v62
	v_fma_f32 v63, -v50, v217, v63
	ds_read_b128 v[202:205], v137 offset:42240
	s_waitcnt lgkmcnt(8)
	v_fma_f32 v62, -v51, v218, v62
	v_fma_f32 v63, -v48, v219, v63
	v_fma_f32 v62, -v49, v220, v62
	v_fma_f32 v63, -v46, v221, v63
	ds_read_b128 v[206:209], v137 offset:42256
	s_waitcnt lgkmcnt(8)
	v_fma_f32 v62, -v47, v222, v62
	v_fma_f32 v63, -v44, v223, v63
	v_fma_f32 v62, -v45, v224, v62
	v_fma_f32 v63, -v42, v225, v63
	ds_read_b128 v[210:213], v137 offset:42272
	s_waitcnt lgkmcnt(8)
	v_fma_f32 v62, -v43, v226, v62
	v_fma_f32 v63, -v40, v227, v63
	v_fma_f32 v62, -v41, v228, v62
	v_fma_f32 v63, -v38, v229, v63
	ds_read_b128 v[214:217], v137 offset:42288
	s_waitcnt lgkmcnt(8)
	v_fma_f32 v62, -v39, v230, v62
	v_fma_f32 v63, -v36, v231, v63
	v_fma_f32 v62, -v37, v232, v62
	v_fma_f32 v63, -v34, v233, v63
	ds_read_b128 v[218:221], v137 offset:42304
	s_waitcnt lgkmcnt(8)
	v_fma_f32 v62, -v35, v234, v62
	v_fma_f32 v63, -v32, v235, v63
	v_fma_f32 v62, -v33, v236, v62
	v_fma_f32 v63, -v30, v237, v63
	ds_read_b128 v[222:225], v137 offset:42320
	s_waitcnt lgkmcnt(8)
	v_fma_f32 v62, -v31, v238, v62
	v_fma_f32 v63, -v28, v239, v63
	v_fma_f32 v62, -v29, v240, v62
	v_fma_f32 v63, -v26, v241, v63
	ds_read_b128 v[226:229], v137 offset:42336
	s_waitcnt lgkmcnt(8)
	v_fma_f32 v62, -v27, v248, v62
	v_fma_f32 v63, -v24, v249, v63
	v_fma_f32 v62, -v25, v250, v62
	v_fma_f32 v63, -v22, v251, v63
	ds_read_b128 v[230:233], v137 offset:42352
	s_waitcnt lgkmcnt(8)
	v_fma_f32 v62, -v23, v252, v62
	v_fma_f32 v63, -v20, v253, v63
	v_fma_f32 v62, -v21, v254, v62
	v_fma_f32 v19, -v18, v255, v63
	v_add_f32_e32 v19, v62, v19
	s_nop 0
	ds_read_b128 v[234:237], v137 offset:42368
	s_waitcnt lgkmcnt(8)
	v_fma_f32 v62, -v81, v202, v88
	v_fma_f32 v63, -v0, v203, 0
	v_fma_f32 v62, -v1, v204, v62
	v_fma_f32 v63, -v2, v205, v63
	ds_read_b128 v[238:241], v137 offset:42384
	s_waitcnt lgkmcnt(8)
	v_fma_f32 v62, -v3, v206, v62
	v_fma_f32 v63, -v4, v207, v63
	v_fma_f32 v62, -v5, v208, v62
	v_fma_f32 v63, -v7, v209, v63
	ds_read_b128 v[248:251], v137 offset:42400
	s_waitcnt lgkmcnt(8)
	v_fma_f32 v62, -v6, v210, v62
	v_fma_f32 v63, -v8, v211, v63
	v_fma_f32 v62, -v9, v212, v62
	v_fma_f32 v63, -v10, v213, v63
	ds_read_b128 v[252:255], v137 offset:42416
	s_waitcnt lgkmcnt(8)
	v_fma_f32 v62, -v11, v214, v62
	v_fma_f32 v63, -v60, v215, v63
	v_fma_f32 v62, -v61, v216, v62
	v_fma_f32 v63, -v58, v217, v63
	ds_read_b128 v[202:205], v137 offset:42432
	s_waitcnt lgkmcnt(8)
	v_fma_f32 v62, -v59, v218, v62
	v_fma_f32 v63, -v56, v219, v63
	v_fma_f32 v62, -v57, v220, v62
	v_fma_f32 v63, -v54, v221, v63
	ds_read_b128 v[206:209], v137 offset:42448
	s_waitcnt lgkmcnt(8)
	v_fma_f32 v62, -v55, v222, v62
	v_fma_f32 v63, -v52, v223, v63
	v_fma_f32 v62, -v53, v224, v62
	v_fma_f32 v63, -v50, v225, v63
	ds_read_b128 v[210:213], v137 offset:42464
	s_waitcnt lgkmcnt(8)
	v_fma_f32 v62, -v51, v226, v62
	v_fma_f32 v63, -v48, v227, v63
	v_fma_f32 v62, -v49, v228, v62
	v_fma_f32 v63, -v46, v229, v63
	ds_read_b128 v[214:217], v137 offset:42496
	s_waitcnt lgkmcnt(8)
	v_fma_f32 v62, -v47, v230, v62
	v_fma_f32 v63, -v44, v231, v63
	v_fma_f32 v62, -v45, v232, v62
	v_fma_f32 v63, -v42, v233, v63
	ds_read_b128 v[218:221], v137 offset:42512
	s_waitcnt lgkmcnt(8)
	v_fma_f32 v62, -v43, v234, v62
	v_fma_f32 v63, -v40, v235, v63
	v_fma_f32 v62, -v41, v236, v62
	v_fma_f32 v63, -v38, v237, v63
	ds_read_b128 v[222:225], v137 offset:42528
	s_waitcnt lgkmcnt(8)
	v_fma_f32 v62, -v39, v238, v62
	v_fma_f32 v63, -v36, v239, v63
	v_fma_f32 v62, -v37, v240, v62
	v_fma_f32 v63, -v34, v241, v63
	ds_read_b128 v[226:229], v137 offset:42544
	s_waitcnt lgkmcnt(8)
	v_fma_f32 v62, -v35, v248, v62
	v_fma_f32 v63, -v32, v249, v63
	v_fma_f32 v62, -v33, v250, v62
	v_fma_f32 v63, -v30, v251, v63
	ds_read_b128 v[230:233], v137 offset:42560
	s_waitcnt lgkmcnt(8)
	v_fma_f32 v62, -v31, v252, v62
	v_fma_f32 v63, -v28, v253, v63
	v_fma_f32 v62, -v29, v254, v62
	v_fma_f32 v63, -v26, v255, v63
	ds_read_b128 v[234:237], v137 offset:42576
	s_waitcnt lgkmcnt(8)
	v_fma_f32 v62, -v27, v202, v62
	v_fma_f32 v63, -v24, v203, v63
	v_fma_f32 v62, -v25, v204, v62
	v_fma_f32 v63, -v22, v205, v63
	ds_read_b128 v[238:241], v137 offset:42592
	s_waitcnt lgkmcnt(8)
	v_fma_f32 v62, -v23, v206, v62
	v_fma_f32 v63, -v20, v207, v63
	v_fma_f32 v62, -v21, v208, v62
	v_fma_f32 v63, -v18, v209, v63
	ds_read_b128 v[248:251], v137 offset:42608
	s_waitcnt lgkmcnt(8)
	v_fma_f32 v16, -v19, v210, v62
	v_add_f32_e32 v16, v63, v16
	s_nop 0
	ds_read_b128 v[252:255], v137 offset:42624
	s_waitcnt lgkmcnt(8)
	v_fma_f32 v62, -v81, v214, v87
	v_fma_f32 v63, -v0, v215, 0
	v_fma_f32 v62, -v1, v216, v62
	v_fma_f32 v63, -v2, v217, v63
	ds_read_b128 v[202:205], v137 offset:42640
	s_waitcnt lgkmcnt(8)
	v_fma_f32 v62, -v3, v218, v62
	v_fma_f32 v63, -v4, v219, v63
	v_fma_f32 v62, -v5, v220, v62
	v_fma_f32 v63, -v7, v221, v63
	ds_read_b128 v[206:209], v137 offset:42656
	s_waitcnt lgkmcnt(8)
	v_fma_f32 v62, -v6, v222, v62
	v_fma_f32 v63, -v8, v223, v63
	v_fma_f32 v62, -v9, v224, v62
	v_fma_f32 v63, -v10, v225, v63
	ds_read_b128 v[210:213], v137 offset:42672
	s_waitcnt lgkmcnt(8)
	v_fma_f32 v62, -v11, v226, v62
	v_fma_f32 v63, -v60, v227, v63
	v_fma_f32 v62, -v61, v228, v62
	v_fma_f32 v63, -v58, v229, v63
	ds_read_b128 v[214:217], v137 offset:42688
	s_waitcnt lgkmcnt(8)
	v_fma_f32 v62, -v59, v230, v62
	v_fma_f32 v63, -v56, v231, v63
	v_fma_f32 v62, -v57, v232, v62
	v_fma_f32 v63, -v54, v233, v63
	ds_read_b128 v[218:221], v137 offset:42704
	s_waitcnt lgkmcnt(8)
	v_fma_f32 v62, -v55, v234, v62
	v_fma_f32 v63, -v52, v235, v63
	v_fma_f32 v62, -v53, v236, v62
	v_fma_f32 v63, -v50, v237, v63
	ds_read_b128 v[222:225], v137 offset:42720
	s_waitcnt lgkmcnt(8)
	v_fma_f32 v62, -v51, v238, v62
	v_fma_f32 v63, -v48, v239, v63
	v_fma_f32 v62, -v49, v240, v62
	v_fma_f32 v63, -v46, v241, v63
	ds_read_b128 v[226:229], v137 offset:42752
	s_waitcnt lgkmcnt(8)
	v_fma_f32 v62, -v47, v248, v62
	v_fma_f32 v63, -v44, v249, v63
	v_fma_f32 v62, -v45, v250, v62
	v_fma_f32 v63, -v42, v251, v63
	ds_read_b128 v[230:233], v137 offset:42768
	s_waitcnt lgkmcnt(8)
	v_fma_f32 v62, -v43, v252, v62
	v_fma_f32 v63, -v40, v253, v63
	v_fma_f32 v62, -v41, v254, v62
	v_fma_f32 v63, -v38, v255, v63
	ds_read_b128 v[234:237], v137 offset:42784
	s_waitcnt lgkmcnt(8)
	v_fma_f32 v62, -v39, v202, v62
	v_fma_f32 v63, -v36, v203, v63
	v_fma_f32 v62, -v37, v204, v62
	v_fma_f32 v63, -v34, v205, v63
	ds_read_b128 v[238:241], v137 offset:42800
	s_waitcnt lgkmcnt(8)
	v_fma_f32 v62, -v35, v206, v62
	v_fma_f32 v63, -v32, v207, v63
	v_fma_f32 v62, -v33, v208, v62
	v_fma_f32 v63, -v30, v209, v63
	ds_read_b128 v[248:251], v137 offset:42816
	s_waitcnt lgkmcnt(8)
	v_fma_f32 v62, -v31, v210, v62
	v_fma_f32 v63, -v28, v211, v63
	v_fma_f32 v62, -v29, v212, v62
	v_fma_f32 v63, -v26, v213, v63
	ds_read_b128 v[252:255], v137 offset:42832
	s_waitcnt lgkmcnt(8)
	v_fma_f32 v62, -v27, v214, v62
	v_fma_f32 v63, -v24, v215, v63
	v_fma_f32 v62, -v25, v216, v62
	v_fma_f32 v63, -v22, v217, v63
	ds_read_b128 v[202:205], v137 offset:42848
	s_waitcnt lgkmcnt(8)
	v_fma_f32 v62, -v23, v218, v62
	v_fma_f32 v63, -v20, v219, v63
	v_fma_f32 v62, -v21, v220, v62
	v_fma_f32 v63, -v18, v221, v63
	ds_read_b128 v[206:209], v137 offset:42864
	s_waitcnt lgkmcnt(8)
	v_fma_f32 v62, -v19, v222, v62
	v_fma_f32 v17, -v16, v223, v63
	v_add_f32_e32 v17, v62, v17
	s_nop 0
	ds_read_b128 v[210:213], v137 offset:42880
	s_waitcnt lgkmcnt(8)
	v_fma_f32 v62, -v81, v226, v86
	v_fma_f32 v63, -v0, v227, 0
	v_fma_f32 v62, -v1, v228, v62
	v_fma_f32 v63, -v2, v229, v63
	ds_read_b128 v[214:217], v137 offset:42896
	s_waitcnt lgkmcnt(8)
	v_fma_f32 v62, -v3, v230, v62
	v_fma_f32 v63, -v4, v231, v63
	v_fma_f32 v62, -v5, v232, v62
	v_fma_f32 v63, -v7, v233, v63
	ds_read_b128 v[218:221], v137 offset:42912
	s_waitcnt lgkmcnt(8)
	v_fma_f32 v62, -v6, v234, v62
	v_fma_f32 v63, -v8, v235, v63
	v_fma_f32 v62, -v9, v236, v62
	v_fma_f32 v63, -v10, v237, v63
	ds_read_b128 v[222:225], v137 offset:42928
	s_waitcnt lgkmcnt(8)
	v_fma_f32 v62, -v11, v238, v62
	v_fma_f32 v63, -v60, v239, v63
	v_fma_f32 v62, -v61, v240, v62
	v_fma_f32 v63, -v58, v241, v63
	ds_read_b128 v[226:229], v137 offset:42944
	s_waitcnt lgkmcnt(8)
	v_fma_f32 v62, -v59, v248, v62
	v_fma_f32 v63, -v56, v249, v63
	v_fma_f32 v62, -v57, v250, v62
	v_fma_f32 v63, -v54, v251, v63
	ds_read_b128 v[230:233], v137 offset:42960
	s_waitcnt lgkmcnt(8)
	v_fma_f32 v62, -v55, v252, v62
	v_fma_f32 v63, -v52, v253, v63
	v_fma_f32 v62, -v53, v254, v62
	v_fma_f32 v63, -v50, v255, v63
	ds_read_b128 v[234:237], v137 offset:42976
	s_waitcnt lgkmcnt(8)
	v_fma_f32 v62, -v51, v202, v62
	v_fma_f32 v63, -v48, v203, v63
	v_fma_f32 v62, -v49, v204, v62
	v_fma_f32 v63, -v46, v205, v63
	ds_read_b128 v[238:241], v137 offset:43008
	s_waitcnt lgkmcnt(8)
	v_fma_f32 v62, -v47, v206, v62
	v_fma_f32 v63, -v44, v207, v63
	v_fma_f32 v62, -v45, v208, v62
	v_fma_f32 v63, -v42, v209, v63
	ds_read_b128 v[248:251], v137 offset:43024
	s_waitcnt lgkmcnt(8)
	v_fma_f32 v62, -v43, v210, v62
	v_fma_f32 v63, -v40, v211, v63
	v_fma_f32 v62, -v41, v212, v62
	v_fma_f32 v63, -v38, v213, v63
	ds_read_b128 v[252:255], v137 offset:43040
	s_waitcnt lgkmcnt(8)
	v_fma_f32 v62, -v39, v214, v62
	v_fma_f32 v63, -v36, v215, v63
	v_fma_f32 v62, -v37, v216, v62
	v_fma_f32 v63, -v34, v217, v63
	ds_read_b128 v[202:205], v137 offset:43056
	s_waitcnt lgkmcnt(8)
	v_fma_f32 v62, -v35, v218, v62
	v_fma_f32 v63, -v32, v219, v63
	v_fma_f32 v62, -v33, v220, v62
	v_fma_f32 v63, -v30, v221, v63
	ds_read_b128 v[206:209], v137 offset:43072
	s_waitcnt lgkmcnt(8)
	v_fma_f32 v62, -v31, v222, v62
	v_fma_f32 v63, -v28, v223, v63
	v_fma_f32 v62, -v29, v224, v62
	v_fma_f32 v63, -v26, v225, v63
	ds_read_b128 v[210:213], v137 offset:43088
	s_waitcnt lgkmcnt(8)
	v_fma_f32 v62, -v27, v226, v62
	v_fma_f32 v63, -v24, v227, v63
	v_fma_f32 v62, -v25, v228, v62
	v_fma_f32 v63, -v22, v229, v63
	ds_read_b128 v[214:217], v137 offset:43104
	s_waitcnt lgkmcnt(8)
	v_fma_f32 v62, -v23, v230, v62
	v_fma_f32 v63, -v20, v231, v63
	v_fma_f32 v62, -v21, v232, v62
	v_fma_f32 v63, -v18, v233, v63
	ds_read_b128 v[218:221], v137 offset:43120
	s_waitcnt lgkmcnt(8)
	v_fma_f32 v62, -v19, v234, v62
	v_fma_f32 v63, -v16, v235, v63
	v_fma_f32 v14, -v17, v236, v62
	v_add_f32_e32 v14, v63, v14
	s_nop 0
	ds_read_b128 v[222:225], v137 offset:43136
	s_waitcnt lgkmcnt(8)
	v_fma_f32 v62, -v81, v238, v85
	v_fma_f32 v63, -v0, v239, 0
	v_fma_f32 v62, -v1, v240, v62
	v_fma_f32 v63, -v2, v241, v63
	ds_read_b128 v[226:229], v137 offset:43152
	s_waitcnt lgkmcnt(8)
	v_fma_f32 v62, -v3, v248, v62
	v_fma_f32 v63, -v4, v249, v63
	v_fma_f32 v62, -v5, v250, v62
	v_fma_f32 v63, -v7, v251, v63
	ds_read_b128 v[230:233], v137 offset:43168
	s_waitcnt lgkmcnt(8)
	v_fma_f32 v62, -v6, v252, v62
	v_fma_f32 v63, -v8, v253, v63
	v_fma_f32 v62, -v9, v254, v62
	v_fma_f32 v63, -v10, v255, v63
	ds_read_b128 v[234:237], v137 offset:43184
	s_waitcnt lgkmcnt(8)
	v_fma_f32 v62, -v11, v202, v62
	v_fma_f32 v63, -v60, v203, v63
	v_fma_f32 v62, -v61, v204, v62
	v_fma_f32 v63, -v58, v205, v63
	ds_read_b128 v[238:241], v137 offset:43200
	s_waitcnt lgkmcnt(8)
	v_fma_f32 v62, -v59, v206, v62
	v_fma_f32 v63, -v56, v207, v63
	v_fma_f32 v62, -v57, v208, v62
	v_fma_f32 v63, -v54, v209, v63
	ds_read_b128 v[248:251], v137 offset:43216
	s_waitcnt lgkmcnt(8)
	v_fma_f32 v62, -v55, v210, v62
	v_fma_f32 v63, -v52, v211, v63
	v_fma_f32 v62, -v53, v212, v62
	v_fma_f32 v63, -v50, v213, v63
	ds_read_b128 v[252:255], v137 offset:43232
	s_waitcnt lgkmcnt(8)
	v_fma_f32 v62, -v51, v214, v62
	v_fma_f32 v63, -v48, v215, v63
	v_fma_f32 v62, -v49, v216, v62
	v_fma_f32 v63, -v46, v217, v63
	ds_read_b128 v[202:205], v137 offset:43264
	s_waitcnt lgkmcnt(8)
	v_fma_f32 v62, -v47, v218, v62
	v_fma_f32 v63, -v44, v219, v63
	v_fma_f32 v62, -v45, v220, v62
	v_fma_f32 v63, -v42, v221, v63
	ds_read_b128 v[206:209], v137 offset:43280
	s_waitcnt lgkmcnt(8)
	v_fma_f32 v62, -v43, v222, v62
	v_fma_f32 v63, -v40, v223, v63
	v_fma_f32 v62, -v41, v224, v62
	v_fma_f32 v63, -v38, v225, v63
	ds_read_b128 v[210:213], v137 offset:43296
	s_waitcnt lgkmcnt(8)
	v_fma_f32 v62, -v39, v226, v62
	v_fma_f32 v63, -v36, v227, v63
	v_fma_f32 v62, -v37, v228, v62
	v_fma_f32 v63, -v34, v229, v63
	ds_read_b128 v[214:217], v137 offset:43312
	s_waitcnt lgkmcnt(8)
	v_fma_f32 v62, -v35, v230, v62
	v_fma_f32 v63, -v32, v231, v63
	v_fma_f32 v62, -v33, v232, v62
	v_fma_f32 v63, -v30, v233, v63
	ds_read_b128 v[218:221], v137 offset:43328
	s_waitcnt lgkmcnt(8)
	v_fma_f32 v62, -v31, v234, v62
	v_fma_f32 v63, -v28, v235, v63
	v_fma_f32 v62, -v29, v236, v62
	v_fma_f32 v63, -v26, v237, v63
	ds_read_b128 v[222:225], v137 offset:43344
	s_waitcnt lgkmcnt(8)
	v_fma_f32 v62, -v27, v238, v62
	v_fma_f32 v63, -v24, v239, v63
	v_fma_f32 v62, -v25, v240, v62
	v_fma_f32 v63, -v22, v241, v63
	ds_read_b128 v[226:229], v137 offset:43360
	s_waitcnt lgkmcnt(8)
	v_fma_f32 v62, -v23, v248, v62
	v_fma_f32 v63, -v20, v249, v63
	v_fma_f32 v62, -v21, v250, v62
	v_fma_f32 v63, -v18, v251, v63
	ds_read_b128 v[230:233], v137 offset:43376
	s_waitcnt lgkmcnt(8)
	v_fma_f32 v62, -v19, v252, v62
	v_fma_f32 v63, -v16, v253, v63
	v_fma_f32 v62, -v17, v254, v62
	v_fma_f32 v15, -v14, v255, v63
	v_add_f32_e32 v15, v62, v15
	s_nop 0
	ds_read_b128 v[234:237], v137 offset:43392
	s_waitcnt lgkmcnt(8)
	v_fma_f32 v62, -v81, v202, v84
	v_fma_f32 v63, -v0, v203, 0
	v_fma_f32 v62, -v1, v204, v62
	v_fma_f32 v63, -v2, v205, v63
	ds_read_b128 v[238:241], v137 offset:43408
	s_waitcnt lgkmcnt(8)
	v_fma_f32 v62, -v3, v206, v62
	v_fma_f32 v63, -v4, v207, v63
	v_fma_f32 v62, -v5, v208, v62
	v_fma_f32 v63, -v7, v209, v63
	ds_read_b128 v[248:251], v137 offset:43424
	s_waitcnt lgkmcnt(8)
	v_fma_f32 v62, -v6, v210, v62
	v_fma_f32 v63, -v8, v211, v63
	v_fma_f32 v62, -v9, v212, v62
	v_fma_f32 v63, -v10, v213, v63
	ds_read_b128 v[252:255], v137 offset:43440
	s_waitcnt lgkmcnt(8)
	v_fma_f32 v62, -v11, v214, v62
	v_fma_f32 v63, -v60, v215, v63
	v_fma_f32 v62, -v61, v216, v62
	v_fma_f32 v63, -v58, v217, v63
	ds_read_b128 v[202:205], v137 offset:43456
	s_waitcnt lgkmcnt(8)
	v_fma_f32 v62, -v59, v218, v62
	v_fma_f32 v63, -v56, v219, v63
	v_fma_f32 v62, -v57, v220, v62
	v_fma_f32 v63, -v54, v221, v63
	ds_read_b128 v[206:209], v137 offset:43472
	s_waitcnt lgkmcnt(8)
	v_fma_f32 v62, -v55, v222, v62
	v_fma_f32 v63, -v52, v223, v63
	v_fma_f32 v62, -v53, v224, v62
	v_fma_f32 v63, -v50, v225, v63
	ds_read_b128 v[210:213], v137 offset:43488
	s_waitcnt lgkmcnt(8)
	v_fma_f32 v62, -v51, v226, v62
	v_fma_f32 v63, -v48, v227, v63
	v_fma_f32 v62, -v49, v228, v62
	v_fma_f32 v63, -v46, v229, v63
	ds_read_b128 v[214:217], v137 offset:43504
	s_waitcnt lgkmcnt(8)
	v_fma_f32 v62, -v47, v230, v62
	v_fma_f32 v63, -v44, v231, v63
	v_fma_f32 v62, -v45, v232, v62
	v_fma_f32 v63, -v42, v233, v63
	ds_read_b128 v[218:221], v137 offset:43520
	s_waitcnt lgkmcnt(8)
	v_fma_f32 v62, -v43, v234, v62
	v_fma_f32 v63, -v40, v235, v63
	v_fma_f32 v62, -v41, v236, v62
	v_fma_f32 v63, -v38, v237, v63
	ds_read_b128 v[222:225], v137 offset:43536
	s_waitcnt lgkmcnt(8)
	v_fma_f32 v62, -v39, v238, v62
	v_fma_f32 v63, -v36, v239, v63
	v_fma_f32 v62, -v37, v240, v62
	v_fma_f32 v63, -v34, v241, v63
	ds_read_b128 v[226:229], v137 offset:43552
	s_waitcnt lgkmcnt(8)
	v_fma_f32 v62, -v35, v248, v62
	v_fma_f32 v63, -v32, v249, v63
	v_fma_f32 v62, -v33, v250, v62
	v_fma_f32 v63, -v30, v251, v63
	ds_read_b128 v[230:233], v137 offset:43568
	s_waitcnt lgkmcnt(8)
	v_fma_f32 v62, -v31, v252, v62
	v_fma_f32 v63, -v28, v253, v63
	v_fma_f32 v62, -v29, v254, v62
	v_fma_f32 v63, -v26, v255, v63
	ds_read_b128 v[234:237], v137 offset:43584
	s_waitcnt lgkmcnt(8)
	v_fma_f32 v62, -v27, v202, v62
	v_fma_f32 v63, -v24, v203, v63
	v_fma_f32 v62, -v25, v204, v62
	v_fma_f32 v63, -v22, v205, v63
	ds_read_b128 v[238:241], v137 offset:43600
	s_waitcnt lgkmcnt(8)
	v_fma_f32 v62, -v23, v206, v62
	v_fma_f32 v63, -v20, v207, v63
	v_fma_f32 v62, -v21, v208, v62
	v_fma_f32 v63, -v18, v209, v63
	ds_read_b128 v[248:251], v137 offset:43616
	s_waitcnt lgkmcnt(8)
	v_fma_f32 v62, -v19, v210, v62
	v_fma_f32 v63, -v16, v211, v63
	v_fma_f32 v62, -v17, v212, v62
	v_fma_f32 v63, -v14, v213, v63
	ds_read_b128 v[252:255], v137 offset:43632
	s_waitcnt lgkmcnt(8)
	v_fma_f32 v12, -v15, v214, v62
	v_add_f32_e32 v12, v63, v12
	s_nop 0
	ds_read_b128 v[202:205], v137 offset:43648
	s_waitcnt lgkmcnt(8)
	v_fma_f32 v62, -v81, v218, v83
	v_fma_f32 v63, -v0, v219, 0
	v_fma_f32 v62, -v1, v220, v62
	v_fma_f32 v63, -v2, v221, v63
	ds_read_b128 v[206:209], v137 offset:43664
	s_waitcnt lgkmcnt(8)
	v_fma_f32 v62, -v3, v222, v62
	v_fma_f32 v63, -v4, v223, v63
	v_fma_f32 v62, -v5, v224, v62
	v_fma_f32 v63, -v7, v225, v63
	ds_read_b128 v[210:213], v137 offset:43680
	s_waitcnt lgkmcnt(8)
	v_fma_f32 v62, -v6, v226, v62
	v_fma_f32 v63, -v8, v227, v63
	v_fma_f32 v62, -v9, v228, v62
	v_fma_f32 v63, -v10, v229, v63
	ds_read_b128 v[214:217], v137 offset:43696
	s_waitcnt lgkmcnt(8)
	v_fma_f32 v62, -v11, v230, v62
	v_fma_f32 v63, -v60, v231, v63
	v_fma_f32 v62, -v61, v232, v62
	v_fma_f32 v63, -v58, v233, v63
	ds_read_b128 v[218:221], v137 offset:43712
	s_waitcnt lgkmcnt(8)
	v_fma_f32 v62, -v59, v234, v62
	v_fma_f32 v63, -v56, v235, v63
	v_fma_f32 v62, -v57, v236, v62
	v_fma_f32 v63, -v54, v237, v63
	ds_read_b128 v[222:225], v137 offset:43728
	s_waitcnt lgkmcnt(8)
	v_fma_f32 v62, -v55, v238, v62
	v_fma_f32 v63, -v52, v239, v63
	v_fma_f32 v62, -v53, v240, v62
	v_fma_f32 v63, -v50, v241, v63
	ds_read_b128 v[226:229], v137 offset:43744
	s_waitcnt lgkmcnt(8)
	v_fma_f32 v62, -v51, v248, v62
	v_fma_f32 v63, -v48, v249, v63
	v_fma_f32 v62, -v49, v250, v62
	v_fma_f32 v63, -v46, v251, v63
	ds_read_b128 v[230:233], v137 offset:43760
	s_waitcnt lgkmcnt(8)
	v_fma_f32 v62, -v47, v252, v62
	v_fma_f32 v63, -v44, v253, v63
	v_fma_f32 v62, -v45, v254, v62
	v_fma_f32 v63, -v42, v255, v63
	ds_read_b128 v[234:237], v137 offset:43776
	s_waitcnt lgkmcnt(8)
	v_fma_f32 v62, -v43, v202, v62
	v_fma_f32 v63, -v40, v203, v63
	v_fma_f32 v62, -v41, v204, v62
	v_fma_f32 v63, -v38, v205, v63
	ds_read_b128 v[238:241], v137 offset:43792
	s_waitcnt lgkmcnt(8)
	v_fma_f32 v62, -v39, v206, v62
	v_fma_f32 v63, -v36, v207, v63
	v_fma_f32 v62, -v37, v208, v62
	v_fma_f32 v63, -v34, v209, v63
	ds_read_b128 v[248:251], v137 offset:43808
	s_waitcnt lgkmcnt(8)
	v_fma_f32 v62, -v35, v210, v62
	v_fma_f32 v63, -v32, v211, v63
	v_fma_f32 v62, -v33, v212, v62
	v_fma_f32 v63, -v30, v213, v63
	ds_read_b128 v[252:255], v137 offset:43824
	s_waitcnt lgkmcnt(8)
	v_fma_f32 v62, -v31, v214, v62
	v_fma_f32 v63, -v28, v215, v63
	v_fma_f32 v62, -v29, v216, v62
	v_fma_f32 v63, -v26, v217, v63
	ds_read_b128 v[202:205], v137 offset:43840
	s_waitcnt lgkmcnt(8)
	v_fma_f32 v62, -v27, v218, v62
	v_fma_f32 v63, -v24, v219, v63
	v_fma_f32 v62, -v25, v220, v62
	v_fma_f32 v63, -v22, v221, v63
	ds_read_b128 v[206:209], v137 offset:43856
	s_waitcnt lgkmcnt(8)
	v_fma_f32 v62, -v23, v222, v62
	v_fma_f32 v63, -v20, v223, v63
	v_fma_f32 v62, -v21, v224, v62
	v_fma_f32 v63, -v18, v225, v63
	ds_read_b128 v[210:213], v137 offset:43872
	s_waitcnt lgkmcnt(8)
	v_fma_f32 v62, -v19, v226, v62
	v_fma_f32 v63, -v16, v227, v63
	v_fma_f32 v62, -v17, v228, v62
	v_fma_f32 v63, -v14, v229, v63
	ds_read_b128 v[214:217], v137 offset:43888
	s_waitcnt lgkmcnt(8)
	v_fma_f32 v62, -v15, v230, v62
	v_fma_f32 v13, -v12, v231, v63
	v_add_f32_e32 v13, v62, v13
	s_nop 0
	ds_read_b128 v[218:221], v137 offset:43904
	s_waitcnt lgkmcnt(8)
	v_fma_f32 v62, -v81, v234, v82
	v_fma_f32 v63, -v0, v235, 0
	v_fma_f32 v62, -v1, v236, v62
	v_fma_f32 v63, -v2, v237, v63
	ds_read_b128 v[222:225], v137 offset:43920
	s_waitcnt lgkmcnt(8)
	v_fma_f32 v62, -v3, v238, v62
	v_fma_f32 v63, -v4, v239, v63
	v_fma_f32 v62, -v5, v240, v62
	v_fma_f32 v63, -v7, v241, v63
	ds_read_b128 v[226:229], v137 offset:43936
	s_waitcnt lgkmcnt(8)
	v_fma_f32 v62, -v6, v248, v62
	v_fma_f32 v63, -v8, v249, v63
	v_fma_f32 v62, -v9, v250, v62
	v_fma_f32 v63, -v10, v251, v63
	ds_read_b128 v[230:233], v137 offset:43952
	s_waitcnt lgkmcnt(8)
	v_fma_f32 v62, -v11, v252, v62
	v_fma_f32 v63, -v60, v253, v63
	v_fma_f32 v62, -v61, v254, v62
	v_fma_f32 v63, -v58, v255, v63
	ds_read_b128 v[234:237], v137 offset:43968
	s_waitcnt lgkmcnt(8)
	v_fma_f32 v62, -v59, v202, v62
	v_fma_f32 v63, -v56, v203, v63
	v_fma_f32 v62, -v57, v204, v62
	v_fma_f32 v63, -v54, v205, v63
	ds_read_b128 v[238:241], v137 offset:43984
	s_waitcnt lgkmcnt(8)
	v_fma_f32 v62, -v55, v206, v62
	v_fma_f32 v63, -v52, v207, v63
	v_fma_f32 v62, -v53, v208, v62
	v_fma_f32 v63, -v50, v209, v63
	ds_read_b128 v[248:251], v137 offset:44000
	s_waitcnt lgkmcnt(8)
	v_fma_f32 v62, -v51, v210, v62
	v_fma_f32 v63, -v48, v211, v63
	v_fma_f32 v62, -v49, v212, v62
	v_fma_f32 v63, -v46, v213, v63
	ds_read_b128 v[252:255], v137 offset:44016
	s_waitcnt lgkmcnt(8)
	v_fma_f32 v62, -v47, v214, v62
	v_fma_f32 v63, -v44, v215, v63
	v_fma_f32 v62, -v45, v216, v62
	v_fma_f32 v63, -v42, v217, v63
	s_waitcnt lgkmcnt(7)
	v_fma_f32 v62, -v43, v218, v62
	v_fma_f32 v63, -v40, v219, v63
	v_fma_f32 v62, -v41, v220, v62
	v_fma_f32 v63, -v38, v221, v63
	s_waitcnt lgkmcnt(6)
	v_fma_f32 v62, -v39, v222, v62
	v_fma_f32 v63, -v36, v223, v63
	v_fma_f32 v62, -v37, v224, v62
	v_fma_f32 v63, -v34, v225, v63
	s_waitcnt lgkmcnt(5)
	v_fma_f32 v62, -v35, v226, v62
	v_fma_f32 v63, -v32, v227, v63
	v_fma_f32 v62, -v33, v228, v62
	v_fma_f32 v63, -v30, v229, v63
	s_waitcnt lgkmcnt(4)
	v_fma_f32 v62, -v31, v230, v62
	v_fma_f32 v63, -v28, v231, v63
	v_fma_f32 v62, -v29, v232, v62
	v_fma_f32 v63, -v26, v233, v63
	s_waitcnt lgkmcnt(3)
	v_fma_f32 v62, -v27, v234, v62
	v_fma_f32 v63, -v24, v235, v63
	v_fma_f32 v62, -v25, v236, v62
	v_fma_f32 v63, -v22, v237, v63
	s_waitcnt lgkmcnt(2)
	v_fma_f32 v62, -v23, v238, v62
	v_fma_f32 v63, -v20, v239, v63
	v_fma_f32 v62, -v21, v240, v62
	v_fma_f32 v63, -v18, v241, v63
	s_waitcnt lgkmcnt(1)
	v_fma_f32 v62, -v19, v248, v62
	v_fma_f32 v63, -v16, v249, v63
	v_fma_f32 v62, -v17, v250, v62
	v_fma_f32 v63, -v14, v251, v63
	s_waitcnt lgkmcnt(0)
	v_fma_f32 v62, -v15, v252, v62
	v_fma_f32 v63, -v12, v253, v63
	v_fma_f32 v62, -v13, v254, v62
	v_add_f32_e32 v62, v63, v62
	s_and_saveexec_b64 s[2:3], s[38:39]
	s_xor_b64 s[2:3], exec, s[2:3]
	s_cbranch_execz .LBB0_657
	v_readlane_b32 s44, v246, 41
	s_lshl_b64 s[4:5], s[42:43], 1
	v_readlane_b32 s52, v246, 49
	v_readlane_b32 s53, v246, 50
	s_add_u32 s4, s52, s4
	v_cvt_pk_bf16_f32 v0, v79, v0
	v_cvt_pk_bf16_f32 v1, v1, v2
	v_cvt_pk_bf16_f32 v2, v3, v4
	v_cvt_pk_bf16_f32 v3, v5, v7
	s_addc_u32 s5, s53, s5
	v_lshlrev_b32_e32 v4, 7, v75
	global_store_dwordx4 v4, v[0:3], s[4:5]
	v_readlane_b32 s45, v246, 42
	v_readlane_b32 s46, v246, 43
	v_cvt_pk_bf16_f32 v0, v6, v8
	v_cvt_pk_bf16_f32 v1, v9, v10
	v_cvt_pk_bf16_f32 v2, v11, v60
	v_cvt_pk_bf16_f32 v3, v61, v58
	global_store_dwordx4 v4, v[0:3], s[4:5] offset:16
	v_readlane_b32 s47, v246, 44
	v_readlane_b32 s48, v246, 45
	v_cvt_pk_bf16_f32 v0, v59, v56
	v_cvt_pk_bf16_f32 v1, v57, v54
	v_cvt_pk_bf16_f32 v2, v55, v52
	v_cvt_pk_bf16_f32 v3, v53, v50
	global_store_dwordx4 v4, v[0:3], s[4:5] offset:32
	v_readlane_b32 s49, v246, 46
	v_readlane_b32 s50, v246, 47
	v_cvt_pk_bf16_f32 v0, v51, v48
	v_cvt_pk_bf16_f32 v1, v49, v46
	v_cvt_pk_bf16_f32 v2, v47, v44
	v_cvt_pk_bf16_f32 v3, v45, v42
	global_store_dwordx4 v4, v[0:3], s[4:5] offset:48
	v_readlane_b32 s51, v246, 48
	v_readlane_b32 s54, v246, 51
	v_cvt_pk_bf16_f32 v0, v43, v40
	v_cvt_pk_bf16_f32 v1, v41, v38
	v_cvt_pk_bf16_f32 v2, v39, v36
	v_cvt_pk_bf16_f32 v3, v37, v34
	global_store_dwordx4 v4, v[0:3], s[4:5] offset:64
	v_readlane_b32 s55, v246, 52
	v_readlane_b32 s56, v246, 53
	v_cvt_pk_bf16_f32 v0, v35, v32
	v_cvt_pk_bf16_f32 v1, v33, v30
	v_cvt_pk_bf16_f32 v2, v31, v28
	v_cvt_pk_bf16_f32 v3, v29, v26
	global_store_dwordx4 v4, v[0:3], s[4:5] offset:80
	v_readlane_b32 s57, v246, 54
	v_readlane_b32 s58, v246, 55
	v_cvt_pk_bf16_f32 v0, v27, v24
	v_cvt_pk_bf16_f32 v1, v25, v22
	v_cvt_pk_bf16_f32 v2, v23, v20
	v_cvt_pk_bf16_f32 v3, v21, v18
	global_store_dwordx4 v4, v[0:3], s[4:5] offset:96
	v_readlane_b32 s59, v246, 56
	s_nop 0
	v_cvt_pk_bf16_f32 v0, v19, v16
	v_cvt_pk_bf16_f32 v1, v17, v14
	v_cvt_pk_bf16_f32 v2, v15, v12
	v_cvt_pk_bf16_f32 v3, v13, v62
	global_store_dwordx4 v4, v[0:3], s[4:5] offset:112
